# diff attention: q stored pre-multiplied by scale*log2e (before the bf16 rounding), running reference max folded into the QK MFMA accumulator init, exp2 in place, bf16 pack of P in the PV shadow, rare
# speedup vs baseline: 1.0344x; 1.0079x over previous
; #define LAS __attribute__((address_space(3)))
; DI void convert_layer(const Frame& F, int l) { for (int u = F.wg; u < CM_NPULL; u += F.nwg) convert_pull(F, l, u); }
; #define SEAM() do { if (a.fused) xcd_barrier(bar); } while (0)
; __global__ void __launch_bounds__(NTHREADS, 2) fwd(Args a) {
;     ...
;     LAS unsigned char* lds0 = (LAS unsigned char*)lds_raw;
;     const int wave0 = __builtin_amdgcn_readfirstlane(threadIdx.x >> 6);
;     volatile LAS unsigned* xbw = (volatile LAS unsigned*)(lds0 + LDS_BYTES - 16);
;     if (threadIdx.x == 0) { xbw[0] = 0u; xbw[1] = 0u; xbw[2] = 0u; xbw[3] = 0u; }
;     __syncthreads();
;     XcdBarrier bar; bar.bar = (unsigned*)(a.ws + WS_CTL); bar.x = 0; bar.st = xbw;
;     if (a.fused) bar = xcd_barrier_post((unsigned*)(a.ws + WS_CTL), xbw);
;     ...
;     if (PIN(0)) { { FR(); convert_layer(F, 0); pro_gemv(F); } SEAM(); }
;     if (PIN(1)) { { FR(); pro_modreduce(F); } SEAM(); }
;     if (PIN(2)) { { FR(); pro_h0(F); } SEAM(); }
;     for (int l = a.l_lo; l < a.l_hi; ++l) {
.LBB0_257:
	s_load_dwordx4 s[8:11], s[0:1], 0xdc
	s_load_dwordx8 s[12:19], s[0:1], 0xb0
	v_mov_b32_e32 v1, 0
	v_mov_b32_e32 v232, 1
	v_mov_b32_e32 v233, 0x358637bd
	s_waitcnt lgkmcnt(0)
	s_cmp_lt_i32 s9, 1
	s_cselect_b64 s[2:3], -1, 0
	s_cmp_gt_i32 s10, 0
	s_cselect_b64 s[4:5], -1, 0
	s_and_b64 s[2:3], s[2:3], s[4:5]
	v_writelane_b32 v253, s2, 8
	s_load_dwordx2 s[4:5], s[0:1], 0xc8
	v_mov_b32_e32 v234, 0xc000
	v_writelane_b32 v253, s3, 9
	s_add_u32 s2, s0, 0xf0
	s_addc_u32 s3, s1, 0
	v_writelane_b32 v253, s2, 10
	s_cmp_lg_u32 s11, 0
	v_mov_b32_e32 v235, 0x3727c5ac
	v_writelane_b32 v253, s3, 11
	s_cselect_b64 s[2:3], -1, 0
	v_writelane_b32 v253, s2, 12
	v_mov_b32_e32 v236, 0x260
	v_mov_b32_e32 v237, 0x2e00
	v_writelane_b32 v253, s3, 13
	s_waitcnt lgkmcnt(0)
	s_add_u32 s2, s4, 0x200
	s_addc_u32 s3, s5, 0
	v_writelane_b32 v253, s2, 14
	v_mov_b32_e32 v238, 0x300
	v_mov_b32_e32 v239, 0xf149f2ca
	v_writelane_b32 v253, s3, 15
	s_add_u32 s2, s4, 0x1000
	s_addc_u32 s3, s5, 0
	v_writelane_b32 v253, s2, 16
	v_mov_b32_e32 v240, 0x318000
	v_mov_b32_e32 v241, 0x4200
	v_writelane_b32 v253, s3, 17
	s_add_u32 s2, s4, 0x1100
	s_addc_u32 s3, s5, 0
	v_writelane_b32 v253, s2, 18
	v_mov_b32_e32 v242, 0x7f800000
	v_mov_b64_e32 v[212:213], 0x3d0901
	v_writelane_b32 v253, s3, 19
	s_add_u32 s2, s4, 0x1200
	s_addc_u32 s3, s5, 0
	v_writelane_b32 v253, s2, 20
	v_mov_b32_e32 v243, 0x7fc00000
	s_movk_i32 s27, 0x180
	v_writelane_b32 v253, s3, 21
	s_add_u32 s2, s4, 0x1300
	s_addc_u32 s3, s5, 0
	v_writelane_b32 v253, s2, 22
	s_cmp_eq_u32 s33, 15
	s_mov_b32 s31, 0x2aaaaaab
	v_writelane_b32 v253, s3, 23
	s_cselect_b64 s[2:3], -1, 0
	v_writelane_b32 v253, s2, 24
	s_cmp_eq_u32 s33, 14
	s_movk_i32 s35, 0xff40
	v_writelane_b32 v253, s3, 25
	s_cselect_b64 s[2:3], -1, 0
	v_writelane_b32 v253, s2, 26
	s_cmp_eq_u32 s33, 13
	s_mov_b32 s96, 0x42ddb3d8
	v_writelane_b32 v253, s3, 27
	s_cselect_b64 s[2:3], -1, 0
	v_writelane_b32 v253, s2, 28
	s_cmp_eq_u32 s33, 12
	s_mov_b32 s97, 0x42fc0000
	v_writelane_b32 v253, s3, 29
	s_cselect_b64 s[2:3], -1, 0
	v_writelane_b32 v253, s2, 30
	s_cmp_eq_u32 s33, 11
	s_mov_b32 s79, 0x42fc6000
	v_writelane_b32 v253, s3, 31
	s_cselect_b64 s[2:3], -1, 0
	v_writelane_b32 v253, s2, 32
	s_cmp_eq_u32 s33, 10
	s_mov_b32 s26, 0x42800000
	v_writelane_b32 v253, s3, 33
	s_cselect_b64 s[2:3], -1, 0
	v_writelane_b32 v253, s2, 34
	s_cmp_eq_u32 s33, 9
	s_mov_b64 s[36:37], 0x80
	v_writelane_b32 v253, s3, 35
	s_cselect_b64 s[2:3], -1, 0
	v_writelane_b32 v253, s2, 36
	s_cmp_eq_u32 s33, 8
	s_mov_b32 s30, 0x3dd53b94
	v_writelane_b32 v253, s3, 37
	s_cselect_b64 s[2:3], -1, 0
	v_writelane_b32 v253, s2, 38
	s_cmp_eq_u32 s33, 7
	s_mov_b64 s[52:53], 0xc000
	v_writelane_b32 v253, s3, 39
	s_cselect_b64 s[2:3], -1, 0
	v_writelane_b32 v253, s2, 40
	s_cmp_eq_u32 s33, 6
	s_mov_b64 s[54:55], 0x8000
	v_writelane_b32 v253, s3, 41
	s_cselect_b64 s[2:3], -1, 0
	v_writelane_b32 v253, s2, 42
	s_cmp_eq_u32 s33, 5
	s_mov_b32 s34, 1.0
	v_writelane_b32 v253, s3, 43
	s_cselect_b64 s[2:3], -1, 0
	v_writelane_b32 v253, s2, 44
	s_cmp_eq_u32 s33, 4
	s_nop 0
	v_writelane_b32 v253, s3, 45
	s_cselect_b64 s[2:3], -1, 0
	v_writelane_b32 v253, s2, 46
	s_cmp_eq_u32 s33, 3
	s_nop 0
	v_writelane_b32 v253, s3, 47
	s_cselect_b64 s[2:3], -1, 0
	v_writelane_b32 v253, s2, 48
	s_cmp_eq_u32 s33, 2
	s_nop 0
	v_writelane_b32 v253, s3, 49
	s_cselect_b64 s[2:3], -1, 0
	v_writelane_b32 v253, s2, 50
	s_cmp_eq_u32 s33, 1
	s_nop 0
	v_writelane_b32 v253, s3, 51
	s_cselect_b64 s[2:3], -1, 0
	v_writelane_b32 v253, s2, 52
	s_cmp_eq_u32 s33, 0
	s_nop 0
	v_writelane_b32 v253, s3, 53
	s_cselect_b64 s[2:3], -1, 0
	v_writelane_b32 v253, s2, 54
	s_nop 1
	v_writelane_b32 v253, s3, 55
	s_lshl_b32 s2, s33, 8
	s_add_u32 s2, s4, s2
	s_addc_u32 s3, s5, 0
	s_add_u32 s6, s2, 0x1400
	s_addc_u32 s7, s3, 0
	v_writelane_b32 v253, s6, 56
	s_add_u32 s2, s2, 0x2400
	s_addc_u32 s3, s3, 0
	v_writelane_b32 v253, s7, 57
	v_writelane_b32 v253, s2, 58
	s_movk_i32 s33, 0x2100
	s_nop 0
	v_writelane_b32 v253, s3, 59
	s_add_u32 s2, s4, 0x3400
	s_addc_u32 s3, s5, 0
	v_writelane_b32 v253, s2, 60
	s_nop 1
	v_writelane_b32 v253, s3, 61
	s_add_u32 s2, s4, 0x3500
	s_addc_u32 s3, s5, 0
	v_writelane_b32 v253, s2, 62
	s_cmp_lt_i32 s9, 2
	s_nop 0
	v_writelane_b32 v253, s3, 63
	s_cselect_b64 s[2:3], -1, 0
	s_cmp_gt_i32 s10, 1
	s_cselect_b64 s[4:5], -1, 0
	s_and_b64 s[2:3], s[2:3], s[4:5]
	v_writelane_b32 v254, s2, 0
	s_cmp_lt_i32 s9, 3
	s_nop 0
	v_writelane_b32 v254, s3, 1
	s_cselect_b64 s[2:3], -1, 0
	s_cmp_gt_i32 s10, 2
	s_cselect_b64 s[4:5], -1, 0
	s_and_b64 s[2:3], s[2:3], s[4:5]
	v_writelane_b32 v254, s2, 2
	s_cmp_lt_i32 s9, 5
	s_nop 0
	v_writelane_b32 v254, s3, 3
	s_cselect_b64 s[2:3], -1, 0
	s_cmp_gt_i32 s10, 4
	s_cselect_b64 s[4:5], -1, 0
	s_and_b64 s[2:3], s[2:3], s[4:5]
	v_writelane_b32 v254, s2, 4
	s_nop 1
	v_writelane_b32 v254, s3, 5
	s_add_u32 s2, s18, 0x4000
	v_writelane_b32 v254, s2, 6
	v_writelane_b32 v254, s12, 7
	s_addc_u32 s2, s19, 0
	s_cmp_lt_i32 s9, 9
	v_writelane_b32 v254, s13, 8
	v_writelane_b32 v254, s14, 9
	v_writelane_b32 v254, s15, 10
	v_writelane_b32 v254, s16, 11
	v_writelane_b32 v254, s17, 12
	v_writelane_b32 v254, s18, 13
	v_writelane_b32 v254, s19, 14
	v_writelane_b32 v254, s2, 15
	s_cselect_b64 s[2:3], -1, 0
	s_cmp_gt_i32 s10, 8
	s_cselect_b64 s[4:5], -1, 0
	s_and_b64 s[2:3], s[2:3], s[4:5]
	v_writelane_b32 v254, s2, 16
	s_cmp_lt_i32 s9, 10
	s_nop 0
	v_writelane_b32 v254, s3, 17
	s_cselect_b64 s[2:3], -1, 0
	s_cmp_gt_i32 s10, 9
	s_cselect_b64 s[4:5], -1, 0
	s_and_b64 s[2:3], s[2:3], s[4:5]
	v_writelane_b32 v254, s2, 18
	s_cmp_lt_i32 s9, 11
	s_nop 0
	v_writelane_b32 v254, s3, 19
	s_cselect_b64 s[2:3], -1, 0
	s_cmp_gt_i32 s10, 10
	s_cselect_b64 s[4:5], -1, 0
	s_and_b64 s[2:3], s[2:3], s[4:5]
	v_writelane_b32 v254, s2, 20
	s_cmp_lt_i32 s9, 12
	s_nop 0
	v_writelane_b32 v254, s3, 21
	s_cselect_b64 s[2:3], -1, 0
	s_cmp_gt_i32 s10, 11
	s_cselect_b64 s[4:5], -1, 0
	s_and_b64 s[2:3], s[2:3], s[4:5]
	v_writelane_b32 v254, s2, 22
	s_cmp_lt_i32 s9, 13
	s_nop 0
	v_writelane_b32 v254, s3, 23
	s_cselect_b64 s[2:3], -1, 0
	s_cmp_gt_i32 s10, 12
	s_cselect_b64 s[4:5], -1, 0
	s_and_b64 s[2:3], s[2:3], s[4:5]
	v_writelane_b32 v254, s2, 24
	s_cmp_lt_i32 s9, 14
	s_nop 0
	v_writelane_b32 v254, s3, 25
	s_cselect_b64 s[2:3], -1, 0
	s_cmp_gt_i32 s10, 13
	s_cselect_b64 s[4:5], -1, 0
	s_and_b64 s[2:3], s[2:3], s[4:5]
	v_writelane_b32 v254, s2, 26
	s_cmp_gt_i32 s9, 14
	s_nop 0
	v_writelane_b32 v254, s3, 27
	v_writelane_b32 v254, s8, 28
	s_cselect_b64 s[2:3], -1, 0
	s_cmp_lt_i32 s10, 15
	v_writelane_b32 v254, s9, 29
	v_writelane_b32 v254, s10, 30
	s_cselect_b64 s[4:5], -1, 0
	v_writelane_b32 v254, s11, 31
	s_or_b64 s[2:3], s[2:3], s[4:5]
	v_writelane_b32 v254, s2, 32
	s_load_dwordx16 s[4:19], s[0:1], 0x30
	s_nop 0
	v_writelane_b32 v254, s3, 33
	s_load_dwordx2 s[2:3], s[0:1], 0xd8
	s_waitcnt lgkmcnt(0)
; #define LAS __attribute__((address_space(3)))
; DI void convert_layer(const Frame& F, int l) { for (int u = F.wg; u < CM_NPULL; u += F.nwg) convert_pull(F, l, u); }
; #define SEAM() do { if (a.fused) xcd_barrier(bar); } while (0)
; __global__ void __launch_bounds__(NTHREADS, 2) fwd(Args a) {
;     ...
;     LAS unsigned char* lds0 = (LAS unsigned char*)lds_raw;
;     const int wave0 = __builtin_amdgcn_readfirstlane(threadIdx.x >> 6);
;     volatile LAS unsigned* xbw = (volatile LAS unsigned*)(lds0 + LDS_BYTES - 16);
;     if (threadIdx.x == 0) { xbw[0] = 0u; xbw[1] = 0u; xbw[2] = 0u; xbw[3] = 0u; }
;     __syncthreads();
;     XcdBarrier bar; bar.bar = (unsigned*)(a.ws + WS_CTL); bar.x = 0; bar.st = xbw;
;     if (a.fused) bar = xcd_barrier_post((unsigned*)(a.ws + WS_CTL), xbw);
;     ...
;     if (PIN(0)) { { FR(); convert_layer(F, 0); pro_gemv(F); } SEAM(); }
;     if (PIN(1)) { { FR(); pro_modreduce(F); } SEAM(); }
;     if (PIN(2)) { { FR(); pro_h0(F); } SEAM(); }
;     for (int l = a.l_lo; l < a.l_hi; ++l) {
	s_lshl_b32 s2, s2, 2
	v_writelane_b32 v254, s2, 34
	s_add_i32 s2, 0, 0x27ff0
	v_writelane_b32 v254, s2, 35
	s_add_i32 s2, 0, 0x27ff4
	v_writelane_b32 v254, s2, 36
	s_add_i32 s2, 0, 0x27fe0
	v_writelane_b32 v254, s2, 37
	s_add_i32 s2, 0, 0x14800
	v_writelane_b32 v254, s2, 38
	s_add_i32 s2, 0, 0x10800
	v_writelane_b32 v254, s2, 39
	s_add_i32 s2, 0, 0x10ba0
	v_writelane_b32 v254, s2, 40
	s_add_i32 s2, 0, 0x20010
	v_writelane_b32 v254, s2, 41
	s_add_i32 s2, 0, 0x20400
	v_writelane_b32 v254, s2, 42
	s_add_i32 s2, 0, 0x20410
	v_writelane_b32 v254, s2, 43
	s_add_i32 s2, 0, 0x20800
	v_writelane_b32 v254, s2, 44
	s_add_i32 s2, 0, 0x20810
	v_writelane_b32 v254, s2, 45
	v_writelane_b32 v254, s4, 46
	s_nop 1
	v_writelane_b32 v254, s5, 47
	v_writelane_b32 v254, s6, 48
	v_writelane_b32 v254, s7, 49
	v_writelane_b32 v254, s8, 50
	v_writelane_b32 v254, s9, 51
	v_writelane_b32 v254, s10, 52
	v_writelane_b32 v254, s11, 53
	v_writelane_b32 v254, s12, 54
	v_writelane_b32 v254, s13, 55
	v_writelane_b32 v254, s14, 56
	v_writelane_b32 v254, s15, 57
	v_writelane_b32 v254, s16, 58
	v_writelane_b32 v254, s17, 59
	v_writelane_b32 v254, s18, 60
	v_writelane_b32 v254, s19, 61
	s_load_dwordx16 s[4:19], s[0:1], 0x70
	s_waitcnt lgkmcnt(0)
	v_writelane_b32 v254, s4, 62
	s_nop 1
	v_writelane_b32 v255, s6, 0
	v_writelane_b32 v255, s7, 1
	v_writelane_b32 v255, s8, 2
	v_writelane_b32 v255, s9, 3
	v_writelane_b32 v255, s10, 4
	v_writelane_b32 v255, s11, 5
	v_writelane_b32 v255, s12, 6
	v_writelane_b32 v255, s13, 7
	v_writelane_b32 v255, s14, 8
	v_writelane_b32 v255, s15, 9
	v_writelane_b32 v255, s16, 10
	v_writelane_b32 v255, s17, 11
	v_writelane_b32 v255, s18, 12
	v_writelane_b32 v254, s5, 63
	v_writelane_b32 v255, s19, 13
	s_mov_b32 s9, 0
	s_branch .LBB0_261

; DI void unpack8(const u32x4 w, float (&f)[8]) { f[0] = bflo(w.x); f[1] = bfhi(w.x); f[2] = bflo(w.y); f[3] = bfhi(w.y); f[4] = bflo(w.z); f[5] = bfhi(w.z); f[6] = bflo(w.w); f[7] = bfhi(w.w); }
; DI u32x4 pack8(const float (&f)[8]) { u32x4 w; w.x = cvtpk(f[0], f[1]); w.y = cvtpk(f[2], f[3]); w.z = cvtpk(f[4], f[5]); w.w = cvtpk(f[6], f[7]); return w; }
; DI void rope8(const u32x4 x, const u32x4 y, const f32x4 (&rt)[4], bool on, u32x4& ox, u32x4& oy) {
;     float a[8], b[8]; unpack8(x, a); unpack8(y, b);
;     if (on) {
; #pragma unroll
;         for (int j = 0; j < 8; ++j) { const float c = rt[j >> 1][(j & 1) * 2], sn = rt[j >> 1][(j & 1) * 2 + 1]; const float x1 = a[j], x2 = b[j]; a[j] = x1 * c - x2 * sn; b[j] = x1 * sn + x2 * c; }
;     }
;     ox = pack8(a); oy = pack8(b);
; DI void prep_rows(const Frame& F, int l) {
;     ...
;             {
;                 u32x4 ox, oy; rope8(R.x, R.y, R.rt, !ri.ctx, ox, oy);
;                 bf16_t* d = (qk == 0 ? Qd : Kd) + ((size_t)((ri.b * 4 + (hs >> 1)) * 2 + (hs & 1)) * LTOT + ri.tok) * 64 + pg * 32 + 8 * hf;
;                 *(u32x4*)d = ox; *(u32x4*)(d + 16) = oy;
;                 *(u32x4*)(Vd + ((size_t)(ri.b * 4 + (lane >> 4)) * LTOT + ri.tok) * 128 + (lane & 15) * 8) = R.dv;
;             }
;             {
;                 float v[8]; unpack8(R.mc, v); float ss = 0.f;
; #pragma unroll
;                 for (int j = 0; j < 8; ++j) ss += v[j] * v[j];
;                 const float sq = wave_sum(lane < 48 ? ss : 0.f), skv = wave_sum(lane < 48 ? 0.f : ss);
;                 const float rs = lane < 48 ? rsqrtf(sq * (1.f / 384.f) + RMS_EPS) : rsqrtf(skv * (1.f / 128.f) + RMS_EPS);
; #pragma unroll
;                 for (int j = 0; j < 8; ++j) v[j] = v[j] * rs * (j < 4 ? gn0[j & 3] : gn1[j & 3]);
;                 bf16_t* dst = lane < 48 ? cq + (size_t)r * 384 + 8 * lane : ckv + (size_t)r * 256 + 8 * (lane - 48);
;                 *(u32x4*)dst = pack8(v);
;                 if (lane < 16) { unsigned z0 = 0u; asm volatile("" : "+v"(z0)); *(u32x4*)(ckv + (size_t)r * 256 + 128 + 8 * lane) = (u32x4){z0, z0, z0, z0}; }
.LBB0_399:
	s_mov_b32 s92, exec_hi
	s_mov_b32 exec_hi, 0
	v_mul_f32_e32 v166, 0x3e38aa3b, v166
	v_mul_f32_e32 v167, 0x3e38aa3b, v167
	v_mul_f32_e32 v162, 0x3e38aa3b, v162
	v_mul_f32_e32 v168, 0x3e38aa3b, v168
	v_mul_f32_e32 v202, 0x3e38aa3b, v202
	v_mul_f32_e32 v169, 0x3e38aa3b, v169
	v_mul_f32_e32 v204, 0x3e38aa3b, v204
	v_mul_f32_e32 v205, 0x3e38aa3b, v205
	v_mul_f32_e32 v210, 0x3e38aa3b, v210
	v_mul_f32_e32 v211, 0x3e38aa3b, v211
	v_mul_f32_e32 v214, 0x3e38aa3b, v214
	v_mul_f32_e32 v215, 0x3e38aa3b, v215
	v_mul_f32_e32 v206, 0x3e38aa3b, v206
	v_mul_f32_e32 v207, 0x3e38aa3b, v207
	v_mul_f32_e32 v208, 0x3e38aa3b, v208
	v_mul_f32_e32 v209, 0x3e38aa3b, v209
	s_mov_b32 exec_hi, s92
	v_cvt_pk_bf16_f32 v166, v166, v167
	v_cvt_pk_bf16_f32 v167, v162, v168
	s_lshl_b32 s25, s28, 2
	v_lshl_or_b32 v0, s28, 3, v175
	v_mov_b64_e32 v[162:163], s[8:9]
	v_cvt_pk_bf16_f32 v221, v202, v169
	v_mad_i64_i32 v[168:169], s[28:29], v0, s33, v[162:163]
	v_or_b32_e32 v0, s25, v216
	v_mad_i64_i32 v[162:163], s[28:29], v0, s33, v[162:163]
	v_lshlrev_b64 v[168:169], 7, v[168:169]
	v_lshlrev_b64 v[162:163], 8, v[162:163]
	v_cvt_pk_bf16_f32 v218, v204, v205
	v_cvt_pk_bf16_f32 v219, v210, v211
	v_cvt_pk_bf16_f32 v220, v214, v215
	v_lshl_add_u64 v[168:169], v[176:177], 0, v[168:169]
	v_lshl_add_u64 v[162:163], v[178:179], 0, v[162:163]
	v_cvt_pk_bf16_f32 v164, v206, v207
	v_cvt_pk_bf16_f32 v165, v208, v209
	global_store_dwordx4 v[168:169], v[218:221], off
	global_store_dwordx4 v[168:169], v[164:167], off offset:32
	s_waitcnt vmcnt(39)
	global_store_dwordx4 v[162:163], v[158:161], off
	s_waitcnt vmcnt(39)
	v_lshlrev_b32_e32 v162, 16, v154
	v_and_b32_e32 v163, 0xffff0000, v154
	v_lshlrev_b32_e32 v158, 16, v157
	v_and_b32_e32 v159, 0xffff0000, v157
	v_lshlrev_b32_e32 v160, 16, v156
	v_and_b32_e32 v161, 0xffff0000, v156
	v_lshlrev_b32_e32 v156, 16, v155
	v_and_b32_e32 v157, 0xffff0000, v155
	v_pk_mul_f32 v[154:155], v[162:163], v[162:163]
	v_pk_mul_f32 v[168:169], v[156:157], v[156:157]
	v_add_f32_e32 v0, v154, v155
	v_add_f32_e32 v0, v168, v0
	v_pk_mul_f32 v[166:167], v[160:161], v[160:161]
	v_add_f32_e32 v0, v169, v0
	v_add_f32_e32 v0, v166, v0
	v_pk_mul_f32 v[164:165], v[158:159], v[158:159]
	v_add_f32_e32 v0, v167, v0
	v_add_f32_e32 v0, v164, v0
	v_add_f32_e32 v154, v165, v0
	v_cndmask_b32_e64 v0, 0, v154, s[0:1]
	ds_swizzle_b32 v155, v0 offset:swizzle(SWAP,1)
	v_cndmask_b32_e64 v154, v154, 0, s[0:1]
	s_ashr_i32 s15, s14, 31
	s_waitcnt lgkmcnt(0)
	v_add_f32_e32 v0, v0, v155
	ds_swizzle_b32 v155, v0 offset:swizzle(SWAP,2)
	s_waitcnt lgkmcnt(0)
	v_add_f32_e32 v0, v0, v155
	ds_swizzle_b32 v155, v0 offset:swizzle(SWAP,4)
	s_waitcnt lgkmcnt(0)
	v_add_f32_e32 v0, v0, v155
	ds_swizzle_b32 v155, v0 offset:swizzle(SWAP,8)
	s_waitcnt lgkmcnt(0)
	v_add_f32_e32 v0, v0, v155
	ds_swizzle_b32 v155, v0 offset:swizzle(SWAP,16)
	s_waitcnt lgkmcnt(0)
	v_add_f32_e32 v0, v0, v155
	ds_swizzle_b32 v155, v154 offset:swizzle(SWAP,1)
	v_mov_b32_e32 v164, v0
	s_nop 1
	v_permlane32_swap_b32_e32 v0, v164
	s_waitcnt lgkmcnt(0)
	v_add_f32_e32 v154, v154, v155
	ds_swizzle_b32 v155, v154 offset:swizzle(SWAP,2)
	s_waitcnt lgkmcnt(0)
	v_add_f32_e32 v154, v154, v155
	ds_swizzle_b32 v155, v154 offset:swizzle(SWAP,4)
	s_waitcnt lgkmcnt(0)
	v_add_f32_e32 v154, v154, v155
	ds_swizzle_b32 v155, v154 offset:swizzle(SWAP,8)
	s_waitcnt lgkmcnt(0)
	v_add_f32_e32 v154, v154, v155
	ds_swizzle_b32 v155, v154 offset:swizzle(SWAP,16)
	s_waitcnt lgkmcnt(0)
	v_add_f32_e32 v165, v154, v155
	v_mov_b32_e32 v166, v165
	s_nop 1
	v_permlane32_swap_b32_e32 v165, v166
	s_and_saveexec_b64 s[28:29], s[38:39]
	s_xor_b64 s[56:57], exec, s[28:29]
	s_lshl_b64 s[28:29], s[14:15], 9
	v_lshl_add_u64 v[154:155], v[180:181], 0, s[28:29]
	s_movk_i32 s28, 0xfd00
	s_mov_b32 s29, -1
	v_lshl_add_u64 v[154:155], v[154:155], 0, s[28:29]
	s_andn2_saveexec_b64 s[56:57], s[56:57]
	v_lshl_add_u64 v[154:155], s[10:11], 0, v[184:185]
	s_or_b64 exec, exec, s[56:57]
	v_cndmask_b32_e64 v0, v165, v0, s[0:1]
	v_cndmask_b32_e64 v164, v166, v164, s[0:1]
	v_add_f32_e32 v0, v0, v164
	v_fmaak_f32 v0, v217, v0, 0x358637bd
	s_mov_b32 s15, 0x800000
	v_mul_f32_e32 v164, 0x4b800000, v0
	v_cmp_gt_f32_e32 vcc, s15, v0
	s_nop 1
	v_cndmask_b32_e32 v0, v0, v164, vcc
	v_rsq_f32_e32 v0, v0
	s_nop 0
	v_mul_f32_e32 v164, 0x45800000, v0
	v_cndmask_b32_e32 v0, v0, v164, vcc
	v_pk_mul_f32 v[156:157], v[0:1], v[156:157] op_sel_hi:[0,1]
	v_pk_mul_f32 v[164:165], v[4:5], v[156:157]
	v_pk_mul_f32 v[156:157], v[0:1], v[160:161] op_sel_hi:[0,1]
	v_pk_mul_f32 v[162:163], v[0:1], v[162:163] op_sel_hi:[0,1]
	v_pk_mul_f32 v[160:161], v[6:7], v[156:157]
	v_pk_mul_f32 v[156:157], v[0:1], v[158:159] op_sel_hi:[0,1]
	v_pk_mul_f32 v[162:163], v[2:3], v[162:163]
	v_pk_mul_f32 v[166:167], v[8:9], v[156:157]
	v_cvt_pk_bf16_f32 v156, v162, v163
	v_cvt_pk_bf16_f32 v157, v164, v165
	v_cvt_pk_bf16_f32 v158, v160, v161
	v_cvt_pk_bf16_f32 v159, v166, v167
	global_store_dwordx4 v[154:155], v[156:159], off
	s_and_saveexec_b64 s[56:57], s[42:43]
	s_cbranch_execz .LBB0_406
	v_mov_b32_e32 v154, v1
	v_lshl_add_u64 v[158:159], s[10:11], 0, v[186:187]
	s_nop 0
	v_mov_b32_e32 v155, v154
	v_mov_b32_e32 v156, v154
	v_mov_b32_e32 v157, v154
	global_store_dwordx4 v[158:159], v[154:157], off
	s_or_b64 exec, exec, s[56:57]
	s_and_saveexec_b64 s[56:57], s[44:45]
	s_cbranch_execnz .LBB0_407

; DI void unpack8(const u32x4 w, float (&f)[8]) { f[0] = bflo(w.x); f[1] = bfhi(w.x); f[2] = bflo(w.y); f[3] = bfhi(w.y); f[4] = bflo(w.z); f[5] = bfhi(w.z); f[6] = bflo(w.w); f[7] = bfhi(w.w); }
; DI u32x4 pack8(const float (&f)[8]) { u32x4 w; w.x = cvtpk(f[0], f[1]); w.y = cvtpk(f[2], f[3]); w.z = cvtpk(f[4], f[5]); w.w = cvtpk(f[6], f[7]); return w; }
; DI void rope8(const u32x4 x, const u32x4 y, const f32x4 (&rt)[4], bool on, u32x4& ox, u32x4& oy) {
;     float a[8], b[8]; unpack8(x, a); unpack8(y, b);
;     if (on) {
; #pragma unroll
;         for (int j = 0; j < 8; ++j) { const float c = rt[j >> 1][(j & 1) * 2], sn = rt[j >> 1][(j & 1) * 2 + 1]; const float x1 = a[j], x2 = b[j]; a[j] = x1 * c - x2 * sn; b[j] = x1 * sn + x2 * c; }
;     }
;     ox = pack8(a); oy = pack8(b);
; DI void prep_rows(const Frame& F, int l) {
;     ...
;             {
;                 u32x4 ox, oy; rope8(R.x, R.y, R.rt, !ri.ctx, ox, oy);
;                 bf16_t* d = (qk == 0 ? Qd : Kd) + ((size_t)((ri.b * 4 + (hs >> 1)) * 2 + (hs & 1)) * LTOT + ri.tok) * 64 + pg * 32 + 8 * hf;
;                 *(u32x4*)d = ox; *(u32x4*)(d + 16) = oy;
;                 *(u32x4*)(Vd + ((size_t)(ri.b * 4 + (lane >> 4)) * LTOT + ri.tok) * 128 + (lane & 15) * 8) = R.dv;
;             }
;             {
;                 float v[8]; unpack8(R.mc, v); float ss = 0.f;
; #pragma unroll
;                 for (int j = 0; j < 8; ++j) ss += v[j] * v[j];
;                 const float sq = wave_sum(lane < 48 ? ss : 0.f), skv = wave_sum(lane < 48 ? 0.f : ss);
;                 const float rs = lane < 48 ? rsqrtf(sq * (1.f / 384.f) + RMS_EPS) : rsqrtf(skv * (1.f / 128.f) + RMS_EPS);
; #pragma unroll
;                 for (int j = 0; j < 8; ++j) v[j] = v[j] * rs * (j < 4 ? gn0[j & 3] : gn1[j & 3]);
;                 bf16_t* dst = lane < 48 ? cq + (size_t)r * 384 + 8 * lane : ckv + (size_t)r * 256 + 8 * (lane - 48);
;                 *(u32x4*)dst = pack8(v);
;                 if (lane < 16) { unsigned z0 = 0u; asm volatile("" : "+v"(z0)); *(u32x4*)(ckv + (size_t)r * 256 + 128 + 8 * lane) = (u32x4){z0, z0, z0, z0}; }
.LBB0_416:
	s_mov_b32 s92, exec_hi
	s_mov_b32 exec_hi, 0
	v_mul_f32_e32 v126, 0x3e38aa3b, v126
	v_mul_f32_e32 v127, 0x3e38aa3b, v127
	v_mul_f32_e32 v122, 0x3e38aa3b, v122
	v_mul_f32_e32 v128, 0x3e38aa3b, v128
	v_mul_f32_e32 v130, 0x3e38aa3b, v130
	v_mul_f32_e32 v129, 0x3e38aa3b, v129
	v_mul_f32_e32 v132, 0x3e38aa3b, v132
	v_mul_f32_e32 v133, 0x3e38aa3b, v133
	v_mul_f32_e32 v138, 0x3e38aa3b, v138
	v_mul_f32_e32 v139, 0x3e38aa3b, v139
	v_mul_f32_e32 v140, 0x3e38aa3b, v140
	v_mul_f32_e32 v141, 0x3e38aa3b, v141
	v_mul_f32_e32 v134, 0x3e38aa3b, v134
	v_mul_f32_e32 v135, 0x3e38aa3b, v135
	v_mul_f32_e32 v136, 0x3e38aa3b, v136
	v_mul_f32_e32 v137, 0x3e38aa3b, v137
	s_mov_b32 exec_hi, s92
	v_cvt_pk_bf16_f32 v126, v126, v127
	v_cvt_pk_bf16_f32 v127, v122, v128
	s_lshl_b32 s15, s25, 2
	v_lshl_or_b32 v0, s25, 3, v175
	v_mov_b64_e32 v[122:123], s[8:9]
	v_cvt_pk_bf16_f32 v145, v130, v129
	v_mad_i64_i32 v[128:129], s[24:25], v0, s33, v[122:123]
	v_or_b32_e32 v0, s15, v216
	v_mad_i64_i32 v[122:123], s[24:25], v0, s33, v[122:123]
	v_lshlrev_b64 v[128:129], 7, v[128:129]
	v_lshlrev_b64 v[122:123], 8, v[122:123]
	v_cvt_pk_bf16_f32 v142, v132, v133
	v_cvt_pk_bf16_f32 v143, v138, v139
	v_cvt_pk_bf16_f32 v144, v140, v141
	v_lshl_add_u64 v[128:129], v[176:177], 0, v[128:129]
	v_lshl_add_u64 v[122:123], v[178:179], 0, v[122:123]
	v_cvt_pk_bf16_f32 v124, v134, v135
	v_cvt_pk_bf16_f32 v125, v136, v137
	global_store_dwordx4 v[128:129], v[142:145], off
	global_store_dwordx4 v[128:129], v[124:127], off offset:32
	s_waitcnt vmcnt(33)
	global_store_dwordx4 v[122:123], v[118:121], off
	s_waitcnt vmcnt(33)
	v_lshlrev_b32_e32 v122, 16, v114
	v_and_b32_e32 v123, 0xffff0000, v114
	v_lshlrev_b32_e32 v118, 16, v117
	v_and_b32_e32 v119, 0xffff0000, v117
	v_lshlrev_b32_e32 v120, 16, v116
	v_and_b32_e32 v121, 0xffff0000, v116
	v_lshlrev_b32_e32 v116, 16, v115
	v_and_b32_e32 v117, 0xffff0000, v115
	v_pk_mul_f32 v[114:115], v[122:123], v[122:123]
	v_pk_mul_f32 v[128:129], v[116:117], v[116:117]
	v_add_f32_e32 v0, v114, v115
	v_add_f32_e32 v0, v128, v0
	v_pk_mul_f32 v[126:127], v[120:121], v[120:121]
	v_add_f32_e32 v0, v129, v0
	v_add_f32_e32 v0, v126, v0
	v_pk_mul_f32 v[124:125], v[118:119], v[118:119]
	v_add_f32_e32 v0, v127, v0
	v_add_f32_e32 v0, v124, v0
	v_add_f32_e32 v114, v125, v0
	v_cndmask_b32_e64 v0, 0, v114, s[0:1]
	ds_swizzle_b32 v115, v0 offset:swizzle(SWAP,1)
	v_cndmask_b32_e64 v114, v114, 0, s[0:1]
	s_ashr_i32 s53, s52, 31
	s_waitcnt lgkmcnt(0)
	v_add_f32_e32 v0, v0, v115
	ds_swizzle_b32 v115, v0 offset:swizzle(SWAP,2)
	s_waitcnt lgkmcnt(0)
	v_add_f32_e32 v0, v0, v115
	ds_swizzle_b32 v115, v0 offset:swizzle(SWAP,4)
	s_waitcnt lgkmcnt(0)
	v_add_f32_e32 v0, v0, v115
	ds_swizzle_b32 v115, v0 offset:swizzle(SWAP,8)
	s_waitcnt lgkmcnt(0)
	v_add_f32_e32 v0, v0, v115
	ds_swizzle_b32 v115, v0 offset:swizzle(SWAP,16)
	s_waitcnt lgkmcnt(0)
	v_add_f32_e32 v0, v0, v115
	ds_swizzle_b32 v115, v114 offset:swizzle(SWAP,1)
	v_mov_b32_e32 v124, v0
	s_nop 1
	v_permlane32_swap_b32_e32 v0, v124
	s_waitcnt lgkmcnt(0)
	v_add_f32_e32 v114, v114, v115
	ds_swizzle_b32 v115, v114 offset:swizzle(SWAP,2)
	s_waitcnt lgkmcnt(0)
	v_add_f32_e32 v114, v114, v115
	ds_swizzle_b32 v115, v114 offset:swizzle(SWAP,4)
	s_waitcnt lgkmcnt(0)
	v_add_f32_e32 v114, v114, v115
	ds_swizzle_b32 v115, v114 offset:swizzle(SWAP,8)
	s_waitcnt lgkmcnt(0)
	v_add_f32_e32 v114, v114, v115
	ds_swizzle_b32 v115, v114 offset:swizzle(SWAP,16)
	s_waitcnt lgkmcnt(0)
	v_add_f32_e32 v125, v114, v115
	v_mov_b32_e32 v126, v125
	s_nop 1
	v_permlane32_swap_b32_e32 v125, v126
	s_and_saveexec_b64 s[24:25], s[38:39]
	s_xor_b64 s[54:55], exec, s[24:25]
	s_lshl_b64 s[24:25], s[52:53], 9
	v_lshl_add_u64 v[114:115], v[180:181], 0, s[24:25]
	s_movk_i32 s24, 0xfd00
	s_mov_b32 s25, -1
	v_lshl_add_u64 v[114:115], v[114:115], 0, s[24:25]
	s_andn2_saveexec_b64 s[54:55], s[54:55]
	v_mad_i64_i32 v[114:115], s[24:25], s52, v238, v[182:183]
	s_or_b64 exec, exec, s[54:55]
	v_cndmask_b32_e64 v0, v125, v0, s[0:1]
	v_cndmask_b32_e64 v124, v126, v124, s[0:1]
	v_add_f32_e32 v0, v0, v124
	v_fmaak_f32 v0, v217, v0, 0x358637bd
	s_mov_b32 s24, 0x800000
	v_mul_f32_e32 v124, 0x4b800000, v0
	v_cmp_gt_f32_e32 vcc, s24, v0
	s_nop 1
	v_cndmask_b32_e32 v0, v0, v124, vcc
	v_rsq_f32_e32 v0, v0
	s_nop 0
	v_mul_f32_e32 v124, 0x45800000, v0
	v_cndmask_b32_e32 v0, v0, v124, vcc
	v_pk_mul_f32 v[116:117], v[0:1], v[116:117] op_sel_hi:[0,1]
	v_pk_mul_f32 v[124:125], v[4:5], v[116:117]
	v_pk_mul_f32 v[116:117], v[0:1], v[120:121] op_sel_hi:[0,1]
	v_pk_mul_f32 v[122:123], v[0:1], v[122:123] op_sel_hi:[0,1]
	v_pk_mul_f32 v[120:121], v[6:7], v[116:117]
	v_pk_mul_f32 v[116:117], v[0:1], v[118:119] op_sel_hi:[0,1]
	v_pk_mul_f32 v[122:123], v[2:3], v[122:123]
	v_pk_mul_f32 v[126:127], v[8:9], v[116:117]
	v_cvt_pk_bf16_f32 v116, v122, v123
	v_cvt_pk_bf16_f32 v117, v124, v125
	v_cvt_pk_bf16_f32 v118, v120, v121
	v_cvt_pk_bf16_f32 v119, v126, v127
	global_store_dwordx4 v[114:115], v[116:119], off
	s_and_saveexec_b64 s[54:55], s[42:43]
	s_cbranch_execz .LBB0_423
	s_lshl_b64 s[24:25], s[52:53], 9
	v_mov_b32_e32 v114, v1
	v_lshl_add_u64 v[118:119], v[180:181], 0, s[24:25]
	s_nop 0
	v_mov_b32_e32 v115, v114
	v_mov_b32_e32 v116, v114
	v_mov_b32_e32 v117, v114
	global_store_dwordx4 v[118:119], v[114:117], off offset:256
	s_or_b64 exec, exec, s[54:55]
	s_and_saveexec_b64 s[52:53], s[44:45]
	s_cbranch_execnz .LBB0_424

; DI void unpack8(const u32x4 w, float (&f)[8]) { f[0] = bflo(w.x); f[1] = bfhi(w.x); f[2] = bflo(w.y); f[3] = bfhi(w.y); f[4] = bflo(w.z); f[5] = bfhi(w.z); f[6] = bflo(w.w); f[7] = bfhi(w.w); }
; DI u32x4 pack8(const float (&f)[8]) { u32x4 w; w.x = cvtpk(f[0], f[1]); w.y = cvtpk(f[2], f[3]); w.z = cvtpk(f[4], f[5]); w.w = cvtpk(f[6], f[7]); return w; }
; DI void rope8(const u32x4 x, const u32x4 y, const f32x4 (&rt)[4], bool on, u32x4& ox, u32x4& oy) {
;     float a[8], b[8]; unpack8(x, a); unpack8(y, b);
;     if (on) {
; #pragma unroll
;         for (int j = 0; j < 8; ++j) { const float c = rt[j >> 1][(j & 1) * 2], sn = rt[j >> 1][(j & 1) * 2 + 1]; const float x1 = a[j], x2 = b[j]; a[j] = x1 * c - x2 * sn; b[j] = x1 * sn + x2 * c; }
;     }
;     ox = pack8(a); oy = pack8(b);
; DI void prep_rows(const Frame& F, int l) {
;     ...
;             {
;                 u32x4 ox, oy; rope8(R.x, R.y, R.rt, !ri.ctx, ox, oy);
;                 bf16_t* d = (qk == 0 ? Qd : Kd) + ((size_t)((ri.b * 4 + (hs >> 1)) * 2 + (hs & 1)) * LTOT + ri.tok) * 64 + pg * 32 + 8 * hf;
;                 *(u32x4*)d = ox; *(u32x4*)(d + 16) = oy;
;                 *(u32x4*)(Vd + ((size_t)(ri.b * 4 + (lane >> 4)) * LTOT + ri.tok) * 128 + (lane & 15) * 8) = R.dv;
;             }
;             {
;                 float v[8]; unpack8(R.mc, v); float ss = 0.f;
; #pragma unroll
;                 for (int j = 0; j < 8; ++j) ss += v[j] * v[j];
;                 const float sq = wave_sum(lane < 48 ? ss : 0.f), skv = wave_sum(lane < 48 ? 0.f : ss);
;                 const float rs = lane < 48 ? rsqrtf(sq * (1.f / 384.f) + RMS_EPS) : rsqrtf(skv * (1.f / 128.f) + RMS_EPS);
; #pragma unroll
;                 for (int j = 0; j < 8; ++j) v[j] = v[j] * rs * (j < 4 ? gn0[j & 3] : gn1[j & 3]);
;                 bf16_t* dst = lane < 48 ? cq + (size_t)r * 384 + 8 * lane : ckv + (size_t)r * 256 + 8 * (lane - 48);
;                 *(u32x4*)dst = pack8(v);
;                 if (lane < 16) { unsigned z0 = 0u; asm volatile("" : "+v"(z0)); *(u32x4*)(ckv + (size_t)r * 256 + 128 + 8 * lane) = (u32x4){z0, z0, z0, z0}; }
.LBB0_433:
	s_mov_b32 s92, exec_hi
	s_mov_b32 exec_hi, 0
	v_mul_f32_e32 v86, 0x3e38aa3b, v86
	v_mul_f32_e32 v87, 0x3e38aa3b, v87
	v_mul_f32_e32 v82, 0x3e38aa3b, v82
	v_mul_f32_e32 v88, 0x3e38aa3b, v88
	v_mul_f32_e32 v90, 0x3e38aa3b, v90
	v_mul_f32_e32 v89, 0x3e38aa3b, v89
	v_mul_f32_e32 v92, 0x3e38aa3b, v92
	v_mul_f32_e32 v93, 0x3e38aa3b, v93
	v_mul_f32_e32 v98, 0x3e38aa3b, v98
	v_mul_f32_e32 v99, 0x3e38aa3b, v99
	v_mul_f32_e32 v100, 0x3e38aa3b, v100
	v_mul_f32_e32 v101, 0x3e38aa3b, v101
	v_mul_f32_e32 v94, 0x3e38aa3b, v94
	v_mul_f32_e32 v95, 0x3e38aa3b, v95
	v_mul_f32_e32 v96, 0x3e38aa3b, v96
	v_mul_f32_e32 v97, 0x3e38aa3b, v97
	s_mov_b32 exec_hi, s92
	v_cvt_pk_bf16_f32 v86, v86, v87
	v_cvt_pk_bf16_f32 v87, v82, v88
	s_lshl_b32 s15, s24, 2
	v_lshl_or_b32 v0, s24, 3, v175
	v_mov_b64_e32 v[82:83], s[8:9]
	v_cvt_pk_bf16_f32 v105, v90, v89
	v_mad_i64_i32 v[88:89], s[24:25], v0, s33, v[82:83]
	v_or_b32_e32 v0, s15, v216
	v_mad_i64_i32 v[82:83], s[24:25], v0, s33, v[82:83]
	v_lshlrev_b64 v[88:89], 7, v[88:89]
	v_lshlrev_b64 v[82:83], 8, v[82:83]
	v_cvt_pk_bf16_f32 v102, v92, v93
	v_cvt_pk_bf16_f32 v103, v98, v99
	v_cvt_pk_bf16_f32 v104, v100, v101
	v_lshl_add_u64 v[88:89], v[176:177], 0, v[88:89]
	v_lshl_add_u64 v[82:83], v[178:179], 0, v[82:83]
	v_cvt_pk_bf16_f32 v84, v94, v95
	v_cvt_pk_bf16_f32 v85, v96, v97
	global_store_dwordx4 v[88:89], v[102:105], off
	global_store_dwordx4 v[88:89], v[84:87], off offset:32
	s_waitcnt vmcnt(27)
	global_store_dwordx4 v[82:83], v[78:81], off
	s_waitcnt vmcnt(27)
	v_lshlrev_b32_e32 v82, 16, v74
	v_and_b32_e32 v83, 0xffff0000, v74
	v_lshlrev_b32_e32 v78, 16, v77
	v_and_b32_e32 v79, 0xffff0000, v77
	v_lshlrev_b32_e32 v80, 16, v76
	v_and_b32_e32 v81, 0xffff0000, v76
	v_lshlrev_b32_e32 v76, 16, v75
	v_and_b32_e32 v77, 0xffff0000, v75
	v_pk_mul_f32 v[74:75], v[82:83], v[82:83]
	v_pk_mul_f32 v[88:89], v[76:77], v[76:77]
	v_add_f32_e32 v0, v74, v75
	v_add_f32_e32 v0, v88, v0
	v_pk_mul_f32 v[86:87], v[80:81], v[80:81]
	v_add_f32_e32 v0, v89, v0
	v_add_f32_e32 v0, v86, v0
	v_pk_mul_f32 v[84:85], v[78:79], v[78:79]
	v_add_f32_e32 v0, v87, v0
	v_add_f32_e32 v0, v84, v0
	v_add_f32_e32 v74, v85, v0
	v_cndmask_b32_e64 v0, 0, v74, s[0:1]
	ds_swizzle_b32 v75, v0 offset:swizzle(SWAP,1)
	v_cndmask_b32_e64 v74, v74, 0, s[0:1]
	s_ashr_i32 s49, s48, 31
	s_waitcnt lgkmcnt(0)
	v_add_f32_e32 v0, v0, v75
	ds_swizzle_b32 v75, v0 offset:swizzle(SWAP,2)
	s_waitcnt lgkmcnt(0)
	v_add_f32_e32 v0, v0, v75
	ds_swizzle_b32 v75, v0 offset:swizzle(SWAP,4)
	s_waitcnt lgkmcnt(0)
	v_add_f32_e32 v0, v0, v75
	ds_swizzle_b32 v75, v0 offset:swizzle(SWAP,8)
	s_waitcnt lgkmcnt(0)
	v_add_f32_e32 v0, v0, v75
	ds_swizzle_b32 v75, v0 offset:swizzle(SWAP,16)
	s_waitcnt lgkmcnt(0)
	v_add_f32_e32 v0, v0, v75
	ds_swizzle_b32 v75, v74 offset:swizzle(SWAP,1)
	v_mov_b32_e32 v84, v0
	s_nop 1
	v_permlane32_swap_b32_e32 v0, v84
	s_waitcnt lgkmcnt(0)
	v_add_f32_e32 v74, v74, v75
	ds_swizzle_b32 v75, v74 offset:swizzle(SWAP,2)
	s_waitcnt lgkmcnt(0)
	v_add_f32_e32 v74, v74, v75
	ds_swizzle_b32 v75, v74 offset:swizzle(SWAP,4)
	s_waitcnt lgkmcnt(0)
	v_add_f32_e32 v74, v74, v75
	ds_swizzle_b32 v75, v74 offset:swizzle(SWAP,8)
	s_waitcnt lgkmcnt(0)
	v_add_f32_e32 v74, v74, v75
	ds_swizzle_b32 v75, v74 offset:swizzle(SWAP,16)
	s_waitcnt lgkmcnt(0)
	v_add_f32_e32 v85, v74, v75
	v_mov_b32_e32 v86, v85
	s_nop 1
	v_permlane32_swap_b32_e32 v85, v86
	s_and_saveexec_b64 s[24:25], s[38:39]
	s_xor_b64 s[50:51], exec, s[24:25]
	s_lshl_b64 s[24:25], s[48:49], 9
	v_lshl_add_u64 v[74:75], v[180:181], 0, s[24:25]
	s_movk_i32 s24, 0xfd00
	s_mov_b32 s25, -1
	v_lshl_add_u64 v[74:75], v[74:75], 0, s[24:25]
	s_andn2_saveexec_b64 s[50:51], s[50:51]
	v_mad_i64_i32 v[74:75], s[24:25], s48, v238, v[182:183]
	s_or_b64 exec, exec, s[50:51]
	v_cndmask_b32_e64 v0, v85, v0, s[0:1]
	v_cndmask_b32_e64 v84, v86, v84, s[0:1]
	v_add_f32_e32 v0, v0, v84
	v_fmaak_f32 v0, v217, v0, 0x358637bd
	s_mov_b32 s23, 0x800000
	v_mul_f32_e32 v84, 0x4b800000, v0
	v_cmp_gt_f32_e32 vcc, s23, v0
	s_nop 1
	v_cndmask_b32_e32 v0, v0, v84, vcc
	v_rsq_f32_e32 v0, v0
	s_nop 0
	v_mul_f32_e32 v84, 0x45800000, v0
	v_cndmask_b32_e32 v0, v0, v84, vcc
	v_pk_mul_f32 v[76:77], v[0:1], v[76:77] op_sel_hi:[0,1]
	v_pk_mul_f32 v[84:85], v[4:5], v[76:77]
	v_pk_mul_f32 v[76:77], v[0:1], v[80:81] op_sel_hi:[0,1]
	v_pk_mul_f32 v[82:83], v[0:1], v[82:83] op_sel_hi:[0,1]
	v_pk_mul_f32 v[80:81], v[6:7], v[76:77]
	v_pk_mul_f32 v[76:77], v[0:1], v[78:79] op_sel_hi:[0,1]
	v_pk_mul_f32 v[82:83], v[2:3], v[82:83]
	v_pk_mul_f32 v[86:87], v[8:9], v[76:77]
	v_cvt_pk_bf16_f32 v76, v82, v83
	v_cvt_pk_bf16_f32 v77, v84, v85
	v_cvt_pk_bf16_f32 v78, v80, v81
	v_cvt_pk_bf16_f32 v79, v86, v87
	global_store_dwordx4 v[74:75], v[76:79], off
	s_and_saveexec_b64 s[50:51], s[42:43]
	s_cbranch_execz .LBB0_440
	s_lshl_b64 s[24:25], s[48:49], 9
	v_mov_b32_e32 v74, v1
	v_lshl_add_u64 v[78:79], v[180:181], 0, s[24:25]
	s_nop 0
	v_mov_b32_e32 v75, v74
	v_mov_b32_e32 v76, v74
	v_mov_b32_e32 v77, v74
	global_store_dwordx4 v[78:79], v[74:77], off offset:256
	s_or_b64 exec, exec, s[50:51]
	s_and_saveexec_b64 s[48:49], s[44:45]
	s_cbranch_execnz .LBB0_441

; DI void unpack8(const u32x4 w, float (&f)[8]) { f[0] = bflo(w.x); f[1] = bfhi(w.x); f[2] = bflo(w.y); f[3] = bfhi(w.y); f[4] = bflo(w.z); f[5] = bfhi(w.z); f[6] = bflo(w.w); f[7] = bfhi(w.w); }
; DI u32x4 pack8(const float (&f)[8]) { u32x4 w; w.x = cvtpk(f[0], f[1]); w.y = cvtpk(f[2], f[3]); w.z = cvtpk(f[4], f[5]); w.w = cvtpk(f[6], f[7]); return w; }
; DI void rope8(const u32x4 x, const u32x4 y, const f32x4 (&rt)[4], bool on, u32x4& ox, u32x4& oy) {
;     float a[8], b[8]; unpack8(x, a); unpack8(y, b);
;     if (on) {
; #pragma unroll
;         for (int j = 0; j < 8; ++j) { const float c = rt[j >> 1][(j & 1) * 2], sn = rt[j >> 1][(j & 1) * 2 + 1]; const float x1 = a[j], x2 = b[j]; a[j] = x1 * c - x2 * sn; b[j] = x1 * sn + x2 * c; }
;     }
;     ox = pack8(a); oy = pack8(b);
; DI void prep_rows(const Frame& F, int l) {
;     ...
;             {
;                 u32x4 ox, oy; rope8(R.x, R.y, R.rt, !ri.ctx, ox, oy);
;                 bf16_t* d = (qk == 0 ? Qd : Kd) + ((size_t)((ri.b * 4 + (hs >> 1)) * 2 + (hs & 1)) * LTOT + ri.tok) * 64 + pg * 32 + 8 * hf;
;                 *(u32x4*)d = ox; *(u32x4*)(d + 16) = oy;
;                 *(u32x4*)(Vd + ((size_t)(ri.b * 4 + (lane >> 4)) * LTOT + ri.tok) * 128 + (lane & 15) * 8) = R.dv;
;             }
;             {
;                 float v[8]; unpack8(R.mc, v); float ss = 0.f;
; #pragma unroll
;                 for (int j = 0; j < 8; ++j) ss += v[j] * v[j];
;                 const float sq = wave_sum(lane < 48 ? ss : 0.f), skv = wave_sum(lane < 48 ? 0.f : ss);
;                 const float rs = lane < 48 ? rsqrtf(sq * (1.f / 384.f) + RMS_EPS) : rsqrtf(skv * (1.f / 128.f) + RMS_EPS);
; #pragma unroll
;                 for (int j = 0; j < 8; ++j) v[j] = v[j] * rs * (j < 4 ? gn0[j & 3] : gn1[j & 3]);
;                 bf16_t* dst = lane < 48 ? cq + (size_t)r * 384 + 8 * lane : ckv + (size_t)r * 256 + 8 * (lane - 48);
;                 *(u32x4*)dst = pack8(v);
;                 if (lane < 16) { unsigned z0 = 0u; asm volatile("" : "+v"(z0)); *(u32x4*)(ckv + (size_t)r * 256 + 128 + 8 * lane) = (u32x4){z0, z0, z0, z0}; }
.LBB0_450:
	s_mov_b32 s92, exec_hi
	s_mov_b32 exec_hi, 0
	v_mul_f32_e32 v46, 0x3e38aa3b, v46
	v_mul_f32_e32 v47, 0x3e38aa3b, v47
	v_mul_f32_e32 v42, 0x3e38aa3b, v42
	v_mul_f32_e32 v48, 0x3e38aa3b, v48
	v_mul_f32_e32 v50, 0x3e38aa3b, v50
	v_mul_f32_e32 v49, 0x3e38aa3b, v49
	v_mul_f32_e32 v52, 0x3e38aa3b, v52
	v_mul_f32_e32 v53, 0x3e38aa3b, v53
	v_mul_f32_e32 v58, 0x3e38aa3b, v58
	v_mul_f32_e32 v59, 0x3e38aa3b, v59
	v_mul_f32_e32 v60, 0x3e38aa3b, v60
	v_mul_f32_e32 v61, 0x3e38aa3b, v61
	v_mul_f32_e32 v54, 0x3e38aa3b, v54
	v_mul_f32_e32 v55, 0x3e38aa3b, v55
	v_mul_f32_e32 v56, 0x3e38aa3b, v56
	v_mul_f32_e32 v57, 0x3e38aa3b, v57
	s_mov_b32 exec_hi, s92
	v_cvt_pk_bf16_f32 v46, v46, v47
	v_cvt_pk_bf16_f32 v47, v42, v48
	s_lshl_b32 s5, s15, 2
	v_lshl_or_b32 v0, s15, 3, v175
	v_mov_b64_e32 v[42:43], s[8:9]
	v_cvt_pk_bf16_f32 v65, v50, v49
	v_mad_i64_i32 v[48:49], s[24:25], v0, s33, v[42:43]
	v_or_b32_e32 v0, s5, v216
	v_mad_i64_i32 v[42:43], s[24:25], v0, s33, v[42:43]
	v_lshlrev_b64 v[48:49], 7, v[48:49]
	v_lshlrev_b64 v[42:43], 8, v[42:43]
	v_cvt_pk_bf16_f32 v62, v52, v53
	v_cvt_pk_bf16_f32 v63, v58, v59
	v_cvt_pk_bf16_f32 v64, v60, v61
	v_lshl_add_u64 v[48:49], v[176:177], 0, v[48:49]
	v_lshl_add_u64 v[42:43], v[178:179], 0, v[42:43]
	v_cvt_pk_bf16_f32 v44, v54, v55
	v_cvt_pk_bf16_f32 v45, v56, v57
	global_store_dwordx4 v[48:49], v[62:65], off
	global_store_dwordx4 v[48:49], v[44:47], off offset:32
	s_waitcnt vmcnt(21)
	global_store_dwordx4 v[42:43], v[38:41], off
	s_waitcnt vmcnt(21)
	v_lshlrev_b32_e32 v42, 16, v34
	v_and_b32_e32 v43, 0xffff0000, v34
	v_lshlrev_b32_e32 v38, 16, v37
	v_and_b32_e32 v39, 0xffff0000, v37
	v_lshlrev_b32_e32 v40, 16, v36
	v_and_b32_e32 v41, 0xffff0000, v36
	v_lshlrev_b32_e32 v36, 16, v35
	v_and_b32_e32 v37, 0xffff0000, v35
	v_pk_mul_f32 v[34:35], v[42:43], v[42:43]
	v_pk_mul_f32 v[48:49], v[36:37], v[36:37]
	v_add_f32_e32 v0, v34, v35
	v_add_f32_e32 v0, v48, v0
	v_pk_mul_f32 v[46:47], v[40:41], v[40:41]
	v_add_f32_e32 v0, v49, v0
	v_add_f32_e32 v0, v46, v0
	v_pk_mul_f32 v[44:45], v[38:39], v[38:39]
	v_add_f32_e32 v0, v47, v0
	v_add_f32_e32 v0, v44, v0
	v_add_f32_e32 v34, v45, v0
	v_cndmask_b32_e64 v0, 0, v34, s[0:1]
	ds_swizzle_b32 v35, v0 offset:swizzle(SWAP,1)
	v_cndmask_b32_e64 v34, v34, 0, s[0:1]
	s_ashr_i32 s23, s22, 31
	s_waitcnt lgkmcnt(0)
	v_add_f32_e32 v0, v0, v35
	ds_swizzle_b32 v35, v0 offset:swizzle(SWAP,2)
	s_waitcnt lgkmcnt(0)
	v_add_f32_e32 v0, v0, v35
	ds_swizzle_b32 v35, v0 offset:swizzle(SWAP,4)
	s_waitcnt lgkmcnt(0)
	v_add_f32_e32 v0, v0, v35
	ds_swizzle_b32 v35, v0 offset:swizzle(SWAP,8)
	s_waitcnt lgkmcnt(0)
	v_add_f32_e32 v0, v0, v35
	ds_swizzle_b32 v35, v0 offset:swizzle(SWAP,16)
	s_waitcnt lgkmcnt(0)
	v_add_f32_e32 v0, v0, v35
	ds_swizzle_b32 v35, v34 offset:swizzle(SWAP,1)
	v_mov_b32_e32 v44, v0
	s_nop 1
	v_permlane32_swap_b32_e32 v0, v44
	s_waitcnt lgkmcnt(0)
	v_add_f32_e32 v34, v34, v35
	ds_swizzle_b32 v35, v34 offset:swizzle(SWAP,2)
	s_waitcnt lgkmcnt(0)
	v_add_f32_e32 v34, v34, v35
	ds_swizzle_b32 v35, v34 offset:swizzle(SWAP,4)
	s_waitcnt lgkmcnt(0)
	v_add_f32_e32 v34, v34, v35
	ds_swizzle_b32 v35, v34 offset:swizzle(SWAP,8)
	s_waitcnt lgkmcnt(0)
	v_add_f32_e32 v34, v34, v35
	ds_swizzle_b32 v35, v34 offset:swizzle(SWAP,16)
	s_waitcnt lgkmcnt(0)
	v_add_f32_e32 v45, v34, v35
	v_mov_b32_e32 v46, v45
	s_nop 1
	v_permlane32_swap_b32_e32 v45, v46
	s_and_saveexec_b64 s[24:25], s[38:39]
	s_xor_b64 s[46:47], exec, s[24:25]
	s_lshl_b64 s[24:25], s[22:23], 9
	v_lshl_add_u64 v[34:35], v[180:181], 0, s[24:25]
	s_movk_i32 s24, 0xfd00
	s_mov_b32 s25, -1
	v_lshl_add_u64 v[34:35], v[34:35], 0, s[24:25]
	s_andn2_saveexec_b64 s[46:47], s[46:47]
	v_mad_i64_i32 v[34:35], s[24:25], s22, v238, v[182:183]
	s_or_b64 exec, exec, s[46:47]
	v_cndmask_b32_e64 v0, v45, v0, s[0:1]
	v_cndmask_b32_e64 v44, v46, v44, s[0:1]
	v_add_f32_e32 v0, v0, v44
	v_fmaak_f32 v0, v217, v0, 0x358637bd
	s_mov_b32 s15, 0x800000
	v_mul_f32_e32 v44, 0x4b800000, v0
	v_cmp_gt_f32_e32 vcc, s15, v0
	s_nop 1
	v_cndmask_b32_e32 v0, v0, v44, vcc
	v_rsq_f32_e32 v0, v0
	s_nop 0
	v_mul_f32_e32 v44, 0x45800000, v0
	v_cndmask_b32_e32 v0, v0, v44, vcc
	v_pk_mul_f32 v[36:37], v[0:1], v[36:37] op_sel_hi:[0,1]
	v_pk_mul_f32 v[44:45], v[4:5], v[36:37]
	v_pk_mul_f32 v[36:37], v[0:1], v[40:41] op_sel_hi:[0,1]
	v_pk_mul_f32 v[42:43], v[0:1], v[42:43] op_sel_hi:[0,1]
	v_pk_mul_f32 v[40:41], v[6:7], v[36:37]
	v_pk_mul_f32 v[36:37], v[0:1], v[38:39] op_sel_hi:[0,1]
	v_pk_mul_f32 v[42:43], v[2:3], v[42:43]
	v_pk_mul_f32 v[46:47], v[8:9], v[36:37]
	v_cvt_pk_bf16_f32 v36, v42, v43
	v_cvt_pk_bf16_f32 v37, v44, v45
	v_cvt_pk_bf16_f32 v38, v40, v41
	v_cvt_pk_bf16_f32 v39, v46, v47
	global_store_dwordx4 v[34:35], v[36:39], off
	s_and_saveexec_b64 s[46:47], s[42:43]
	s_cbranch_execz .LBB0_456
	s_lshl_b64 s[22:23], s[22:23], 9
	v_mov_b32_e32 v34, v1
	v_lshl_add_u64 v[38:39], v[180:181], 0, s[22:23]
	s_nop 0
	v_mov_b32_e32 v35, v34
	v_mov_b32_e32 v36, v34
	v_mov_b32_e32 v37, v34
	global_store_dwordx4 v[38:39], v[34:37], off offset:256

; #define LAS __attribute__((address_space(3)))
; template <int DQK, int SDEPTH, bool OUT_BF16, int QREG = DQK / 16, bool OUT_F16 = false> ...
;     ...
;   const int wid = tid >> 6, lane = tid & 63, r32 = lane & 31, hi = lane >> 5;
;   LAS char* V_lds = lds; LAS char* K_lds = lds + 2 * SHM_V;
;   LAS float* ws = (LAS float*)(lds + 2 * SHM_V + 2 * SHM_K) + wid * 64; LAS float* li_l = ws; LAS float* al_l = ws + 32;
;   constexpr int QLDS = DQK / 16 - QREG;
;   LAS char* Qp = lds + 2 * SHM_V + 2 * SHM_K + NW * 64 * 4 + wid * (QLDS * 1024) + lane * 16;
;   float m_reg = -1e30f, l_reg = 0; f32x16 o[4] = {}; bf16x8 qr[QREG];
;   const bf16_t* Qw = Qb + (long)(wid * QBLK + r32) * DQK + hi * 8;
; #pragma unroll
;   for (int d0 = 0; d0 < QREG; ++d0) qr[d0] = *reinterpret_cast<const bf16x8*>(Qw + d0 * 16);
;   if constexpr (QLDS > 0) {
;     static_assert(DQK != 192 || QLDS >= 4, "rope fragments must be among the LDS ones");
; #pragma unroll
;     for (int d0 = QREG; d0 < (DQK == 192 ? 8 : DQK / 16); ++d0) *(LAS bf16x8*)(Qp + (d0 - QREG) * 1024) = *reinterpret_cast<const bf16x8*>(Qw + d0 * 16);
;     if constexpr (DQK == 192) {
;       u32x4 f[4];
; #pragma unroll
;       for (int d0 = 0; d0 < 4; ++d0) f[d0] = *reinterpret_cast<const u32x4*>(Qw + (8 + d0) * 16);
;       if (tq0 >= 0) { const int t = tq0 + wid * QBLK + r32; const f32x2* rr = rt + (t >> 6) * 16 + 8 * hi; const f32x2* rc = rt + (t & 63) * 16 + 8 * hi;
; #pragma unroll
; DI void diff_unit(const Frame& F, int t) {
;     ...
;     const int bh = hd >> 1, sub = hd & 1, b = bh >> 2, h = bh & 3;
;     const int tok0 = ctx ? 0 : CTX + qb * 256; const int row0 = ctx ? MLAT + b * CTX : b * SEQ + qb * 256;
;     const int key0 = half == 1 ? LTOT / 2 : 0, nkeys = ctx ? CTX : (half >= 0 ? LTOT / 2 : LTOT);
;     _Float16* Ob = half == 1 ? (_Float16*)(F.ws + WS_OD2) : (_Float16*)(F.big + WB_OD);
;     f32x2* st = half >= 0 ? (f32x2*)(F.big + WB_DST) + ((size_t)((half * 2 + sub) * 4 + h) * MT + row0) : (f32x2*)nullptr;
;     att::attn_body<64, 2, false, 4, true>(Qd + ((size_t)hd * LTOT + tok0) * 64, Kd + ((size_t)hd * LTOT + key0) * 64, Vd + ((size_t)bh * LTOT + key0) * 128, Ob + ((size_t)sub * MT + row0) * 512 + h * 128, 512, nkeys, (LAS char*)F.lds, F.tid, nullptr, -1, st);
.LBB0_781:
	s_add_i32 s2, s0, 0x100
	s_ashr_i32 s3, s2, 31
	s_and_b64 s[0:1], s[42:43], exec
	s_cselect_b32 s3, 0, s3
	s_cselect_b32 s2, 0, s2
	s_cmp_eq_u32 s8, 1
	s_cselect_b64 s[40:41], -1, 0
	s_and_b64 s[0:1], s[40:41], exec
	s_mul_i32 s10, s24, 0x2100
	s_cselect_b32 s28, 0x1080, 0
	s_mul_hi_i32 s8, s24, 0x2100
	s_add_u32 s0, s2, s10
	s_addc_u32 s1, s3, s8
	s_lshl_b64 s[0:1], s[0:1], 7
	s_add_u32 s0, s4, s0
	s_addc_u32 s1, s5, s1
	s_add_u32 s2, s10, s28
	s_addc_u32 s3, s8, 0
	s_lshl_b64 s[2:3], s[2:3], 7
	s_add_u32 s2, s4, s2
	s_addc_u32 s3, s5, s3
	s_mul_i32 s10, s25, 0x2100
	s_mul_hi_i32 s8, s25, 0x2100
	s_add_u32 s10, s10, s28
	s_addc_u32 s11, s8, 0
	s_lshl_b64 s[10:11], s[10:11], 8
	v_ashrrev_i32_e32 v4, 31, v2
	s_add_u32 s8, s4, s10
	v_lshrrev_b32_e32 v4, 29, v4
	s_addc_u32 s11, s5, s11
	v_ashrrev_i32_e32 v16, 4, v2
	v_add_u32_e32 v4, v2, v4
	s_add_u32 s10, s8, 0x37404000
	v_lshlrev_b32_e32 v3, 3, v58
	v_ashrrev_i32_e32 v20, 3, v4
	v_and_b32_e32 v4, -8, v4
	v_ashrrev_i32_e32 v17, 31, v16
	s_addc_u32 s11, s11, 0
	v_and_b32_e32 v0, 0x78, v3
	v_add_u32_e32 v18, 32, v16
	v_sub_u32_e32 v26, v2, v4
	v_lshlrev_b64 v[50:51], 8, v[16:17]
	v_lshlrev_b32_e32 v12, 3, v26
	v_lshl_add_u64 v[4:5], s[10:11], 0, v[50:51]
	v_lshlrev_b32_e32 v6, 1, v0
	v_mov_b32_e32 v7, v1
	v_ashrrev_i32_e32 v19, 31, v18
	v_ashrrev_i32_e32 v21, 31, v20
	v_lshl_add_u64 v[56:57], v[4:5], 0, v[6:7]
	v_lshlrev_b64 v[4:5], 8, v[18:19]
	v_ashrrev_i32_e32 v13, 31, v12
	v_lshlrev_b64 v[52:53], 7, v[20:21]
	v_lshl_add_u64 v[4:5], s[10:11], 0, v[4:5]
	v_lshl_add_u64 v[14:15], s[2:3], 0, v[52:53]
	v_lshlrev_b64 v[54:55], 1, v[12:13]
	v_lshl_add_u64 v[8:9], v[4:5], 0, v[6:7]
	v_lshl_add_u64 v[76:77], v[14:15], 0, v[54:55]
	s_mov_b32 s2, 0x36384000
	global_load_dwordx4 v[4:7], v[56:57], off
	s_nop 0
	global_load_dwordx4 v[8:11], v[8:9], off
	v_add_co_u32_e32 v12, vcc, s2, v76
	v_ashrrev_i32_e32 v17, 1, v2
	s_movk_i32 s2, 0xffe0
	v_addc_co_u32_e32 v13, vcc, 0, v77, vcc
	v_bfi_b32 v154, s2, v17, v58
	global_load_dwordx4 v[12:15], v[12:13], off
	v_ashrrev_i32_e32 v155, 31, v154
	v_bfe_u32 v166, v58, 5, 1
	v_lshlrev_b64 v[22:23], 7, v[154:155]
	v_lshl_add_u64 v[22:23], s[0:1], 0, v[22:23]
	v_lshlrev_b32_e32 v0, 4, v166
	v_lshl_add_u64 v[22:23], v[22:23], 0, v[0:1]
	s_mov_b32 s0, 0x35304000
	v_add_co_u32_e32 v24, vcc, s0, v22
	s_mov_b64 s[0:1], 0x35304000
	s_nop 0
	v_addc_co_u32_e32 v25, vcc, 0, v23, vcc
	global_load_dwordx4 v[110:113], v[24:25], off
	v_lshl_add_u64 v[22:23], v[22:23], 0, s[0:1]
	global_load_dwordx4 v[106:109], v[22:23], off offset:32
	global_load_dwordx4 v[102:105], v[22:23], off offset:64
	global_load_dwordx4 v[98:101], v[22:23], off offset:96
	v_and_b32_e32 v19, 0xfffff0, v16
	v_lshlrev_b32_e32 v21, 1, v16
	v_and_or_b32 v19, v21, 8, v19
	v_lshrrev_b32_e32 v24, 1, v16
	v_bfe_u32 v3, v3, 5, 2
	v_and_b32_e32 v16, 3, v16
	v_and_b32_e32 v21, 0xfffff0, v18
	v_lshlrev_b32_e32 v18, 1, v18
	v_lshrrev_b32_e32 v19, 1, v19
	v_lshlrev_b32_e32 v59, 4, v58
	v_and_or_b32 v16, v24, 4, v16
	v_and_or_b32 v18, v18, 8, v21
	v_or_b32_e32 v19, v19, v3
	v_and_b32_e32 v25, 48, v59
	v_lshlrev_b32_e32 v16, 6, v16
	v_lshrrev_b32_e32 v18, 1, v18
	v_lshlrev_b32_e32 v19, 9, v19
	v_or_b32_e32 v3, v18, v3
	v_or3_b32 v18, v19, v16, v25
	v_lshlrev_b32_e32 v3, 9, v3
	v_add_u32_e32 v172, 0, v18
	v_or3_b32 v3, v3, v16, v25
	s_waitcnt vmcnt(0)
	v_add_u32_e32 v173, 0, v3
	v_lshlrev_b32_e32 v3, 7, v20
	v_and_b32_e32 v167, 31, v58
	s_movk_i32 s0, 0x70
	v_and_b32_e32 v2, 0x3fffffc0, v2
	v_lshl_add_u32 v157, v2, 2, 0
	v_and_b32_e32 v78, 63, v58
	s_mul_hi_i32 s3, s25, 0x210000
	s_mul_i32 s25, s25, 0x210000
	s_mov_b32 s8, s9
	v_and_b32_e32 v156, 0xffffffe0, v17
	s_mov_b32 s10, s9
	s_mov_b32 s11, s9
	s_mov_b32 s12, s9
	s_mov_b32 s13, s9
	s_mov_b32 s14, s9
	s_mov_b32 s15, s9
	s_mov_b32 s16, s9
	s_mov_b32 s17, s9
	s_mov_b32 s18, s9
	s_mov_b32 s19, s9
	s_mov_b32 s20, s9
	s_mov_b32 s21, s9
	s_mov_b32 s22, s9
	s_mov_b32 s23, s9
	s_mov_b32 s46, 1
	v_lshl_add_u32 v168, v167, 2, v157
	v_mov_b32_e32 v170, 0
	s_waitcnt vmcnt(6)
	ds_write_b128 v172, v[4:7]
	v_bitop3_b32 v4, v20, v26, 7 bitop3:0x6c
	v_lshl_add_u32 v4, v4, 4, 0
	v_add_u32_e32 v174, v4, v3
	s_waitcnt vmcnt(5)
	ds_write_b128 v173, v[8:11]
	v_bitop3_b32 v3, v0, v59, s0 bitop3:0x78
	s_movk_i32 s0, 0x4000
	v_add_co_u32_e32 v2, vcc, s0, v56
	s_waitcnt vmcnt(4)
	ds_write_b128 v174, v[12:15] offset:32768
	v_lshl_add_u32 v12, v167, 7, 0
	v_add_u32_e32 v175, v12, v3
	s_waitcnt lgkmcnt(0)
	s_barrier
; DI void partialSM(f32x16& p0, f32x16& p1, float& m_reg, float& mn, float& alpha, const float SCALE) {
;   const float C = SCALE * 1.4426950408889634f;
;   float pmax = p0[0];
; #pragma unroll
;   for (int r = 1; r < 16; ++r) pmax = fmaxf(pmax, p0[r]);
; #pragma unroll
;   for (int r = 0; r < 16; ++r) pmax = fmaxf(pmax, p1[r]);
;   { auto rr = __builtin_amdgcn_permlane32_swap(__float_as_uint(pmax), __float_as_uint(pmax), false, false);
;     pmax = fmaxf(__uint_as_float(rr[0]), __uint_as_float(rr[1])); }
;   if (__builtin_expect(__all(pmax - m_reg <= THR / SCALE), 1)) { mn = m_reg; alpha = 1.f; }
;   else { mn = fmaxf(m_reg, pmax); alpha = __builtin_amdgcn_exp2f((m_reg - mn) * C); m_reg = mn; }
;   const float mnC = -mn * C;
; #pragma unroll
;   for (int r = 0; r < 16; ++r) p0[r] = fmaf(p0[r], C, mnC);
; #pragma unroll
;   for (int r = 0; r < 16; ++r) p1[r] = fmaf(p1[r], C, mnC);
; #pragma unroll
;   for (int r = 0; r < 16; ++r) p0[r] = __builtin_amdgcn_exp2f(p0[r]);
; }
	ds_read_b128 v[4:7], v175 offset:32768
	ds_read_b128 v[8:11], v175 offset:36864
	v_and_b32_e32 v13, 0x70, v59
	v_bitop3_b32 v3, v0, v13, 32 bitop3:0x36
	v_add_u32_e32 v176, v12, v3
	s_waitcnt vmcnt(3) lgkmcnt(1)
	v_mfma_f32_32x32x16_bf16 v[18:33], v[4:7], v[110:113], 0
	ds_read_b128 v[4:7], v176 offset:32768
	v_addc_co_u32_e32 v3, vcc, 0, v57, vcc
	s_movk_i32 s0, 0x6000
	v_lshlrev_b32_e32 v14, 3, v78
	s_waitcnt lgkmcnt(1)
	v_mfma_f32_32x32x16_bf16 v[34:49], v[8:11], v[110:113], 0
	ds_read_b128 v[8:11], v176 offset:36864
	s_waitcnt vmcnt(2) lgkmcnt(1)
	v_mfma_f32_32x32x16_bf16 v[18:33], v[4:7], v[106:109], v[18:33]
	v_add_co_u32_e32 v4, vcc, s0, v56
	s_mov_b32 s0, 0x36386000
	s_nop 0
	v_addc_co_u32_e32 v5, vcc, 0, v57, vcc
	v_bitop3_b32 v6, v0, v13, 64 bitop3:0x36
	global_load_dwordx4 v[60:63], v[2:3], off
	global_load_dwordx4 v[64:67], v[4:5], off
	v_add_co_u32_e32 v2, vcc, s0, v76
	v_add_u32_e32 v178, v12, v6
	s_nop 0
	v_addc_co_u32_e32 v3, vcc, 0, v77, vcc
	global_load_dwordx4 v[68:71], v[2:3], off
	ds_read_b128 v[2:5], v178 offset:32768
	v_and_b32_e32 v6, 0xc0, v59
	v_lshlrev_b32_e32 v7, 1, v58
	s_waitcnt lgkmcnt(1)
	v_mfma_f32_32x32x16_bf16 v[34:49], v[8:11], v[106:109], v[34:49]
	v_and_or_b32 v6, v14, 24, v6
	v_and_b32_e32 v7, 32, v7
	v_and_b32_e32 v8, 0x100, v14
	s_movk_i32 s0, 0x60
	v_or3_b32 v59, v6, v7, v8
	ds_read_b128 v[6:9], v178 offset:36864
	v_add_u32_e32 v171, 0, v59
	s_waitcnt vmcnt(4) lgkmcnt(1)
	v_mfma_f32_32x32x16_bf16 v[18:33], v[2:5], v[102:105], v[18:33]
	v_bitop3_b32 v2, v0, v13, s0 bitop3:0x36
	v_add_u32_e32 v177, v12, v2
	ds_read_b128 v[2:5], v177 offset:32768
	ds_read_b128 v[72:75], v177 offset:36864
	s_mov_b32 s0, 0x8000
	s_waitcnt lgkmcnt(2)
	v_mfma_f32_32x32x16_bf16 v[34:49], v[6:9], v[102:105], v[34:49]
	s_waitcnt vmcnt(3) lgkmcnt(1)
	v_mfma_f32_32x32x16_bf16 v[18:33], v[2:5], v[98:101], v[18:33]
	v_mov_b64_e32 v[2:3], s[8:9]
	v_mov_b64_e32 v[4:5], s[10:11]
	v_mov_b64_e32 v[6:7], s[12:13]
	v_mov_b64_e32 v[8:9], s[14:15]
	v_mov_b64_e32 v[10:11], s[16:17]
	v_mov_b64_e32 v[12:13], s[18:19]
	v_mov_b64_e32 v[14:15], s[20:21]
	s_waitcnt lgkmcnt(0)
	v_mfma_f32_32x32x16_bf16 v[34:49], v[72:75], v[98:101], v[34:49]
	s_nop 2
	v_max_f32_e32 v72, v19, v19
	v_max_f32_e32 v73, v18, v18
	v_max_f32_e32 v72, v73, v72
	v_max3_f32 v72, v72, v20, v21
	v_max3_f32 v72, v72, v22, v23
	v_max3_f32 v72, v72, v24, v25
	v_max3_f32 v72, v72, v26, v27
	v_max3_f32 v72, v72, v28, v29
	v_max3_f32 v72, v72, v30, v31
	v_max3_f32 v72, v72, v32, v33
	v_max3_f32 v72, v72, v34, v35
	v_max3_f32 v72, v72, v36, v37
	v_max3_f32 v72, v72, v38, v39
	v_max3_f32 v72, v72, v40, v41
	v_max3_f32 v72, v72, v42, v43
	v_max3_f32 v72, v72, v44, v45
	v_max3_f32 v72, v72, v46, v47
	v_max3_f32 v72, v72, v48, v49
	v_mov_b32_e32 v73, v72
	s_nop 1
	v_permlane32_swap_b32_e32 v72, v73
	v_max_f32_e32 v73, v73, v73
	v_max_f32_e32 v72, v72, v72
	v_max_f32_e32 v74, v72, v73
	v_add_f32_e32 v72, 0x7149f2ca, v74
	v_cmp_ge_f32_e32 vcc, 0x4138aa3b, v72
	v_add_co_u32_e64 v72, s[0:1], s0, v56
	s_cmp_eq_u64 vcc, exec
	s_nop 0
	v_addc_co_u32_e64 v73, s[0:1], 0, v57, s[0:1]
	s_mov_b32 s0, 0xa000
	s_nop 0
	v_add_co_u32_e64 v56, s[0:1], s0, v56
	global_load_dwordx4 v[114:117], v[72:73], off
	s_nop 0
	v_addc_co_u32_e64 v57, s[0:1], 0, v57, s[0:1]
	s_mov_b32 s0, 0x36388000
	s_nop 0
	v_add_co_u32_e64 v72, s[0:1], s0, v76
	s_cselect_b64 vcc, -1, 0
	s_nop 0
	v_addc_co_u32_e64 v73, s[0:1], 0, v77, s[0:1]
	global_load_dwordx4 v[118:121], v[56:57], off
	global_load_dwordx4 v[122:125], v[72:73], off
	v_max_f32_e32 v56, 0xf149f2ca, v74
	v_cndmask_b32_e32 v142, v56, v239, vcc
	v_sub_f32_e32 v57, 0xf149f2ca, v56
	v_mul_f32_e32 v56, 0xbf800000, v142
	v_fmamk_f32 v18, v18, 0x3f800000, v56
	v_exp_f32_e32 v146, v18
	v_fmamk_f32 v18, v19, 0x3f800000, v56
	v_exp_f32_e32 v148, v18
	v_fmamk_f32 v18, v20, 0x3f800000, v56
	v_exp_f32_e32 v150, v18
	v_fmamk_f32 v18, v21, 0x3f800000, v56
	v_exp_f32_e32 v152, v18
	v_fmamk_f32 v18, v22, 0x3f800000, v56
	v_exp_f32_e32 v162, v18
	v_fmamk_f32 v18, v23, 0x3f800000, v56
	v_exp_f32_e32 v164, v18
	v_fmamk_f32 v18, v24, 0x3f800000, v56
	v_exp_f32_e32 v165, v18
	v_fmamk_f32 v18, v25, 0x3f800000, v56
	v_exp_f32_e32 v186, v18
	v_fmamk_f32 v18, v26, 0x3f800000, v56
	v_mul_f32_e32 v57, 0x3f800000, v57
	v_exp_f32_e32 v144, v18
	v_fmamk_f32 v18, v27, 0x3f800000, v56
	s_add_i32 s2, 0, 0x4000
	v_exp_f32_e32 v57, v57
	v_exp_f32_e32 v145, v18
	v_fmamk_f32 v18, v28, 0x3f800000, v56
	v_add_u32_e32 v169, s2, v59
	s_lshl_b32 s2, s28, 8
	v_exp_f32_e32 v147, v18
	v_fmamk_f32 v18, v29, 0x3f800000, v56
	s_add_u32 s2, s25, s2
	v_exp_f32_e32 v149, v18
	v_fmamk_f32 v18, v30, 0x3f800000, v56
	s_addc_u32 s3, s3, 0
	v_mov_b64_e32 v[16:17], s[22:23]
	v_exp_f32_e32 v151, v18
	v_fmamk_f32 v18, v31, 0x3f800000, v56
	v_lshl_add_u64 v[158:159], s[2:3], 0, v[50:51]
	s_mul_i32 s2, s24, 0x108000
	s_lshl_b32 s8, s28, 7
	v_pk_fma_f32 v[126:127], v[48:49], s[34:35], v[56:57] op_sel_hi:[1,0,0]
	v_pk_fma_f32 v[132:133], v[46:47], s[34:35], v[56:57] op_sel_hi:[1,0,0]
	v_pk_fma_f32 v[136:137], v[44:45], s[34:35], v[56:57] op_sel_hi:[1,0,0]
	v_pk_fma_f32 v[128:129], v[42:43], s[34:35], v[56:57] op_sel_hi:[1,0,0]
	v_pk_fma_f32 v[130:131], v[40:41], s[34:35], v[56:57] op_sel_hi:[1,0,0]
	v_pk_fma_f32 v[134:135], v[38:39], s[34:35], v[56:57] op_sel_hi:[1,0,0]
	v_pk_fma_f32 v[138:139], v[36:37], s[34:35], v[56:57] op_sel_hi:[1,0,0]
	v_pk_fma_f32 v[140:141], v[34:35], s[34:35], v[56:57] op_sel_hi:[1,0,0]
	v_exp_f32_e32 v153, v18
	v_fmamk_f32 v18, v32, 0x3f800000, v56
	v_fmac_f32_e32 v56, 0x3f800000, v33
	s_mul_hi_i32 s3, s24, 0x108000
	s_add_u32 s2, s2, s8
	v_exp_f32_e32 v163, v18
	v_exp_f32_e32 v183, v56
	v_and_b32_e32 v18, 15, v58
	s_addc_u32 s3, s3, 0
	s_waitcnt vmcnt(3)
	v_lshl_or_b32 v158, v18, 4, v158
	v_lshl_add_u64 v[18:19], s[2:3], 0, v[52:53]
	s_waitcnt vmcnt(5)
	ds_write_b128 v172, v[60:63] offset:16384
	s_waitcnt vmcnt(4)
	ds_write_b128 v173, v[64:67] offset:16384
	s_waitcnt vmcnt(3)
	ds_write_b128 v174, v[68:71] offset:40960
	v_cndmask_b32_e64 v179, v57, 1.0, vcc
	v_lshl_add_u64 v[160:161], v[18:19], 0, v[54:55]
	v_mov_b64_e32 v[64:65], v[16:17]
	v_mov_b64_e32 v[48:49], v[16:17]
	v_mov_b64_e32 v[32:33], v[16:17]
	v_cmp_gt_u32_e64 s[0:1], 32, v78
	v_mov_b64_e32 v[62:63], v[14:15]
	v_mov_b64_e32 v[60:61], v[12:13]
	v_mov_b64_e32 v[58:59], v[10:11]
	v_mov_b64_e32 v[56:57], v[8:9]
	v_mov_b64_e32 v[54:55], v[6:7]
	v_mov_b64_e32 v[52:53], v[4:5]
	v_mov_b64_e32 v[50:51], v[2:3]
	v_mov_b64_e32 v[46:47], v[14:15]
	v_mov_b64_e32 v[44:45], v[12:13]
	v_mov_b64_e32 v[42:43], v[10:11]
	v_mov_b64_e32 v[40:41], v[8:9]
	v_mov_b64_e32 v[38:39], v[6:7]
	v_mov_b64_e32 v[36:37], v[4:5]
	v_mov_b64_e32 v[34:35], v[2:3]
	v_mov_b64_e32 v[30:31], v[14:15]
	v_mov_b64_e32 v[28:29], v[12:13]
	v_mov_b64_e32 v[26:27], v[10:11]
	v_mov_b64_e32 v[24:25], v[8:9]
	v_mov_b64_e32 v[22:23], v[6:7]
	v_mov_b64_e32 v[20:21], v[4:5]
	v_mov_b64_e32 v[18:19], v[2:3]
	s_waitcnt lgkmcnt(0)
	s_barrier
; #define SBAR() __builtin_amdgcn_sched_barrier(0)
; #define SLOAD(i, k0) do { sr_[i].vs0 = *reinterpret_cast<const bf16x8*>(&Vh[(long)((k0) + sr) * DV + sc]); sr_[i].vs1 = *reinterpret_cast<const bf16x8*>(&Vh[(long)((k0) + 32 + sr) * DV + sc]); \
;     _Pragma("unroll") for (int _c = 0; _c < NKC; ++_c) sr_[i].ks[_c] = *reinterpret_cast<const bf16x8*>(&Kh[(long)((k0) + krow[_c]) * DQK + kcol[_c]]); } while (0)
; #define SWRITE(b, i) do { *(LAS bf16x8*)(V_lds + (b) * SHM_V + vst0) = sr_[i].vs0; *(LAS bf16x8*)(V_lds + (b) * SHM_V + vst1) = sr_[i].vs1; \
;     _Pragma("unroll") for (int _c = 0; _c < NKC; ++_c) *(LAS bf16x8*)(K_lds + (b) * SHM_K + kswz<DQK>(krow[_c], kcol[_c] * 2)) = sr_[i].ks[_c]; } while (0)
; #define SWAIT() do { if constexpr (SDEPTH == 2) { if constexpr (NKC == 1) asm volatile("s_waitcnt vmcnt(3)" ::: "memory"); else if constexpr (NKC == 2) asm volatile("s_waitcnt vmcnt(4)" ::: "memory"); else asm volatile("s_waitcnt vmcnt(5)" ::: "memory"); } \
;     else asm volatile("s_waitcnt vmcnt(0)" ::: "memory"); } while (0)
; DI void finishSM(f32x16& p0, f32x16& p1, float alpha, float& l_reg, bf16x8& pa0, bf16x8& pa1, bf16x8& pa2, bf16x8& pa3) {
; #pragma unroll
;   for (int r = 0; r < 16; ++r) p1[r] = __builtin_amdgcn_exp2f(p1[r]);
;   float ps = 0;
; #pragma unroll
;   for (int r = 0; r < 16; ++r) ps += p0[r];
; #pragma unroll
;   for (int r = 0; r < 16; ++r) ps += p1[r];
;   { auto rr = __builtin_amdgcn_permlane32_swap(__float_as_uint(ps), __float_as_uint(ps), false, false);
;     ps = __uint_as_float(rr[0]) + __uint_as_float(rr[1]); }
;   l_reg = l_reg * alpha + ps;
;     ...
;   PK4(p0, 0, pa0); PK4(p0, 8, pa1); PK4(p1, 0, pa2); PK4(p1, 8, pa3);
;     ...
; }
; template <int DQK, int SDEPTH, bool OUT_BF16, int QREG = DQK / 16, bool OUT_F16 = false> ...
;     ...
;   SLOAD(SO, KVBLK); if constexpr (SDEPTH == 2) { if (2 < NT) SLOAD(SE, 2 * KVBLK); }
;   SWAIT(); SWRITE(1, SO); __syncthreads();
;   for (int j = 1; j + 1 < NT; j += 2) {
;     SBAR(); QKT(pB0, pB1, K_lds + SHM_K);
;     finishSM(pA0, pA1, alA, l_reg, pa0, pa1, pa2, pa3); SBAR();
;     SLOAD(SO, (j + SDEPTH) * KVBLK); SBAR();
;     pv_d0(o, vb0, pa0, pa1, pa2, pa3); partialSM(pB0, pB1, m_reg, mnB, alB, SCALE);
	v_exp_f32_e32 v140, v140
	v_exp_f32_e32 v141, v141
	v_exp_f32_e32 v138, v138
	v_exp_f32_e32 v139, v139
	v_exp_f32_e32 v134, v134
	v_exp_f32_e32 v135, v135
	v_exp_f32_e32 v130, v130
	v_exp_f32_e32 v131, v131
	v_exp_f32_e32 v128, v128
	v_exp_f32_e32 v129, v129
	v_exp_f32_e32 v136, v136
	v_exp_f32_e32 v137, v137
	v_exp_f32_e32 v132, v132
	v_exp_f32_e32 v133, v133
	v_exp_f32_e32 v126, v126
	v_exp_f32_e32 v127, v127
	v_mov_b32_e32 v206, v142
	v_mul_f32_e32 v205, 0xbf800000, v142
	v_add_f32_e32 v203, v146, v148
	v_add_f32_e32 v203, v150, v203
	v_add_f32_e32 v203, v152, v203
	v_add_f32_e32 v203, v162, v203
	v_add_f32_e32 v203, v164, v203
	v_add_f32_e32 v203, v165, v203
	v_add_f32_e32 v203, v186, v203
	v_add_f32_e32 v203, v144, v203
	v_add_f32_e32 v203, v145, v203
	v_add_f32_e32 v203, v147, v203
	v_add_f32_e32 v203, v149, v203
	v_add_f32_e32 v203, v151, v203
	v_add_f32_e32 v203, v153, v203
	v_add_f32_e32 v203, v163, v203
	v_add_f32_e32 v203, v183, v203
	v_add_f32_e32 v203, v140, v203
	v_add_f32_e32 v203, v141, v203
	v_add_f32_e32 v203, v138, v203
	v_add_f32_e32 v203, v139, v203
	v_add_f32_e32 v203, v134, v203
	v_add_f32_e32 v203, v135, v203
	v_add_f32_e32 v203, v130, v203
	v_add_f32_e32 v203, v131, v203
	v_add_f32_e32 v203, v128, v203
	v_add_f32_e32 v203, v129, v203
	v_add_f32_e32 v203, v136, v203
	v_add_f32_e32 v203, v137, v203
	v_add_f32_e32 v203, v132, v203
	v_add_f32_e32 v203, v133, v203
	v_add_f32_e32 v203, v126, v203
	v_add_f32_e32 v203, v127, v203
	v_cvt_pk_bf16_f32 v66, v146, v148
	v_cvt_pk_bf16_f32 v67, v150, v152
	v_cvt_pk_bf16_f32 v68, v162, v164
	v_cvt_pk_bf16_f32 v69, v165, v186
	v_cvt_pk_bf16_f32 v70, v144, v145
	v_cvt_pk_bf16_f32 v71, v147, v149
	v_cvt_pk_bf16_f32 v72, v151, v153
	v_cvt_pk_bf16_f32 v73, v163, v183
	v_cvt_pk_bf16_f32 v74, v140, v141
	v_cvt_pk_bf16_f32 v75, v138, v139
	v_cvt_pk_bf16_f32 v76, v134, v135
	v_cvt_pk_bf16_f32 v77, v130, v131
	v_cvt_pk_bf16_f32 v78, v128, v129
	v_cvt_pk_bf16_f32 v79, v136, v137
	v_cvt_pk_bf16_f32 v80, v132, v133
	v_cvt_pk_bf16_f32 v81, v126, v127
	s_nop 1
	v_permlane32_swap_b32_e32 v66, v68
	v_permlane32_swap_b32_e32 v67, v69
	v_permlane32_swap_b32_e32 v70, v72
	v_permlane32_swap_b32_e32 v71, v73
	v_permlane32_swap_b32_e32 v74, v76
	v_permlane32_swap_b32_e32 v75, v77
	v_permlane32_swap_b32_e32 v78, v80
	v_permlane32_swap_b32_e32 v79, v81
	v_mov_b32_e32 v138, v66
	v_mov_b32_e32 v139, v67
	v_mov_b32_e32 v140, v68
	v_mov_b32_e32 v141, v69
	v_mov_b32_e32 v144, v70
	v_mov_b32_e32 v145, v71
	v_mov_b32_e32 v146, v72
	v_mov_b32_e32 v147, v73
	v_mov_b32_e32 v148, v74
	v_mov_b32_e32 v149, v75
	v_mov_b32_e32 v150, v76
	v_mov_b32_e32 v151, v77
	v_mov_b32_e32 v162, v78
	v_mov_b32_e32 v163, v79
	v_mov_b32_e32 v164, v80
	v_mov_b32_e32 v165, v81
	v_mov_b32_e32 v170, v203
	v_mov_b32_e32 v214, v205
	v_mov_b32_e32 v215, v205
	v_mov_b32_e32 v216, v205
	v_mov_b32_e32 v217, v205
	v_mov_b32_e32 v218, v205
	v_mov_b32_e32 v219, v205
	v_mov_b32_e32 v220, v205
	v_mov_b32_e32 v221, v205
	v_mov_b32_e32 v222, v205
	v_mov_b32_e32 v223, v205
	v_mov_b32_e32 v224, v205
	v_mov_b32_e32 v225, v205
	v_mov_b32_e32 v226, v205
	v_mov_b32_e32 v227, v205
	v_mov_b32_e32 v228, v205
	v_mov_b32_e32 v229, v205
	s_add_u32 s80, s4, 0x37410000
	s_addc_u32 s81, s5, 0
	s_add_u32 s82, s4, 0x37412000
	s_addc_u32 s83, s5, 0
	s_add_u32 s84, s4, 0x3638a000
	s_addc_u32 s85, s5, 0
	s_add_u32 s86, s4, 0x37414000
	s_addc_u32 s87, s5, 0
	s_add_u32 s88, s4, 0x37416000
	s_addc_u32 s89, s5, 0
	s_add_u32 s90, s4, 0x3638c000
	s_addc_u32 s91, s5, 0
.LBB0_782:
	ds_read_b128 v[66:69], v175 offset:40960
	ds_read_b128 v[70:73], v175 offset:45056
	ds_read_b128 v[188:191], v176 offset:40960
	ds_read_b128 v[192:195], v176 offset:45056
	s_waitcnt lgkmcnt(3)
	v_mfma_f32_32x32x16_bf16 v[82:97], v[66:69], v[110:113], v[214:229]
	s_waitcnt lgkmcnt(2)
	v_mfma_f32_32x32x16_bf16 v[66:81], v[70:73], v[110:113], v[214:229]
	s_waitcnt lgkmcnt(1)
	v_mfma_f32_32x32x16_bf16 v[82:97], v[188:191], v[106:109], v[82:97]
	s_waitcnt lgkmcnt(0)
	v_mfma_f32_32x32x16_bf16 v[66:81], v[192:195], v[106:109], v[66:81]
	ds_read_b128 v[188:191], v178 offset:40960
	ds_read_b128 v[192:195], v178 offset:45056
	s_waitcnt lgkmcnt(1)
	v_mfma_f32_32x32x16_bf16 v[82:97], v[188:191], v[102:105], v[82:97]
	s_waitcnt lgkmcnt(0)
	v_mfma_f32_32x32x16_bf16 v[66:81], v[192:195], v[102:105], v[66:81]
	ds_read_b128 v[188:191], v177 offset:40960
	ds_read_b128 v[192:195], v177 offset:45056
	s_waitcnt lgkmcnt(1)
	v_mfma_f32_32x32x16_bf16 v[82:97], v[188:191], v[98:101], v[82:97]
	s_waitcnt lgkmcnt(0)
	v_mfma_f32_32x32x16_bf16 v[66:81], v[192:195], v[98:101], v[66:81]
	global_load_dwordx4 v[126:129], v158, s[80:81]
	global_load_dwordx4 v[130:133], v158, s[82:83]
	global_load_dwordx4 v[134:137], v160, s[84:85]
	ds_read_b64_tr_b16 v[186:187], v171 offset:0x0
	ds_read_b64_tr_b16 v[188:189], v171 offset:0x800
	ds_read_b64_tr_b16 v[190:191], v171 offset:0x1000
	ds_read_b64_tr_b16 v[192:193], v171 offset:0x1800
	ds_read_b64_tr_b16 v[194:195], v171 offset:0x2000
	ds_read_b64_tr_b16 v[196:197], v171 offset:0x2800
	ds_read_b64_tr_b16 v[198:199], v171 offset:0x3000
	ds_read_b64_tr_b16 v[200:201], v171 offset:0x3800
	s_waitcnt lgkmcnt(0)
; #define SBAR() __builtin_amdgcn_sched_barrier(0)
; template <int OFF> DI s16x4 tr_read(int vb) { s16x4 r; asm volatile("ds_read_b64_tr_b16 %0, %1 offset:%2" : "=&v"(r) : "v"(vb), "i"(OFF) : "memory"); return r; }
; #define SWRITE(b, i) do { *(LAS bf16x8*)(V_lds + (b) * SHM_V + vst0) = sr_[i].vs0; *(LAS bf16x8*)(V_lds + (b) * SHM_V + vst1) = sr_[i].vs1; \
;     _Pragma("unroll") for (int _c = 0; _c < NKC; ++_c) *(LAS bf16x8*)(K_lds + (b) * SHM_K + kswz<DQK>(krow[_c], kcol[_c] * 2)) = sr_[i].ks[_c]; } while (0)
; DI void finishSM(f32x16& p0, f32x16& p1, float alpha, float& l_reg, bf16x8& pa0, bf16x8& pa1, bf16x8& pa2, bf16x8& pa3) {
; #pragma unroll
;   for (int r = 0; r < 16; ++r) p1[r] = __builtin_amdgcn_exp2f(p1[r]);
;   float ps = 0;
; #pragma unroll
;   for (int r = 0; r < 16; ++r) ps += p0[r];
; #pragma unroll
;   for (int r = 0; r < 16; ++r) ps += p1[r];
;   { auto rr = __builtin_amdgcn_permlane32_swap(__float_as_uint(ps), __float_as_uint(ps), false, false);
;     ps = __uint_as_float(rr[0]) + __uint_as_float(rr[1]); }
;   l_reg = l_reg * alpha + ps;
;     ...
;   PK4(p0, 0, pa0); PK4(p0, 8, pa1); PK4(p1, 0, pa2); PK4(p1, 8, pa3);
;     ...
; }
; template <int D0> DI void pv_one(f32x16& od, int vb, bf16x8 pa0, bf16x8 pa1, bf16x8 pa2, bf16x8 pa3) {
;   const s16x4 l0 = tr_read<v_rd_off(D0, 0, 0)>(vb), h0 = tr_read<v_rd_off(D0, 0, 1)>(vb), l1 = tr_read<v_rd_off(D0, 1, 0)>(vb), h1 = tr_read<v_rd_off(D0, 1, 1)>(vb);
;   const s16x4 l2 = tr_read<v_rd_off(D0, 2, 0)>(vb), h2 = tr_read<v_rd_off(D0, 2, 1)>(vb), l3 = tr_read<v_rd_off(D0, 3, 0)>(vb), h3 = tr_read<v_rd_off(D0, 3, 1)>(vb);
;   asm volatile("s_waitcnt lgkmcnt(0)" ::: "memory"); SBAR();
;     ...
;   od = __builtin_amdgcn_mfma_f32_32x32x16_bf16(pa0, PK(l0, h0), od, 0, 0, 0);
;   od = __builtin_amdgcn_mfma_f32_32x32x16_bf16(pa1, PK(l1, h1), od, 0, 0, 0);
;   od = __builtin_amdgcn_mfma_f32_32x32x16_bf16(pa2, PK(l2, h2), od, 0, 0, 0);
;   od = __builtin_amdgcn_mfma_f32_32x32x16_bf16(pa3, PK(l3, h3), od, 0, 0, 0);
;     ...
; }
; DI void pv_d0(f32x16* o, int vb, bf16x8 pa0, bf16x8 pa1, bf16x8 pa2, bf16x8 pa3) {
;   pv_one<0>(o[0], vb, pa0, pa1, pa2, pa3); pv_one<1>(o[1], vb, pa0, pa1, pa2, pa3); pv_one<2>(o[2], vb, pa0, pa1, pa2, pa3); pv_one<3>(o[3], vb, pa0, pa1, pa2, pa3);
; }
; template <int DQK, int SDEPTH, bool OUT_BF16, int QREG = DQK / 16, bool OUT_F16 = false> ...
;     ...
;     __syncthreads(); SWAIT(); SWRITE(0, SE);
	v_mfma_f32_32x32x16_bf16 v[2:17], v[138:141], v[186:189], v[2:17]
	ds_read_b64_tr_b16 v[186:187], v171 offset:0x200
	ds_read_b64_tr_b16 v[188:189], v171 offset:0xa00
	v_exp_f32_e32 v82, v82
	v_exp_f32_e32 v83, v83
	v_exp_f32_e32 v84, v84
	v_exp_f32_e32 v85, v85
	v_exp_f32_e32 v86, v86
	v_add_f32_e32 v180, v82, v83
	v_mfma_f32_32x32x16_bf16 v[2:17], v[144:147], v[190:193], v[2:17]
	ds_read_b64_tr_b16 v[190:191], v171 offset:0x1200
	ds_read_b64_tr_b16 v[192:193], v171 offset:0x1a00
	v_exp_f32_e32 v87, v87
	v_add_f32_e32 v180, v84, v180
	v_exp_f32_e32 v88, v88
	v_add_f32_e32 v180, v85, v180
	v_cvt_pk_bf16_f32 v208, v82, v83
	v_mfma_f32_32x32x16_bf16 v[2:17], v[148:151], v[194:197], v[2:17]
	ds_read_b64_tr_b16 v[194:195], v171 offset:0x2200
	ds_read_b64_tr_b16 v[196:197], v171 offset:0x2a00
	v_exp_f32_e32 v89, v89
	v_add_f32_e32 v180, v86, v180
	v_exp_f32_e32 v90, v90
	v_add_f32_e32 v180, v87, v180
	v_cvt_pk_bf16_f32 v209, v84, v85
	v_exp_f32_e32 v91, v91
	v_mfma_f32_32x32x16_bf16 v[2:17], v[162:165], v[198:201], v[2:17]
	ds_read_b64_tr_b16 v[198:199], v171 offset:0x3200
	ds_read_b64_tr_b16 v[200:201], v171 offset:0x3a00
	v_add_f32_e32 v180, v88, v180
	v_exp_f32_e32 v92, v92
	v_add_f32_e32 v180, v89, v180
	v_cvt_pk_bf16_f32 v210, v86, v87
	v_exp_f32_e32 v93, v93
	s_waitcnt lgkmcnt(0)
	v_mfma_f32_32x32x16_bf16 v[50:65], v[138:141], v[186:189], v[50:65]
	ds_read_b64_tr_b16 v[186:187], v171 offset:0x400
	ds_read_b64_tr_b16 v[188:189], v171 offset:0xc00
	v_add_f32_e32 v180, v90, v180
	v_exp_f32_e32 v94, v94
	v_add_f32_e32 v180, v91, v180
	v_cvt_pk_bf16_f32 v211, v88, v89
	v_exp_f32_e32 v95, v95
	v_add_f32_e32 v180, v92, v180
	v_mfma_f32_32x32x16_bf16 v[50:65], v[144:147], v[190:193], v[50:65]
	ds_read_b64_tr_b16 v[190:191], v171 offset:0x1400
	ds_read_b64_tr_b16 v[192:193], v171 offset:0x1c00
	v_exp_f32_e32 v96, v96
	v_add_f32_e32 v180, v93, v180
	v_cvt_pk_bf16_f32 v244, v90, v91
	v_exp_f32_e32 v97, v97
	v_add_f32_e32 v180, v94, v180
	v_mfma_f32_32x32x16_bf16 v[50:65], v[148:151], v[194:197], v[50:65]
	ds_read_b64_tr_b16 v[194:195], v171 offset:0x2400
	ds_read_b64_tr_b16 v[196:197], v171 offset:0x2c00
	v_exp_f32_e32 v66, v66
	v_add_f32_e32 v180, v95, v180
	v_cvt_pk_bf16_f32 v245, v92, v93
	v_permlane32_swap_b32_e32 v208, v210
	v_exp_f32_e32 v67, v67
	v_add_f32_e32 v180, v96, v180
	v_mfma_f32_32x32x16_bf16 v[50:65], v[162:165], v[198:201], v[50:65]
	ds_read_b64_tr_b16 v[198:199], v171 offset:0x3400
	ds_read_b64_tr_b16 v[200:201], v171 offset:0x3c00
	v_permlane32_swap_b32_e32 v209, v211
	v_exp_f32_e32 v68, v68
	v_add_f32_e32 v180, v97, v180
	v_cvt_pk_bf16_f32 v246, v94, v95
	v_exp_f32_e32 v69, v69
	s_waitcnt lgkmcnt(0)
	v_mfma_f32_32x32x16_bf16 v[34:49], v[138:141], v[186:189], v[34:49]
	ds_read_b64_tr_b16 v[186:187], v171 offset:0x600
	ds_read_b64_tr_b16 v[188:189], v171 offset:0xe00
	v_add_f32_e32 v180, v66, v180
	v_exp_f32_e32 v70, v70
	v_add_f32_e32 v180, v67, v180
	v_cvt_pk_bf16_f32 v247, v96, v97
	v_exp_f32_e32 v71, v71
	v_add_f32_e32 v180, v68, v180
	v_mfma_f32_32x32x16_bf16 v[34:49], v[144:147], v[190:193], v[34:49]
	ds_read_b64_tr_b16 v[190:191], v171 offset:0x1600
	ds_read_b64_tr_b16 v[192:193], v171 offset:0x1e00
	v_exp_f32_e32 v72, v72
	v_add_f32_e32 v180, v69, v180
	v_cvt_pk_bf16_f32 v248, v66, v67
	v_exp_f32_e32 v73, v73
	v_add_f32_e32 v180, v70, v180
	v_exp_f32_e32 v74, v74
	v_mfma_f32_32x32x16_bf16 v[34:49], v[148:151], v[194:197], v[34:49]
	ds_read_b64_tr_b16 v[194:195], v171 offset:0x2600
	ds_read_b64_tr_b16 v[196:197], v171 offset:0x2e00
	v_add_f32_e32 v180, v71, v180
	v_cvt_pk_bf16_f32 v249, v68, v69
	v_permlane32_swap_b32_e32 v244, v246
	v_exp_f32_e32 v75, v75
	v_add_f32_e32 v180, v72, v180
	v_mfma_f32_32x32x16_bf16 v[34:49], v[162:165], v[198:201], v[34:49]
	ds_read_b64_tr_b16 v[198:199], v171 offset:0x3600
	ds_read_b64_tr_b16 v[200:201], v171 offset:0x3e00
	v_permlane32_swap_b32_e32 v245, v247
	v_exp_f32_e32 v76, v76
	v_add_f32_e32 v180, v73, v180
	v_cvt_pk_bf16_f32 v250, v70, v71
	v_exp_f32_e32 v77, v77
	v_add_f32_e32 v180, v74, v180
	s_waitcnt lgkmcnt(0)
	v_mfma_f32_32x32x16_bf16 v[18:33], v[138:141], v[186:189], v[18:33]
	v_exp_f32_e32 v78, v78
	v_add_f32_e32 v180, v75, v180
	v_cvt_pk_bf16_f32 v251, v72, v73
	v_exp_f32_e32 v79, v79
	v_add_f32_e32 v180, v76, v180
	v_mfma_f32_32x32x16_bf16 v[18:33], v[144:147], v[190:193], v[18:33]
	v_exp_f32_e32 v80, v80
	v_add_f32_e32 v180, v77, v180
	v_cvt_pk_bf16_f32 v182, v74, v75
	v_exp_f32_e32 v81, v81
	v_add_f32_e32 v180, v78, v180
	v_add_f32_e32 v180, v79, v180
	v_mfma_f32_32x32x16_bf16 v[18:33], v[148:151], v[194:197], v[18:33]
	v_cvt_pk_bf16_f32 v183, v76, v77
	v_permlane32_swap_b32_e32 v248, v250
	v_add_f32_e32 v180, v80, v180
	v_permlane32_swap_b32_e32 v249, v251
	v_add_f32_e32 v180, v81, v180
	v_mfma_f32_32x32x16_bf16 v[18:33], v[162:165], v[198:201], v[18:33]
	v_cvt_pk_bf16_f32 v184, v78, v79
	v_cvt_pk_bf16_f32 v185, v80, v81
	v_cmp_nge_f32_e32 vcc, 0x453a4f54, v180
	v_add_f32_e32 v207, v170, v180
	v_permlane32_swap_b32_e32 v182, v184
	v_permlane32_swap_b32_e32 v183, v185
	s_barrier
	s_waitcnt vmcnt(3)
	ds_write_b128 v172, v[114:117]
	ds_write_b128 v173, v[118:121]
	ds_write_b128 v174, v[122:125] offset:32768
	s_cbranch_vccz .LBB0_786
; DI void partialSM(f32x16& p0, f32x16& p1, float& m_reg, float& mn, float& alpha, const float SCALE) {
;   const float C = SCALE * 1.4426950408889634f;
;   float pmax = p0[0];
; #pragma unroll
;   for (int r = 1; r < 16; ++r) pmax = fmaxf(pmax, p0[r]);
; #pragma unroll
;   for (int r = 0; r < 16; ++r) pmax = fmaxf(pmax, p1[r]);
;   { auto rr = __builtin_amdgcn_permlane32_swap(__float_as_uint(pmax), __float_as_uint(pmax), false, false);
;     pmax = fmaxf(__uint_as_float(rr[0]), __uint_as_float(rr[1])); }
;   if (__builtin_expect(__all(pmax - m_reg <= THR / SCALE), 1)) { mn = m_reg; alpha = 1.f; }
;   else { mn = fmaxf(m_reg, pmax); alpha = __builtin_amdgcn_exp2f((m_reg - mn) * C); m_reg = mn; }
;   const float mnC = -mn * C;
; #pragma unroll
;   for (int r = 0; r < 16; ++r) p0[r] = fmaf(p0[r], C, mnC);
; #pragma unroll
;   for (int r = 0; r < 16; ++r) p1[r] = fmaf(p1[r], C, mnC);
; #pragma unroll
;   for (int r = 0; r < 16; ++r) p0[r] = __builtin_amdgcn_exp2f(p0[r]);
; }
; DI void finishSM(f32x16& p0, f32x16& p1, float alpha, float& l_reg, bf16x8& pa0, bf16x8& pa1, bf16x8& pa2, bf16x8& pa3) {
; #pragma unroll
;   for (int r = 0; r < 16; ++r) p1[r] = __builtin_amdgcn_exp2f(p1[r]);
;   float ps = 0;
; #pragma unroll
;   for (int r = 0; r < 16; ++r) ps += p0[r];
; #pragma unroll
;   for (int r = 0; r < 16; ++r) ps += p1[r];
;   { auto rr = __builtin_amdgcn_permlane32_swap(__float_as_uint(ps), __float_as_uint(ps), false, false);
;     ps = __uint_as_float(rr[0]) + __uint_as_float(rr[1]); }
;   l_reg = l_reg * alpha + ps;
;     ...
;   PK4(p0, 0, pa0); PK4(p0, 8, pa1); PK4(p1, 0, pa2); PK4(p1, 8, pa3);
;     ...
; }
	ds_read_b128 v[66:69], v175 offset:40960
	ds_read_b128 v[70:73], v175 offset:45056
	ds_read_b128 v[188:191], v176 offset:40960
	ds_read_b128 v[192:195], v176 offset:45056
	s_waitcnt lgkmcnt(3)
	v_mfma_f32_32x32x16_bf16 v[82:97], v[66:69], v[110:113], 0
	s_waitcnt lgkmcnt(2)
	v_mfma_f32_32x32x16_bf16 v[66:81], v[70:73], v[110:113], 0
	s_waitcnt lgkmcnt(1)
	v_mfma_f32_32x32x16_bf16 v[82:97], v[188:191], v[106:109], v[82:97]
	s_waitcnt lgkmcnt(0)
	v_mfma_f32_32x32x16_bf16 v[66:81], v[192:195], v[106:109], v[66:81]
	ds_read_b128 v[188:191], v178 offset:40960
	ds_read_b128 v[192:195], v178 offset:45056
	s_waitcnt lgkmcnt(1)
	v_mfma_f32_32x32x16_bf16 v[82:97], v[188:191], v[102:105], v[82:97]
	s_waitcnt lgkmcnt(0)
	v_mfma_f32_32x32x16_bf16 v[66:81], v[192:195], v[102:105], v[66:81]
	ds_read_b128 v[188:191], v177 offset:40960
	ds_read_b128 v[192:195], v177 offset:45056
	s_waitcnt lgkmcnt(1)
	v_mfma_f32_32x32x16_bf16 v[82:97], v[188:191], v[98:101], v[82:97]
	s_waitcnt lgkmcnt(0)
	v_mfma_f32_32x32x16_bf16 v[66:81], v[192:195], v[98:101], v[66:81]
	s_nop 7
	s_nop 7
	v_max3_f32 v203, v82, v83, v84
	v_max3_f32 v204, v85, v86, v87
	v_max3_f32 v203, v203, v88, v89
	v_max3_f32 v204, v204, v90, v91
	v_max3_f32 v203, v203, v92, v93
	v_max3_f32 v204, v204, v94, v95
	v_max3_f32 v203, v203, v96, v97
	v_max3_f32 v204, v204, v66, v67
	v_max3_f32 v203, v203, v68, v69
	v_max3_f32 v204, v204, v70, v71
	v_max3_f32 v203, v203, v72, v73
	v_max3_f32 v204, v204, v74, v75
	v_max3_f32 v203, v203, v76, v77
	v_max3_f32 v204, v204, v78, v79
	v_max3_f32 v203, v203, v80, v81
	v_max_f32_e32 v203, v203, v204
	v_mov_b32_e32 v204, v203
	s_nop 1
	v_permlane32_swap_b32_e32 v203, v204
	v_max_f32_e32 v203, v203, v204
	v_max_f32_e32 v203, v206, v203
	v_sub_f32_e32 v204, v206, v203
	v_exp_f32_e32 v152, v204
	v_mov_b32_e32 v206, v203
	v_mul_f32_e32 v205, 0xbf800000, v203
	v_mov_b32_e32 v214, v205
	v_mov_b32_e32 v215, v205
	v_mov_b32_e32 v216, v205
	v_mov_b32_e32 v217, v205
	v_mov_b32_e32 v218, v205
	v_mov_b32_e32 v219, v205
	v_mov_b32_e32 v220, v205
	v_mov_b32_e32 v221, v205
	v_mov_b32_e32 v222, v205
	v_mov_b32_e32 v223, v205
	v_mov_b32_e32 v224, v205
	v_mov_b32_e32 v225, v205
	v_mov_b32_e32 v226, v205
	v_mov_b32_e32 v227, v205
	v_mov_b32_e32 v228, v205
	v_mov_b32_e32 v229, v205
	v_add_f32_e32 v82, v205, v82
	v_add_f32_e32 v83, v205, v83
	v_add_f32_e32 v84, v205, v84
	v_add_f32_e32 v85, v205, v85
	v_add_f32_e32 v86, v205, v86
	v_add_f32_e32 v87, v205, v87
	v_add_f32_e32 v88, v205, v88
	v_add_f32_e32 v89, v205, v89
	v_add_f32_e32 v90, v205, v90
	v_add_f32_e32 v91, v205, v91
	v_add_f32_e32 v92, v205, v92
	v_add_f32_e32 v93, v205, v93
	v_add_f32_e32 v94, v205, v94
	v_add_f32_e32 v95, v205, v95
	v_add_f32_e32 v96, v205, v96
	v_add_f32_e32 v97, v205, v97
	v_add_f32_e32 v66, v205, v66
	v_add_f32_e32 v67, v205, v67
	v_add_f32_e32 v68, v205, v68
	v_add_f32_e32 v69, v205, v69
	v_add_f32_e32 v70, v205, v70
	v_add_f32_e32 v71, v205, v71
	v_add_f32_e32 v72, v205, v72
	v_add_f32_e32 v73, v205, v73
	v_add_f32_e32 v74, v205, v74
	v_add_f32_e32 v75, v205, v75
	v_add_f32_e32 v76, v205, v76
	v_add_f32_e32 v77, v205, v77
	v_add_f32_e32 v78, v205, v78
	v_add_f32_e32 v79, v205, v79
	v_add_f32_e32 v80, v205, v80
	v_add_f32_e32 v81, v205, v81
	v_exp_f32_e32 v82, v82
	v_exp_f32_e32 v83, v83
	v_exp_f32_e32 v84, v84
	v_exp_f32_e32 v85, v85
	v_exp_f32_e32 v86, v86
	v_exp_f32_e32 v87, v87
	v_exp_f32_e32 v88, v88
	v_exp_f32_e32 v89, v89
	v_exp_f32_e32 v90, v90
	v_exp_f32_e32 v91, v91
	v_exp_f32_e32 v92, v92
	v_exp_f32_e32 v93, v93
	v_exp_f32_e32 v94, v94
	v_exp_f32_e32 v95, v95
	v_exp_f32_e32 v96, v96
	v_exp_f32_e32 v97, v97
	v_exp_f32_e32 v66, v66
	v_exp_f32_e32 v67, v67
	v_exp_f32_e32 v68, v68
	v_exp_f32_e32 v69, v69
	v_exp_f32_e32 v70, v70
	v_exp_f32_e32 v71, v71
	v_exp_f32_e32 v72, v72
	v_exp_f32_e32 v73, v73
	v_exp_f32_e32 v74, v74
	v_exp_f32_e32 v75, v75
	v_exp_f32_e32 v76, v76
	v_exp_f32_e32 v77, v77
	v_exp_f32_e32 v78, v78
	v_exp_f32_e32 v79, v79
	v_exp_f32_e32 v80, v80
	v_exp_f32_e32 v81, v81
	s_nop 0
	v_add_f32_e32 v180, v82, v83
	v_add_f32_e32 v180, v84, v180
	v_add_f32_e32 v180, v85, v180
	v_add_f32_e32 v180, v86, v180
	v_add_f32_e32 v180, v87, v180
	v_add_f32_e32 v180, v88, v180
	v_add_f32_e32 v180, v89, v180
	v_add_f32_e32 v180, v90, v180
	v_add_f32_e32 v180, v91, v180
	v_add_f32_e32 v180, v92, v180
	v_add_f32_e32 v180, v93, v180
	v_add_f32_e32 v180, v94, v180
	v_add_f32_e32 v180, v95, v180
	v_add_f32_e32 v180, v96, v180
	v_add_f32_e32 v180, v97, v180
	v_add_f32_e32 v180, v66, v180
	v_add_f32_e32 v180, v67, v180
	v_add_f32_e32 v180, v68, v180
	v_add_f32_e32 v180, v69, v180
	v_add_f32_e32 v180, v70, v180
	v_add_f32_e32 v180, v71, v180
	v_add_f32_e32 v180, v72, v180
	v_add_f32_e32 v180, v73, v180
	v_add_f32_e32 v180, v74, v180
	v_add_f32_e32 v180, v75, v180
	v_add_f32_e32 v180, v76, v180
	v_add_f32_e32 v180, v77, v180
	v_add_f32_e32 v180, v78, v180
	v_add_f32_e32 v180, v79, v180
	v_add_f32_e32 v180, v80, v180
	v_add_f32_e32 v180, v81, v180
	v_fma_f32 v207, v152, v170, v180
	v_cvt_pk_bf16_f32 v208, v82, v83
	v_cvt_pk_bf16_f32 v209, v84, v85
	v_cvt_pk_bf16_f32 v210, v86, v87
	v_cvt_pk_bf16_f32 v211, v88, v89
	v_cvt_pk_bf16_f32 v244, v90, v91
	v_cvt_pk_bf16_f32 v245, v92, v93
	v_cvt_pk_bf16_f32 v246, v94, v95
	v_cvt_pk_bf16_f32 v247, v96, v97
	v_cvt_pk_bf16_f32 v248, v66, v67
	v_cvt_pk_bf16_f32 v249, v68, v69
	v_cvt_pk_bf16_f32 v250, v70, v71
	v_cvt_pk_bf16_f32 v251, v72, v73
	v_cvt_pk_bf16_f32 v182, v74, v75
	v_cvt_pk_bf16_f32 v183, v76, v77
	v_cvt_pk_bf16_f32 v184, v78, v79
	v_cvt_pk_bf16_f32 v185, v80, v81
	s_nop 1
	v_permlane32_swap_b32_e32 v208, v210
	v_permlane32_swap_b32_e32 v209, v211
	v_permlane32_swap_b32_e32 v244, v246
	v_permlane32_swap_b32_e32 v245, v247
	v_permlane32_swap_b32_e32 v248, v250
	v_permlane32_swap_b32_e32 v249, v251
	v_permlane32_swap_b32_e32 v182, v184
	v_permlane32_swap_b32_e32 v183, v185
	s_and_saveexec_b64 s[10:11], s[0:1]
	ds_write_b32 v168, v152 offset:49280
	s_or_b64 exec, exec, s[10:11]
	s_waitcnt lgkmcnt(0)
; #define SBAR() __builtin_amdgcn_sched_barrier(0)
; template <int OFF> DI s16x4 tr_read(int vb) { s16x4 r; asm volatile("ds_read_b64_tr_b16 %0, %1 offset:%2" : "=&v"(r) : "v"(vb), "i"(OFF) : "memory"); return r; }
; #define SLOAD(i, k0) do { sr_[i].vs0 = *reinterpret_cast<const bf16x8*>(&Vh[(long)((k0) + sr) * DV + sc]); sr_[i].vs1 = *reinterpret_cast<const bf16x8*>(&Vh[(long)((k0) + 32 + sr) * DV + sc]); \
;     _Pragma("unroll") for (int _c = 0; _c < NKC; ++_c) sr_[i].ks[_c] = *reinterpret_cast<const bf16x8*>(&Kh[(long)((k0) + krow[_c]) * DQK + kcol[_c]]); } while (0)
; template <int D0> DI void pv_one(f32x16& od, int vb, bf16x8 pa0, bf16x8 pa1, bf16x8 pa2, bf16x8 pa3) {
;   const s16x4 l0 = tr_read<v_rd_off(D0, 0, 0)>(vb), h0 = tr_read<v_rd_off(D0, 0, 1)>(vb), l1 = tr_read<v_rd_off(D0, 1, 0)>(vb), h1 = tr_read<v_rd_off(D0, 1, 1)>(vb);
;   const s16x4 l2 = tr_read<v_rd_off(D0, 2, 0)>(vb), h2 = tr_read<v_rd_off(D0, 2, 1)>(vb), l3 = tr_read<v_rd_off(D0, 3, 0)>(vb), h3 = tr_read<v_rd_off(D0, 3, 1)>(vb);
;   asm volatile("s_waitcnt lgkmcnt(0)" ::: "memory"); SBAR();
;     ...
;   od = __builtin_amdgcn_mfma_f32_32x32x16_bf16(pa0, PK(l0, h0), od, 0, 0, 0);
;   od = __builtin_amdgcn_mfma_f32_32x32x16_bf16(pa1, PK(l1, h1), od, 0, 0, 0);
;   od = __builtin_amdgcn_mfma_f32_32x32x16_bf16(pa2, PK(l2, h2), od, 0, 0, 0);
;   od = __builtin_amdgcn_mfma_f32_32x32x16_bf16(pa3, PK(l3, h3), od, 0, 0, 0);
;     ...
; }
; DI void pv_d0(f32x16* o, int vb, bf16x8 pa0, bf16x8 pa1, bf16x8 pa2, bf16x8 pa3) {
;   pv_one<0>(o[0], vb, pa0, pa1, pa2, pa3); pv_one<1>(o[1], vb, pa0, pa1, pa2, pa3); pv_one<2>(o[2], vb, pa0, pa1, pa2, pa3); pv_one<3>(o[3], vb, pa0, pa1, pa2, pa3);
; }
; template <int DQK, int SDEPTH, bool OUT_BF16, int QREG = DQK / 16, bool OUT_F16 = false> ...
;     ...
;     SBAR(); QKT(pA0, pA1, K_lds);
;     finishSM(pB0, pB1, alB, l_reg, pa0, pa1, pa2, pa3); SBAR();
;     if (SDEPTH == 1 || j + 3 < NT) SLOAD(SE, (j + 1 + SDEPTH) * KVBLK); SBAR();
;     pv_d0(o, vb0 + SHM_V, pa0, pa1, pa2, pa3); partialSM(pA0, pA1, m_reg, mnA, alA, SCALE);
	v_add_u32_e32 v179, v157, v0
	ds_read_b128 v[186:189], v179 offset:49376
	ds_read_b128 v[190:193], v179 offset:49344
	ds_read_b128 v[194:197], v179 offset:49312
	ds_read_b128 v[198:201], v179 offset:49280
	s_waitcnt lgkmcnt(3)
	v_pk_mul_f32 v[14:15], v[14:15], v[186:187]
	s_waitcnt lgkmcnt(2)
	v_pk_mul_f32 v[10:11], v[10:11], v[190:191]
	s_waitcnt lgkmcnt(1)
	v_pk_mul_f32 v[6:7], v[6:7], v[194:195]
	v_pk_mul_f32 v[16:17], v[16:17], v[188:189]
	v_pk_mul_f32 v[12:13], v[12:13], v[192:193]
	v_pk_mul_f32 v[8:9], v[8:9], v[196:197]
	s_waitcnt lgkmcnt(0)
	v_pk_mul_f32 v[4:5], v[4:5], v[200:201]
	v_pk_mul_f32 v[2:3], v[2:3], v[198:199]
	v_pk_mul_f32 v[62:63], v[62:63], v[186:187]
	v_pk_mul_f32 v[58:59], v[58:59], v[190:191]
	v_pk_mul_f32 v[54:55], v[54:55], v[194:195]
	v_pk_mul_f32 v[64:65], v[64:65], v[188:189]
	v_pk_mul_f32 v[60:61], v[60:61], v[192:193]
	v_pk_mul_f32 v[56:57], v[56:57], v[196:197]
	v_pk_mul_f32 v[52:53], v[52:53], v[200:201]
	v_pk_mul_f32 v[50:51], v[50:51], v[198:199]
	v_pk_mul_f32 v[46:47], v[46:47], v[186:187]
	v_pk_mul_f32 v[42:43], v[42:43], v[190:191]
	v_pk_mul_f32 v[38:39], v[38:39], v[194:195]
	v_pk_mul_f32 v[48:49], v[48:49], v[188:189]
	v_pk_mul_f32 v[44:45], v[44:45], v[192:193]
	v_pk_mul_f32 v[40:41], v[40:41], v[196:197]
	v_pk_mul_f32 v[36:37], v[36:37], v[200:201]
	v_pk_mul_f32 v[34:35], v[34:35], v[198:199]
	v_pk_mul_f32 v[30:31], v[30:31], v[186:187]
	v_pk_mul_f32 v[26:27], v[26:27], v[190:191]
	v_pk_mul_f32 v[22:23], v[22:23], v[194:195]
	v_pk_mul_f32 v[32:33], v[32:33], v[188:189]
	v_pk_mul_f32 v[28:29], v[28:29], v[192:193]
	v_pk_mul_f32 v[24:25], v[24:25], v[196:197]
	v_pk_mul_f32 v[20:21], v[20:21], v[200:201]
	v_pk_mul_f32 v[18:19], v[18:19], v[198:199]
.LBB0_786:
	s_waitcnt lgkmcnt(0)
	s_barrier
	ds_read_b128 v[66:69], v175 offset:32768
	ds_read_b128 v[70:73], v175 offset:36864
	ds_read_b128 v[188:191], v176 offset:32768
	ds_read_b128 v[192:195], v176 offset:36864
	s_waitcnt lgkmcnt(3)
	v_mfma_f32_32x32x16_bf16 v[82:97], v[66:69], v[110:113], v[214:229]
	s_waitcnt lgkmcnt(2)
	v_mfma_f32_32x32x16_bf16 v[66:81], v[70:73], v[110:113], v[214:229]
	s_waitcnt lgkmcnt(1)
	v_mfma_f32_32x32x16_bf16 v[82:97], v[188:191], v[106:109], v[82:97]
	s_waitcnt lgkmcnt(0)
	v_mfma_f32_32x32x16_bf16 v[66:81], v[192:195], v[106:109], v[66:81]
	ds_read_b128 v[188:191], v178 offset:32768
	ds_read_b128 v[192:195], v178 offset:36864
	s_waitcnt lgkmcnt(1)
	v_mfma_f32_32x32x16_bf16 v[82:97], v[188:191], v[102:105], v[82:97]
	s_waitcnt lgkmcnt(0)
	v_mfma_f32_32x32x16_bf16 v[66:81], v[192:195], v[102:105], v[66:81]
	ds_read_b128 v[188:191], v177 offset:32768
	ds_read_b128 v[192:195], v177 offset:36864
	s_waitcnt lgkmcnt(1)
	v_mfma_f32_32x32x16_bf16 v[82:97], v[188:191], v[98:101], v[82:97]
	s_waitcnt lgkmcnt(0)
	v_mfma_f32_32x32x16_bf16 v[66:81], v[192:195], v[98:101], v[66:81]
	s_cmp_le_u32 s7, s46
	s_cselect_b64 s[2:3], -1, 0
	s_or_b64 s[10:11], s[42:43], s[2:3]
	s_and_b64 vcc, exec, s[10:11]
	s_cbranch_vccnz .LBB0_788
	global_load_dwordx4 v[114:117], v158, s[86:87]
	global_load_dwordx4 v[118:121], v158, s[88:89]
	global_load_dwordx4 v[122:125], v160, s[90:91]
.LBB0_788:
	ds_read_b64_tr_b16 v[186:187], v169 offset:0x0
	ds_read_b64_tr_b16 v[188:189], v169 offset:0x800
	ds_read_b64_tr_b16 v[190:191], v169 offset:0x1000
	ds_read_b64_tr_b16 v[192:193], v169 offset:0x1800
	ds_read_b64_tr_b16 v[194:195], v169 offset:0x2000
	ds_read_b64_tr_b16 v[196:197], v169 offset:0x2800
	ds_read_b64_tr_b16 v[198:199], v169 offset:0x3000
	ds_read_b64_tr_b16 v[200:201], v169 offset:0x3800
	s_waitcnt lgkmcnt(0)
	v_mfma_f32_32x32x16_bf16 v[2:17], v[208:211], v[186:189], v[2:17]
	ds_read_b64_tr_b16 v[186:187], v169 offset:0x200
	ds_read_b64_tr_b16 v[188:189], v169 offset:0xa00
	v_exp_f32_e32 v82, v82
	v_exp_f32_e32 v83, v83
	v_exp_f32_e32 v84, v84
	v_exp_f32_e32 v85, v85
	v_exp_f32_e32 v86, v86
	v_add_f32_e32 v180, v82, v83
	v_mfma_f32_32x32x16_bf16 v[2:17], v[244:247], v[190:193], v[2:17]
	ds_read_b64_tr_b16 v[190:191], v169 offset:0x1200
	ds_read_b64_tr_b16 v[192:193], v169 offset:0x1a00
	v_exp_f32_e32 v87, v87
	v_add_f32_e32 v180, v84, v180
	v_exp_f32_e32 v88, v88
	v_add_f32_e32 v180, v85, v180
	v_cvt_pk_bf16_f32 v138, v82, v83
	v_mfma_f32_32x32x16_bf16 v[2:17], v[248:251], v[194:197], v[2:17]
	ds_read_b64_tr_b16 v[194:195], v169 offset:0x2200
	ds_read_b64_tr_b16 v[196:197], v169 offset:0x2a00
	v_exp_f32_e32 v89, v89
	v_add_f32_e32 v180, v86, v180
	v_exp_f32_e32 v90, v90
	v_add_f32_e32 v180, v87, v180
	v_cvt_pk_bf16_f32 v139, v84, v85
	v_exp_f32_e32 v91, v91
	v_mfma_f32_32x32x16_bf16 v[2:17], v[182:185], v[198:201], v[2:17]
	ds_read_b64_tr_b16 v[198:199], v169 offset:0x3200
	ds_read_b64_tr_b16 v[200:201], v169 offset:0x3a00
	v_add_f32_e32 v180, v88, v180
	v_exp_f32_e32 v92, v92
	v_add_f32_e32 v180, v89, v180
	v_cvt_pk_bf16_f32 v140, v86, v87
	v_exp_f32_e32 v93, v93
	s_waitcnt lgkmcnt(0)
	v_mfma_f32_32x32x16_bf16 v[50:65], v[208:211], v[186:189], v[50:65]
	ds_read_b64_tr_b16 v[186:187], v169 offset:0x400
	ds_read_b64_tr_b16 v[188:189], v169 offset:0xc00
	v_add_f32_e32 v180, v90, v180
	v_exp_f32_e32 v94, v94
	v_add_f32_e32 v180, v91, v180
	v_cvt_pk_bf16_f32 v141, v88, v89
	v_exp_f32_e32 v95, v95
	v_add_f32_e32 v180, v92, v180
	v_mfma_f32_32x32x16_bf16 v[50:65], v[244:247], v[190:193], v[50:65]
	ds_read_b64_tr_b16 v[190:191], v169 offset:0x1400
	ds_read_b64_tr_b16 v[192:193], v169 offset:0x1c00
	v_exp_f32_e32 v96, v96
	v_add_f32_e32 v180, v93, v180
	v_cvt_pk_bf16_f32 v144, v90, v91
	v_exp_f32_e32 v97, v97
	v_add_f32_e32 v180, v94, v180
	v_mfma_f32_32x32x16_bf16 v[50:65], v[248:251], v[194:197], v[50:65]
	ds_read_b64_tr_b16 v[194:195], v169 offset:0x2400
	ds_read_b64_tr_b16 v[196:197], v169 offset:0x2c00
	v_exp_f32_e32 v66, v66
	v_add_f32_e32 v180, v95, v180
	v_cvt_pk_bf16_f32 v145, v92, v93
	v_permlane32_swap_b32_e32 v138, v140
	v_exp_f32_e32 v67, v67
	v_add_f32_e32 v180, v96, v180
	v_mfma_f32_32x32x16_bf16 v[50:65], v[182:185], v[198:201], v[50:65]
	ds_read_b64_tr_b16 v[198:199], v169 offset:0x3400
	ds_read_b64_tr_b16 v[200:201], v169 offset:0x3c00
	v_permlane32_swap_b32_e32 v139, v141
	v_exp_f32_e32 v68, v68
	v_add_f32_e32 v180, v97, v180
	v_cvt_pk_bf16_f32 v146, v94, v95
	v_exp_f32_e32 v69, v69
	s_waitcnt lgkmcnt(0)
; #define SBAR() __builtin_amdgcn_sched_barrier(0)
; template <int OFF> DI s16x4 tr_read(int vb) { s16x4 r; asm volatile("ds_read_b64_tr_b16 %0, %1 offset:%2" : "=&v"(r) : "v"(vb), "i"(OFF) : "memory"); return r; }
; #define SWRITE(b, i) do { *(LAS bf16x8*)(V_lds + (b) * SHM_V + vst0) = sr_[i].vs0; *(LAS bf16x8*)(V_lds + (b) * SHM_V + vst1) = sr_[i].vs1; \
;     _Pragma("unroll") for (int _c = 0; _c < NKC; ++_c) *(LAS bf16x8*)(K_lds + (b) * SHM_K + kswz<DQK>(krow[_c], kcol[_c] * 2)) = sr_[i].ks[_c]; } while (0)
; #define SWAIT() do { if constexpr (SDEPTH == 2) { if constexpr (NKC == 1) asm volatile("s_waitcnt vmcnt(3)" ::: "memory"); else if constexpr (NKC == 2) asm volatile("s_waitcnt vmcnt(4)" ::: "memory"); else asm volatile("s_waitcnt vmcnt(5)" ::: "memory"); } \
;     else asm volatile("s_waitcnt vmcnt(0)" ::: "memory"); } while (0)
; template <int D0> DI void pv_one(f32x16& od, int vb, bf16x8 pa0, bf16x8 pa1, bf16x8 pa2, bf16x8 pa3) {
;   const s16x4 l0 = tr_read<v_rd_off(D0, 0, 0)>(vb), h0 = tr_read<v_rd_off(D0, 0, 1)>(vb), l1 = tr_read<v_rd_off(D0, 1, 0)>(vb), h1 = tr_read<v_rd_off(D0, 1, 1)>(vb);
;   const s16x4 l2 = tr_read<v_rd_off(D0, 2, 0)>(vb), h2 = tr_read<v_rd_off(D0, 2, 1)>(vb), l3 = tr_read<v_rd_off(D0, 3, 0)>(vb), h3 = tr_read<v_rd_off(D0, 3, 1)>(vb);
;   asm volatile("s_waitcnt lgkmcnt(0)" ::: "memory"); SBAR();
;     ...
;   od = __builtin_amdgcn_mfma_f32_32x32x16_bf16(pa0, PK(l0, h0), od, 0, 0, 0);
;   od = __builtin_amdgcn_mfma_f32_32x32x16_bf16(pa1, PK(l1, h1), od, 0, 0, 0);
;   od = __builtin_amdgcn_mfma_f32_32x32x16_bf16(pa2, PK(l2, h2), od, 0, 0, 0);
;   od = __builtin_amdgcn_mfma_f32_32x32x16_bf16(pa3, PK(l3, h3), od, 0, 0, 0);
;     ...
; }
; DI void pv_d0(f32x16* o, int vb, bf16x8 pa0, bf16x8 pa1, bf16x8 pa2, bf16x8 pa3) {
;   pv_one<0>(o[0], vb, pa0, pa1, pa2, pa3); pv_one<1>(o[1], vb, pa0, pa1, pa2, pa3); pv_one<2>(o[2], vb, pa0, pa1, pa2, pa3); pv_one<3>(o[3], vb, pa0, pa1, pa2, pa3);
; }
; template <int DQK, int SDEPTH, bool OUT_BF16, int QREG = DQK / 16, bool OUT_F16 = false> ...
;     ...
;     pv_d0(o, vb0 + SHM_V, pa0, pa1, pa2, pa3); partialSM(pA0, pA1, m_reg, mnA, alA, SCALE);
;     __syncthreads(); SWAIT(); SWRITE(1, SO);
;     RESC(alA); __syncthreads();
	v_mfma_f32_32x32x16_bf16 v[34:49], v[208:211], v[186:189], v[34:49]
	ds_read_b64_tr_b16 v[186:187], v169 offset:0x600
	ds_read_b64_tr_b16 v[188:189], v169 offset:0xe00
	v_add_f32_e32 v180, v66, v180
	v_exp_f32_e32 v70, v70
	v_add_f32_e32 v180, v67, v180
	v_cvt_pk_bf16_f32 v147, v96, v97
	v_exp_f32_e32 v71, v71
	v_add_f32_e32 v180, v68, v180
	v_mfma_f32_32x32x16_bf16 v[34:49], v[244:247], v[190:193], v[34:49]
	ds_read_b64_tr_b16 v[190:191], v169 offset:0x1600
	ds_read_b64_tr_b16 v[192:193], v169 offset:0x1e00
	v_exp_f32_e32 v72, v72
	v_add_f32_e32 v180, v69, v180
	v_cvt_pk_bf16_f32 v148, v66, v67
	v_exp_f32_e32 v73, v73
	v_add_f32_e32 v180, v70, v180
	v_exp_f32_e32 v74, v74
	v_mfma_f32_32x32x16_bf16 v[34:49], v[248:251], v[194:197], v[34:49]
	ds_read_b64_tr_b16 v[194:195], v169 offset:0x2600
	ds_read_b64_tr_b16 v[196:197], v169 offset:0x2e00
	v_add_f32_e32 v180, v71, v180
	v_cvt_pk_bf16_f32 v149, v68, v69
	v_permlane32_swap_b32_e32 v144, v146
	v_exp_f32_e32 v75, v75
	v_add_f32_e32 v180, v72, v180
	v_mfma_f32_32x32x16_bf16 v[34:49], v[182:185], v[198:201], v[34:49]
	ds_read_b64_tr_b16 v[198:199], v169 offset:0x3600
	ds_read_b64_tr_b16 v[200:201], v169 offset:0x3e00
	v_permlane32_swap_b32_e32 v145, v147
	v_exp_f32_e32 v76, v76
	v_add_f32_e32 v180, v73, v180
	v_cvt_pk_bf16_f32 v150, v70, v71
	v_exp_f32_e32 v77, v77
	v_add_f32_e32 v180, v74, v180
	s_waitcnt lgkmcnt(0)
	v_mfma_f32_32x32x16_bf16 v[18:33], v[208:211], v[186:189], v[18:33]
	v_exp_f32_e32 v78, v78
	v_add_f32_e32 v180, v75, v180
	v_cvt_pk_bf16_f32 v151, v72, v73
	v_exp_f32_e32 v79, v79
	v_add_f32_e32 v180, v76, v180
	v_mfma_f32_32x32x16_bf16 v[18:33], v[244:247], v[190:193], v[18:33]
	v_exp_f32_e32 v80, v80
	v_add_f32_e32 v180, v77, v180
	v_cvt_pk_bf16_f32 v162, v74, v75
	v_exp_f32_e32 v81, v81
	v_add_f32_e32 v180, v78, v180
	v_add_f32_e32 v180, v79, v180
	v_mfma_f32_32x32x16_bf16 v[18:33], v[248:251], v[194:197], v[18:33]
	v_cvt_pk_bf16_f32 v163, v76, v77
	v_permlane32_swap_b32_e32 v148, v150
	v_add_f32_e32 v180, v80, v180
	v_permlane32_swap_b32_e32 v149, v151
	v_add_f32_e32 v180, v81, v180
	v_mfma_f32_32x32x16_bf16 v[18:33], v[182:185], v[198:201], v[18:33]
	v_cvt_pk_bf16_f32 v164, v78, v79
	v_cvt_pk_bf16_f32 v165, v80, v81
	v_cmp_nge_f32_e32 vcc, 0x453a4f54, v180
	v_add_f32_e32 v170, v207, v180
	v_permlane32_swap_b32_e32 v162, v164
	v_permlane32_swap_b32_e32 v163, v165
	v_mov_b32_e32 v143, 1.0
	s_barrier
	s_waitcnt vmcnt(3)
	s_waitcnt vmcnt(2)
	ds_write_b128 v172, v[126:129] offset:16384
	s_waitcnt vmcnt(1)
	ds_write_b128 v173, v[130:133] offset:16384
	s_waitcnt vmcnt(0)
	ds_write_b128 v174, v[134:137] offset:40960
	s_cbranch_vccz .LBB0_792
	ds_read_b128 v[66:69], v175 offset:32768
	ds_read_b128 v[70:73], v175 offset:36864
	ds_read_b128 v[188:191], v176 offset:32768
	ds_read_b128 v[192:195], v176 offset:36864
	s_waitcnt lgkmcnt(3)
	v_mfma_f32_32x32x16_bf16 v[82:97], v[66:69], v[110:113], 0
	s_waitcnt lgkmcnt(2)
	v_mfma_f32_32x32x16_bf16 v[66:81], v[70:73], v[110:113], 0
	s_waitcnt lgkmcnt(1)
	v_mfma_f32_32x32x16_bf16 v[82:97], v[188:191], v[106:109], v[82:97]
	s_waitcnt lgkmcnt(0)
	v_mfma_f32_32x32x16_bf16 v[66:81], v[192:195], v[106:109], v[66:81]
	ds_read_b128 v[188:191], v178 offset:32768
	ds_read_b128 v[192:195], v178 offset:36864
	s_waitcnt lgkmcnt(1)
	v_mfma_f32_32x32x16_bf16 v[82:97], v[188:191], v[102:105], v[82:97]
	s_waitcnt lgkmcnt(0)
	v_mfma_f32_32x32x16_bf16 v[66:81], v[192:195], v[102:105], v[66:81]
	ds_read_b128 v[188:191], v177 offset:32768
	ds_read_b128 v[192:195], v177 offset:36864
	s_waitcnt lgkmcnt(1)
	v_mfma_f32_32x32x16_bf16 v[82:97], v[188:191], v[98:101], v[82:97]
	s_waitcnt lgkmcnt(0)
; DI void partialSM(f32x16& p0, f32x16& p1, float& m_reg, float& mn, float& alpha, const float SCALE) {
;   const float C = SCALE * 1.4426950408889634f;
;   float pmax = p0[0];
; #pragma unroll
;   for (int r = 1; r < 16; ++r) pmax = fmaxf(pmax, p0[r]);
; #pragma unroll
;   for (int r = 0; r < 16; ++r) pmax = fmaxf(pmax, p1[r]);
;   { auto rr = __builtin_amdgcn_permlane32_swap(__float_as_uint(pmax), __float_as_uint(pmax), false, false);
;     pmax = fmaxf(__uint_as_float(rr[0]), __uint_as_float(rr[1])); }
;   if (__builtin_expect(__all(pmax - m_reg <= THR / SCALE), 1)) { mn = m_reg; alpha = 1.f; }
;   else { mn = fmaxf(m_reg, pmax); alpha = __builtin_amdgcn_exp2f((m_reg - mn) * C); m_reg = mn; }
;   const float mnC = -mn * C;
; #pragma unroll
;   for (int r = 0; r < 16; ++r) p0[r] = fmaf(p0[r], C, mnC);
; #pragma unroll
;   for (int r = 0; r < 16; ++r) p1[r] = fmaf(p1[r], C, mnC);
; #pragma unroll
;   for (int r = 0; r < 16; ++r) p0[r] = __builtin_amdgcn_exp2f(p0[r]);
; }
; DI void finishSM(f32x16& p0, f32x16& p1, float alpha, float& l_reg, bf16x8& pa0, bf16x8& pa1, bf16x8& pa2, bf16x8& pa3) {
; #pragma unroll
;   for (int r = 0; r < 16; ++r) p1[r] = __builtin_amdgcn_exp2f(p1[r]);
;   float ps = 0;
; #pragma unroll
;   for (int r = 0; r < 16; ++r) ps += p0[r];
; #pragma unroll
;   for (int r = 0; r < 16; ++r) ps += p1[r];
;   { auto rr = __builtin_amdgcn_permlane32_swap(__float_as_uint(ps), __float_as_uint(ps), false, false);
;     ps = __uint_as_float(rr[0]) + __uint_as_float(rr[1]); }
;   l_reg = l_reg * alpha + ps;
;     ...
;   PK4(p0, 0, pa0); PK4(p0, 8, pa1); PK4(p1, 0, pa2); PK4(p1, 8, pa3);
;     ...
; }
	v_mfma_f32_32x32x16_bf16 v[66:81], v[192:195], v[98:101], v[66:81]
	s_nop 7
	s_nop 7
	v_max3_f32 v203, v82, v83, v84
	v_max3_f32 v204, v85, v86, v87
	v_max3_f32 v203, v203, v88, v89
	v_max3_f32 v204, v204, v90, v91
	v_max3_f32 v203, v203, v92, v93
	v_max3_f32 v204, v204, v94, v95
	v_max3_f32 v203, v203, v96, v97
	v_max3_f32 v204, v204, v66, v67
	v_max3_f32 v203, v203, v68, v69
	v_max3_f32 v204, v204, v70, v71
	v_max3_f32 v203, v203, v72, v73
	v_max3_f32 v204, v204, v74, v75
	v_max3_f32 v203, v203, v76, v77
	v_max3_f32 v204, v204, v78, v79
	v_max3_f32 v203, v203, v80, v81
	v_max_f32_e32 v203, v203, v204
	v_mov_b32_e32 v204, v203
	s_nop 1
	v_permlane32_swap_b32_e32 v203, v204
	v_max_f32_e32 v203, v203, v204
	v_max_f32_e32 v203, v206, v203
	v_sub_f32_e32 v204, v206, v203
	v_exp_f32_e32 v143, v204
	v_mov_b32_e32 v206, v203
	v_mul_f32_e32 v205, 0xbf800000, v203
	v_mov_b32_e32 v214, v205
	v_mov_b32_e32 v215, v205
	v_mov_b32_e32 v216, v205
	v_mov_b32_e32 v217, v205
	v_mov_b32_e32 v218, v205
	v_mov_b32_e32 v219, v205
	v_mov_b32_e32 v220, v205
	v_mov_b32_e32 v221, v205
	v_mov_b32_e32 v222, v205
	v_mov_b32_e32 v223, v205
	v_mov_b32_e32 v224, v205
	v_mov_b32_e32 v225, v205
	v_mov_b32_e32 v226, v205
	v_mov_b32_e32 v227, v205
	v_mov_b32_e32 v228, v205
	v_mov_b32_e32 v229, v205
	v_add_f32_e32 v82, v205, v82
	v_add_f32_e32 v83, v205, v83
	v_add_f32_e32 v84, v205, v84
	v_add_f32_e32 v85, v205, v85
	v_add_f32_e32 v86, v205, v86
	v_add_f32_e32 v87, v205, v87
	v_add_f32_e32 v88, v205, v88
	v_add_f32_e32 v89, v205, v89
	v_add_f32_e32 v90, v205, v90
	v_add_f32_e32 v91, v205, v91
	v_add_f32_e32 v92, v205, v92
	v_add_f32_e32 v93, v205, v93
	v_add_f32_e32 v94, v205, v94
	v_add_f32_e32 v95, v205, v95
	v_add_f32_e32 v96, v205, v96
	v_add_f32_e32 v97, v205, v97
	v_add_f32_e32 v66, v205, v66
	v_add_f32_e32 v67, v205, v67
	v_add_f32_e32 v68, v205, v68
	v_add_f32_e32 v69, v205, v69
	v_add_f32_e32 v70, v205, v70
	v_add_f32_e32 v71, v205, v71
	v_add_f32_e32 v72, v205, v72
	v_add_f32_e32 v73, v205, v73
	v_add_f32_e32 v74, v205, v74
	v_add_f32_e32 v75, v205, v75
	v_add_f32_e32 v76, v205, v76
	v_add_f32_e32 v77, v205, v77
	v_add_f32_e32 v78, v205, v78
	v_add_f32_e32 v79, v205, v79
	v_add_f32_e32 v80, v205, v80
	v_add_f32_e32 v81, v205, v81
	v_exp_f32_e32 v82, v82
	v_exp_f32_e32 v83, v83
	v_exp_f32_e32 v84, v84
	v_exp_f32_e32 v85, v85
	v_exp_f32_e32 v86, v86
	v_exp_f32_e32 v87, v87
	v_exp_f32_e32 v88, v88
	v_exp_f32_e32 v89, v89
	v_exp_f32_e32 v90, v90
	v_exp_f32_e32 v91, v91
	v_exp_f32_e32 v92, v92
	v_exp_f32_e32 v93, v93
	v_exp_f32_e32 v94, v94
	v_exp_f32_e32 v95, v95
	v_exp_f32_e32 v96, v96
	v_exp_f32_e32 v97, v97
	v_exp_f32_e32 v66, v66
	v_exp_f32_e32 v67, v67
	v_exp_f32_e32 v68, v68
	v_exp_f32_e32 v69, v69
	v_exp_f32_e32 v70, v70
	v_exp_f32_e32 v71, v71
	v_exp_f32_e32 v72, v72
	v_exp_f32_e32 v73, v73
	v_exp_f32_e32 v74, v74
	v_exp_f32_e32 v75, v75
	v_exp_f32_e32 v76, v76
	v_exp_f32_e32 v77, v77
	v_exp_f32_e32 v78, v78
	v_exp_f32_e32 v79, v79
	v_exp_f32_e32 v80, v80
	v_exp_f32_e32 v81, v81
	s_nop 0
	v_add_f32_e32 v180, v82, v83
	v_add_f32_e32 v180, v84, v180
	v_add_f32_e32 v180, v85, v180
	v_add_f32_e32 v180, v86, v180
	v_add_f32_e32 v180, v87, v180
	v_add_f32_e32 v180, v88, v180
	v_add_f32_e32 v180, v89, v180
	v_add_f32_e32 v180, v90, v180
	v_add_f32_e32 v180, v91, v180
	v_add_f32_e32 v180, v92, v180
	v_add_f32_e32 v180, v93, v180
	v_add_f32_e32 v180, v94, v180
	v_add_f32_e32 v180, v95, v180
	v_add_f32_e32 v180, v96, v180
	v_add_f32_e32 v180, v97, v180
	v_add_f32_e32 v180, v66, v180
	v_add_f32_e32 v180, v67, v180
	v_add_f32_e32 v180, v68, v180
	v_add_f32_e32 v180, v69, v180
	v_add_f32_e32 v180, v70, v180
	v_add_f32_e32 v180, v71, v180
	v_add_f32_e32 v180, v72, v180
	v_add_f32_e32 v180, v73, v180
	v_add_f32_e32 v180, v74, v180
	v_add_f32_e32 v180, v75, v180
	v_add_f32_e32 v180, v76, v180
	v_add_f32_e32 v180, v77, v180
	v_add_f32_e32 v180, v78, v180
	v_add_f32_e32 v180, v79, v180
	v_add_f32_e32 v180, v80, v180
	v_add_f32_e32 v180, v81, v180
	v_fma_f32 v170, v143, v207, v180
	v_cvt_pk_bf16_f32 v138, v82, v83
	v_cvt_pk_bf16_f32 v139, v84, v85
	v_cvt_pk_bf16_f32 v140, v86, v87
	v_cvt_pk_bf16_f32 v141, v88, v89
	v_cvt_pk_bf16_f32 v144, v90, v91
	v_cvt_pk_bf16_f32 v145, v92, v93
	v_cvt_pk_bf16_f32 v146, v94, v95
	v_cvt_pk_bf16_f32 v147, v96, v97
	v_cvt_pk_bf16_f32 v148, v66, v67
	v_cvt_pk_bf16_f32 v149, v68, v69
	v_cvt_pk_bf16_f32 v150, v70, v71
	v_cvt_pk_bf16_f32 v151, v72, v73
	v_cvt_pk_bf16_f32 v162, v74, v75
	v_cvt_pk_bf16_f32 v163, v76, v77
	v_cvt_pk_bf16_f32 v164, v78, v79
	v_cvt_pk_bf16_f32 v165, v80, v81
	s_nop 1
	v_permlane32_swap_b32_e32 v138, v140
	v_permlane32_swap_b32_e32 v139, v141
	v_permlane32_swap_b32_e32 v144, v146
	v_permlane32_swap_b32_e32 v145, v147
	v_permlane32_swap_b32_e32 v148, v150
	v_permlane32_swap_b32_e32 v149, v151
	v_permlane32_swap_b32_e32 v162, v164
	v_permlane32_swap_b32_e32 v163, v165
	s_and_saveexec_b64 s[12:13], s[0:1]
	ds_write_b32 v168, v143 offset:49280
	s_or_b64 exec, exec, s[12:13]
	s_waitcnt lgkmcnt(0)
	v_add_u32_e32 v179, v157, v0
	ds_read_b128 v[186:189], v179 offset:49376
	ds_read_b128 v[190:193], v179 offset:49344
	ds_read_b128 v[194:197], v179 offset:49312
	ds_read_b128 v[198:201], v179 offset:49280
	s_waitcnt lgkmcnt(3)
	v_pk_mul_f32 v[14:15], v[14:15], v[186:187]
	s_waitcnt lgkmcnt(2)
	v_pk_mul_f32 v[10:11], v[10:11], v[190:191]
	s_waitcnt lgkmcnt(1)
	v_pk_mul_f32 v[6:7], v[6:7], v[194:195]
	v_pk_mul_f32 v[16:17], v[16:17], v[188:189]
	v_pk_mul_f32 v[12:13], v[12:13], v[192:193]
	v_pk_mul_f32 v[8:9], v[8:9], v[196:197]
	s_waitcnt lgkmcnt(0)
	v_pk_mul_f32 v[4:5], v[4:5], v[200:201]
	v_pk_mul_f32 v[2:3], v[2:3], v[198:199]
	v_pk_mul_f32 v[62:63], v[62:63], v[186:187]
	v_pk_mul_f32 v[58:59], v[58:59], v[190:191]
	v_pk_mul_f32 v[54:55], v[54:55], v[194:195]
	v_pk_mul_f32 v[64:65], v[64:65], v[188:189]
	v_pk_mul_f32 v[60:61], v[60:61], v[192:193]
	v_pk_mul_f32 v[56:57], v[56:57], v[196:197]
	v_pk_mul_f32 v[52:53], v[52:53], v[200:201]
	v_pk_mul_f32 v[50:51], v[50:51], v[198:199]
	v_pk_mul_f32 v[46:47], v[46:47], v[186:187]
	v_pk_mul_f32 v[42:43], v[42:43], v[190:191]
	v_pk_mul_f32 v[38:39], v[38:39], v[194:195]
	v_pk_mul_f32 v[48:49], v[48:49], v[188:189]
	v_pk_mul_f32 v[44:45], v[44:45], v[192:193]
	v_pk_mul_f32 v[40:41], v[40:41], v[196:197]
	v_pk_mul_f32 v[36:37], v[36:37], v[200:201]
	v_pk_mul_f32 v[34:35], v[34:35], v[198:199]
	v_pk_mul_f32 v[30:31], v[30:31], v[186:187]
	v_pk_mul_f32 v[26:27], v[26:27], v[190:191]
	v_pk_mul_f32 v[22:23], v[22:23], v[194:195]
	v_pk_mul_f32 v[32:33], v[32:33], v[188:189]
	v_pk_mul_f32 v[28:29], v[28:29], v[192:193]
	v_pk_mul_f32 v[24:25], v[24:25], v[196:197]
	v_pk_mul_f32 v[20:21], v[20:21], v[200:201]
	v_pk_mul_f32 v[18:19], v[18:19], v[198:199]

; #define SBAR() __builtin_amdgcn_sched_barrier(0)
; #define RESC(a) do { if (__any((a) < 1.f)) { if (hi == 0) al_l[r32] = (a); asm volatile("s_waitcnt lgkmcnt(0)" ::: "memory"); \
;     _Pragma("unroll") for (int d = 0; d < 4; ++d) _Pragma("unroll") for (int r = 0; r < 16; ++r) o[d][r] *= al_l[crow(r, hi)]; } } while (0)
; template <int DQK, int SDEPTH, bool OUT_BF16, int QREG = DQK / 16, bool OUT_F16 = false> ...
;     ...
;   SBAR(); QKT(pB0, pB1, K_lds + SHM_K);
;   finishSM(pA0, pA1, alA, l_reg, pa0, pa1, pa2, pa3); SBAR();
;   pv_d0(o, vb0, pa0, pa1, pa2, pa3); partialSM(pB0, pB1, m_reg, mnB, alB, SCALE);
;   __syncthreads(); RESC(alB);
.Ldiff_loop_exit:
	v_mov_b32_e32 v142, v206
	v_mov_b32_e32 v170, v207
	v_mov_b32_e32 v203, v207
	s_nop 1
	v_permlane32_swap_b32_e32 v170, v203
	v_add_f32_e32 v170, v170, v203
.LBB0_794:
	ds_read_b128 v[66:69], v175 offset:40960
	ds_read_b128 v[70:73], v175 offset:45056
	s_waitcnt lgkmcnt(1)
	v_mfma_f32_32x32x16_bf16 v[82:97], v[66:69], v[110:113], 0
	s_waitcnt lgkmcnt(0)
	v_mfma_f32_32x32x16_bf16 v[66:81], v[70:73], v[110:113], 0
	ds_read_b128 v[110:113], v176 offset:40960
	ds_read_b128 v[114:117], v176 offset:45056
	s_waitcnt lgkmcnt(1)
	v_mfma_f32_32x32x16_bf16 v[82:97], v[110:113], v[106:109], v[82:97]
	s_waitcnt lgkmcnt(0)
	v_mfma_f32_32x32x16_bf16 v[66:81], v[114:117], v[106:109], v[66:81]
	ds_read_b128 v[106:109], v178 offset:40960
	ds_read_b128 v[110:113], v178 offset:45056
	s_waitcnt lgkmcnt(1)
	v_mfma_f32_32x32x16_bf16 v[82:97], v[106:109], v[102:105], v[82:97]
	s_waitcnt lgkmcnt(0)
	v_mfma_f32_32x32x16_bf16 v[66:81], v[110:113], v[102:105], v[66:81]
	ds_read_b128 v[102:105], v177 offset:40960
	ds_read_b128 v[106:109], v177 offset:45056
	s_waitcnt lgkmcnt(1)
	v_mfma_f32_32x32x16_bf16 v[82:97], v[102:105], v[98:101], v[82:97]
	s_waitcnt lgkmcnt(0)
	v_mfma_f32_32x32x16_bf16 v[66:81], v[106:109], v[98:101], v[66:81]
	v_mov_b32_e32 v99, v180
	v_mov_b32_e32 v100, v180
	s_nop 1
	v_permlane32_swap_b32_e32 v99, v100
	ds_read_b64_tr_b16 v[118:119], v171 offset:0
	ds_read_b64_tr_b16 v[120:121], v171 offset:0x800
	ds_read_b64_tr_b16 v[122:123], v171 offset:0x1000
	ds_read_b64_tr_b16 v[124:125], v171 offset:0x1800
	ds_read_b64_tr_b16 v[126:127], v171 offset:0x2000
	ds_read_b64_tr_b16 v[128:129], v171 offset:0x2800
	ds_read_b64_tr_b16 v[130:131], v171 offset:0x3000
	ds_read_b64_tr_b16 v[132:133], v171 offset:0x3800
	s_waitcnt lgkmcnt(0)
	s_nop 0
	v_mfma_f32_32x32x16_bf16 v[2:17], v[138:141], v[118:121], v[2:17]
	ds_read_b64_tr_b16 v[118:119], v171 offset:0x200
	ds_read_b64_tr_b16 v[120:121], v171 offset:0xa00
	v_mfma_f32_32x32x16_bf16 v[2:17], v[144:147], v[122:125], v[2:17]
	ds_read_b64_tr_b16 v[122:123], v171 offset:0x1200
	ds_read_b64_tr_b16 v[124:125], v171 offset:0x1a00
	v_mfma_f32_32x32x16_bf16 v[2:17], v[148:151], v[126:129], v[2:17]
	ds_read_b64_tr_b16 v[126:127], v171 offset:0x2200
	ds_read_b64_tr_b16 v[128:129], v171 offset:0x2a00
	v_mfma_f32_32x32x16_bf16 v[2:17], v[162:165], v[130:133], v[2:17]
	ds_read_b64_tr_b16 v[130:131], v171 offset:0x3200
	ds_read_b64_tr_b16 v[132:133], v171 offset:0x3a00
	s_waitcnt lgkmcnt(0)
	v_mfma_f32_32x32x16_bf16 v[50:65], v[138:141], v[118:121], v[50:65]
	ds_read_b64_tr_b16 v[118:119], v171 offset:0x400
	ds_read_b64_tr_b16 v[120:121], v171 offset:0xc00
	v_mfma_f32_32x32x16_bf16 v[50:65], v[144:147], v[122:125], v[50:65]
	ds_read_b64_tr_b16 v[122:123], v171 offset:0x1400
	ds_read_b64_tr_b16 v[124:125], v171 offset:0x1c00
	v_mfma_f32_32x32x16_bf16 v[50:65], v[148:151], v[126:129], v[50:65]
	ds_read_b64_tr_b16 v[126:127], v171 offset:0x2400
	ds_read_b64_tr_b16 v[128:129], v171 offset:0x2c00
	v_mfma_f32_32x32x16_bf16 v[50:65], v[162:165], v[130:133], v[50:65]
	ds_read_b64_tr_b16 v[130:131], v171 offset:0x3400
	ds_read_b64_tr_b16 v[132:133], v171 offset:0x3c00
	s_waitcnt lgkmcnt(0)
	v_mfma_f32_32x32x16_bf16 v[34:49], v[138:141], v[118:121], v[34:49]
	ds_read_b64_tr_b16 v[118:119], v171 offset:0x600
	ds_read_b64_tr_b16 v[120:121], v171 offset:0xe00
	v_mfma_f32_32x32x16_bf16 v[34:49], v[144:147], v[122:125], v[34:49]
	ds_read_b64_tr_b16 v[122:123], v171 offset:0x1600
	ds_read_b64_tr_b16 v[124:125], v171 offset:0x1e00
	v_mfma_f32_32x32x16_bf16 v[34:49], v[148:151], v[126:129], v[34:49]
	ds_read_b64_tr_b16 v[126:127], v171 offset:0x2600
	ds_read_b64_tr_b16 v[128:129], v171 offset:0x2e00
	v_mfma_f32_32x32x16_bf16 v[34:49], v[162:165], v[130:133], v[34:49]
	ds_read_b64_tr_b16 v[130:131], v171 offset:0x3600
	ds_read_b64_tr_b16 v[132:133], v171 offset:0x3e00
	s_waitcnt lgkmcnt(0)
	v_mfma_f32_32x32x16_bf16 v[18:33], v[138:141], v[118:121], v[18:33]
	v_max_f32_e32 v98, v83, v83
	v_max_f32_e32 v101, v82, v82
	v_max_f32_e32 v98, v101, v98
	v_max3_f32 v98, v98, v84, v85
	v_max3_f32 v98, v98, v86, v87
	v_max3_f32 v98, v98, v88, v89
	v_max3_f32 v98, v98, v90, v91
	v_max3_f32 v98, v98, v92, v93
	v_max3_f32 v98, v98, v94, v95
	v_mfma_f32_32x32x16_bf16 v[18:33], v[144:147], v[122:125], v[18:33]
	v_max3_f32 v98, v98, v96, v97
	v_max3_f32 v98, v98, v66, v67
	v_max3_f32 v98, v98, v68, v69
	v_max3_f32 v98, v98, v70, v71
	v_max3_f32 v98, v98, v72, v73
	v_max3_f32 v98, v98, v74, v75
	v_max3_f32 v98, v98, v76, v77
	v_max3_f32 v98, v98, v78, v79
	v_mfma_f32_32x32x16_bf16 v[18:33], v[148:151], v[126:129], v[18:33]
	v_max3_f32 v98, v98, v80, v81
	v_mov_b32_e32 v101, v98
	s_nop 1
	v_permlane32_swap_b32_e32 v98, v101
	v_max_f32_e32 v101, v101, v101
	v_max_f32_e32 v98, v98, v98
	v_max_f32_e32 v98, v98, v101
	v_sub_f32_e32 v101, v98, v142
	v_cmp_ge_f32_e32 vcc, 0x4138aa3b, v101
	v_max_f32_e32 v101, v142, v142
	v_max_f32_e32 v98, v101, v98
	v_mfma_f32_32x32x16_bf16 v[18:33], v[162:165], v[130:133], v[18:33]
	v_sub_f32_e32 v101, v142, v98
	v_mul_f32_e32 v101, 0x3f800000, v101
	v_exp_f32_e32 v101, v101
	s_cmp_eq_u64 vcc, exec
	s_cselect_b64 s[2:3], -1, 0
	v_cndmask_b32_e64 v101, v101, 1.0, s[2:3]
	v_cmp_gt_f32_e32 vcc, 1.0, v101
	s_barrier
	s_cbranch_vccz .LBB0_798
; #define SBAR() __builtin_amdgcn_sched_barrier(0)
; #define RESC(a) do { if (__any((a) < 1.f)) { if (hi == 0) al_l[r32] = (a); asm volatile("s_waitcnt lgkmcnt(0)" ::: "memory"); \
;     _Pragma("unroll") for (int d = 0; d < 4; ++d) _Pragma("unroll") for (int r = 0; r < 16; ++r) o[d][r] *= al_l[crow(r, hi)]; } } while (0)
; DI void partialSM(f32x16& p0, f32x16& p1, float& m_reg, float& mn, float& alpha, const float SCALE) {
;   const float C = SCALE * 1.4426950408889634f;
;   float pmax = p0[0];
; #pragma unroll
;   for (int r = 1; r < 16; ++r) pmax = fmaxf(pmax, p0[r]);
; #pragma unroll
;   for (int r = 0; r < 16; ++r) pmax = fmaxf(pmax, p1[r]);
;   { auto rr = __builtin_amdgcn_permlane32_swap(__float_as_uint(pmax), __float_as_uint(pmax), false, false);
;     pmax = fmaxf(__uint_as_float(rr[0]), __uint_as_float(rr[1])); }
;   if (__builtin_expect(__all(pmax - m_reg <= THR / SCALE), 1)) { mn = m_reg; alpha = 1.f; }
;   else { mn = fmaxf(m_reg, pmax); alpha = __builtin_amdgcn_exp2f((m_reg - mn) * C); m_reg = mn; }
;   const float mnC = -mn * C;
; #pragma unroll
;   for (int r = 0; r < 16; ++r) p0[r] = fmaf(p0[r], C, mnC);
; #pragma unroll
;   for (int r = 0; r < 16; ++r) p1[r] = fmaf(p1[r], C, mnC);
; #pragma unroll
;   for (int r = 0; r < 16; ++r) p0[r] = __builtin_amdgcn_exp2f(p0[r]);
; }
; DI void finishSM(f32x16& p0, f32x16& p1, float alpha, float& l_reg, bf16x8& pa0, bf16x8& pa1, bf16x8& pa2, bf16x8& pa3) {
; #pragma unroll
;   for (int r = 0; r < 16; ++r) p1[r] = __builtin_amdgcn_exp2f(p1[r]);
;   float ps = 0;
; #pragma unroll
;   for (int r = 0; r < 16; ++r) ps += p0[r];
; #pragma unroll
;   for (int r = 0; r < 16; ++r) ps += p1[r];
;   { auto rr = __builtin_amdgcn_permlane32_swap(__float_as_uint(ps), __float_as_uint(ps), false, false);
;     ps = __uint_as_float(rr[0]) + __uint_as_float(rr[1]); }
;   l_reg = l_reg * alpha + ps;
;     ...
;   PK4(p0, 0, pa0); PK4(p0, 8, pa1); PK4(p1, 0, pa2); PK4(p1, 8, pa3);
;     ...
; }
; template <int DQK, int SDEPTH, bool OUT_BF16, int QREG = DQK / 16, bool OUT_F16 = false> ...
;     ...
;   pv_d0(o, vb0, pa0, pa1, pa2, pa3); partialSM(pB0, pB1, m_reg, mnB, alB, SCALE);
;   __syncthreads(); RESC(alB);
;   finishSM(pB0, pB1, alB, l_reg, pa0, pa1, pa2, pa3); SBAR();
;   pv_d0(o, vb0 + SHM_V, pa0, pa1, pa2, pa3);
	s_and_saveexec_b64 s[10:11], s[0:1]
	ds_write_b32 v168, v101 offset:49280
	s_or_b64 exec, exec, s[10:11]
	s_waitcnt lgkmcnt(0)
	v_add_u32_e32 v114, v157, v0
	ds_read_b128 v[102:105], v114 offset:49376
	ds_read_b128 v[106:109], v114 offset:49344
	ds_read_b128 v[110:113], v114 offset:49312
	ds_read_b128 v[114:117], v114 offset:49280
	s_waitcnt lgkmcnt(3)
	v_pk_mul_f32 v[14:15], v[14:15], v[102:103]
	s_waitcnt lgkmcnt(2)
	v_pk_mul_f32 v[10:11], v[10:11], v[106:107]
	s_waitcnt lgkmcnt(1)
	v_pk_mul_f32 v[6:7], v[6:7], v[110:111]
	v_pk_mul_f32 v[16:17], v[16:17], v[104:105]
	v_pk_mul_f32 v[12:13], v[12:13], v[108:109]
	v_pk_mul_f32 v[8:9], v[8:9], v[112:113]
	s_waitcnt lgkmcnt(0)
	v_pk_mul_f32 v[4:5], v[4:5], v[116:117]
	v_pk_mul_f32 v[2:3], v[2:3], v[114:115]
	v_pk_mul_f32 v[62:63], v[62:63], v[102:103]
	v_pk_mul_f32 v[58:59], v[58:59], v[106:107]
	v_pk_mul_f32 v[54:55], v[54:55], v[110:111]
	v_pk_mul_f32 v[64:65], v[64:65], v[104:105]
	v_pk_mul_f32 v[60:61], v[60:61], v[108:109]
	v_pk_mul_f32 v[56:57], v[56:57], v[112:113]
	v_pk_mul_f32 v[52:53], v[52:53], v[116:117]
	v_pk_mul_f32 v[50:51], v[50:51], v[114:115]
	v_pk_mul_f32 v[46:47], v[46:47], v[102:103]
	v_pk_mul_f32 v[42:43], v[42:43], v[106:107]
	v_pk_mul_f32 v[38:39], v[38:39], v[110:111]
	v_pk_mul_f32 v[48:49], v[48:49], v[104:105]
	v_pk_mul_f32 v[44:45], v[44:45], v[108:109]
	v_pk_mul_f32 v[40:41], v[40:41], v[112:113]
	v_pk_mul_f32 v[36:37], v[36:37], v[116:117]
	v_pk_mul_f32 v[34:35], v[34:35], v[114:115]
	v_pk_mul_f32 v[30:31], v[30:31], v[102:103]
	v_pk_mul_f32 v[26:27], v[26:27], v[106:107]
	v_pk_mul_f32 v[22:23], v[22:23], v[110:111]
	v_pk_mul_f32 v[32:33], v[32:33], v[104:105]
	v_pk_mul_f32 v[28:29], v[28:29], v[108:109]
	v_pk_mul_f32 v[24:25], v[24:25], v[112:113]
	v_pk_mul_f32 v[20:21], v[20:21], v[116:117]
	v_pk_mul_f32 v[18:19], v[18:19], v[114:115]
.LBB0_798:
	v_cndmask_b32_e64 v98, v98, v142, s[2:3]
	v_mul_f32_e32 v102, 0xbf800000, v98
	v_fmamk_f32 v82, v82, 0x3f800000, v102
	v_fmamk_f32 v83, v83, 0x3f800000, v102
	v_fmamk_f32 v111, v93, 0x3f800000, v102
	v_fmamk_f32 v93, v74, 0x3f800000, v102
	v_exp_f32_e32 v74, v82
	v_fmamk_f32 v84, v84, 0x3f800000, v102
	v_fmamk_f32 v112, v94, 0x3f800000, v102
	v_fmamk_f32 v94, v75, 0x3f800000, v102
	v_exp_f32_e32 v75, v83
	v_fmamk_f32 v103, v85, 0x3f800000, v102
	v_fmamk_f32 v113, v95, 0x3f800000, v102
	v_fmamk_f32 v95, v76, 0x3f800000, v102
	v_exp_f32_e32 v76, v84
	v_fmamk_f32 v104, v86, 0x3f800000, v102
	v_fmamk_f32 v114, v96, 0x3f800000, v102
	v_fmamk_f32 v96, v77, 0x3f800000, v102
	v_exp_f32_e32 v77, v103
	v_fmamk_f32 v79, v79, 0x3f800000, v102
	v_fmamk_f32 v105, v87, 0x3f800000, v102
	v_fmamk_f32 v106, v88, 0x3f800000, v102
	v_fmamk_f32 v107, v89, 0x3f800000, v102
	v_fmamk_f32 v108, v90, 0x3f800000, v102
	v_fmamk_f32 v109, v91, 0x3f800000, v102
	v_fmamk_f32 v110, v92, 0x3f800000, v102
	v_fmamk_f32 v115, v97, 0x3f800000, v102
	v_fmamk_f32 v85, v66, 0x3f800000, v102
	v_fmamk_f32 v86, v67, 0x3f800000, v102
	v_fmamk_f32 v87, v68, 0x3f800000, v102
	v_fmamk_f32 v88, v69, 0x3f800000, v102
	v_fmamk_f32 v89, v70, 0x3f800000, v102
	v_fmamk_f32 v90, v71, 0x3f800000, v102
	v_fmamk_f32 v91, v72, 0x3f800000, v102
	v_fmamk_f32 v92, v73, 0x3f800000, v102
	v_fmamk_f32 v97, v78, 0x3f800000, v102
	v_exp_f32_e32 v78, v104
	v_fmamk_f32 v80, v80, 0x3f800000, v102
	v_fmac_f32_e32 v102, 0x3f800000, v81
	v_add_f32_e32 v81, v99, v100
	v_exp_f32_e32 v100, v79
	v_add_f32_e32 v79, 0, v74
	v_exp_f32_e32 v82, v105
	v_add_f32_e32 v79, v75, v79
	v_exp_f32_e32 v83, v106
	v_add_f32_e32 v79, v76, v79
	v_exp_f32_e32 v84, v107
	v_add_f32_e32 v79, v77, v79
	v_exp_f32_e32 v66, v108
	v_add_f32_e32 v79, v78, v79
	v_exp_f32_e32 v67, v109
	v_add_f32_e32 v79, v82, v79
	v_exp_f32_e32 v68, v110
	v_add_f32_e32 v79, v83, v79
	v_exp_f32_e32 v69, v111
	v_add_f32_e32 v79, v84, v79
	v_exp_f32_e32 v70, v112
	v_add_f32_e32 v79, v66, v79
	v_exp_f32_e32 v71, v113
	v_add_f32_e32 v79, v67, v79
	v_exp_f32_e32 v72, v114
	v_add_f32_e32 v79, v68, v79
	v_exp_f32_e32 v73, v115
	v_add_f32_e32 v79, v69, v79
	v_exp_f32_e32 v85, v85
	v_add_f32_e32 v79, v70, v79
	v_exp_f32_e32 v86, v86
	v_add_f32_e32 v79, v71, v79
	v_exp_f32_e32 v87, v87
	v_add_f32_e32 v79, v72, v79
	v_exp_f32_e32 v88, v88
	v_add_f32_e32 v79, v73, v79
	v_exp_f32_e32 v89, v89
	v_add_f32_e32 v79, v85, v79
	v_exp_f32_e32 v90, v90
	v_add_f32_e32 v79, v86, v79
	v_exp_f32_e32 v91, v91
	v_add_f32_e32 v79, v87, v79
	v_exp_f32_e32 v92, v92
	v_add_f32_e32 v79, v88, v79
	v_exp_f32_e32 v93, v93
	v_add_f32_e32 v79, v89, v79
	v_exp_f32_e32 v94, v94
	v_add_f32_e32 v79, v90, v79
	v_exp_f32_e32 v95, v95
	v_add_f32_e32 v79, v91, v79
	v_exp_f32_e32 v96, v96
	v_add_f32_e32 v79, v92, v79
	v_exp_f32_e32 v97, v97
	v_add_f32_e32 v79, v93, v79
	v_add_f32_e32 v79, v94, v79
	v_exp_f32_e32 v103, v80
	v_add_f32_e32 v79, v95, v79
	v_exp_f32_e32 v102, v102
	v_add_f32_e32 v79, v96, v79
	v_add_f32_e32 v79, v97, v79
	v_add_f32_e32 v79, v100, v79
	v_add_f32_e32 v79, v103, v79
	v_add_f32_e32 v79, v102, v79
	v_mov_b32_e32 v80, v79
	s_nop 1
	v_permlane32_swap_b32_e32 v79, v80
	v_fmac_f32_e32 v81, v170, v143
	v_add_f32_e32 v99, v79, v80
	v_fmac_f32_e32 v99, v81, v101
	v_cvt_pk_bf16_f32 v74, v74, v75
	v_cvt_pk_bf16_f32 v75, v76, v77
	v_cvt_pk_bf16_f32 v76, v78, v82
	v_cvt_pk_bf16_f32 v77, v83, v84
	v_cvt_pk_bf16_f32 v66, v66, v67
	v_cvt_pk_bf16_f32 v67, v68, v69
	v_cvt_pk_bf16_f32 v68, v70, v71
	v_cvt_pk_bf16_f32 v69, v72, v73
	v_cvt_pk_bf16_f32 v70, v85, v86
	v_cvt_pk_bf16_f32 v71, v87, v88
	v_cvt_pk_bf16_f32 v72, v89, v90
	v_cvt_pk_bf16_f32 v73, v91, v92
	v_cvt_pk_bf16_f32 v78, v93, v94
	v_cvt_pk_bf16_f32 v79, v95, v96
	v_cvt_pk_bf16_f32 v80, v97, v100
	v_cvt_pk_bf16_f32 v81, v103, v102
	v_permlane32_swap_b32_e32 v74, v76
	v_permlane32_swap_b32_e32 v75, v77
	v_permlane32_swap_b32_e32 v66, v68
	v_permlane32_swap_b32_e32 v67, v69
	v_permlane32_swap_b32_e32 v70, v72
	v_permlane32_swap_b32_e32 v71, v73
	v_permlane32_swap_b32_e32 v78, v80
	v_permlane32_swap_b32_e32 v79, v81
	ds_read_b64_tr_b16 v[82:83], v169 offset:0
	ds_read_b64_tr_b16 v[84:85], v169 offset:0x800
	ds_read_b64_tr_b16 v[86:87], v169 offset:0x1000
	ds_read_b64_tr_b16 v[88:89], v169 offset:0x1800
	ds_read_b64_tr_b16 v[90:91], v169 offset:0x2000
	ds_read_b64_tr_b16 v[92:93], v169 offset:0x2800
	ds_read_b64_tr_b16 v[94:95], v169 offset:0x3000
	ds_read_b64_tr_b16 v[96:97], v169 offset:0x3800
	s_waitcnt lgkmcnt(0)
; template <int DQK, int SDEPTH, bool OUT_BF16, int QREG = DQK / 16, bool OUT_F16 = false> ...
;     ...
;   pv_d0(o, vb0 + SHM_V, pa0, pa1, pa2, pa3);
;   if (hi == 0) li_l[r32] = l_reg; asm volatile("s_waitcnt lgkmcnt(0)" ::: "memory");
;   if (stats != nullptr && hi == 0) stats[wid * QBLK + r32] = (f32x2){m_reg, l_reg};
	s_nop 0
	v_mfma_f32_32x32x16_bf16 v[2:17], v[74:77], v[82:85], v[2:17]
	ds_read_b64_tr_b16 v[82:83], v169 offset:0x200
	ds_read_b64_tr_b16 v[84:85], v169 offset:0xa00
	v_mfma_f32_32x32x16_bf16 v[2:17], v[66:69], v[86:89], v[2:17]
	ds_read_b64_tr_b16 v[86:87], v169 offset:0x1200
	ds_read_b64_tr_b16 v[88:89], v169 offset:0x1a00
	v_mfma_f32_32x32x16_bf16 v[2:17], v[70:73], v[90:93], v[2:17]
	ds_read_b64_tr_b16 v[90:91], v169 offset:0x2200
	ds_read_b64_tr_b16 v[92:93], v169 offset:0x2a00
	v_mfma_f32_32x32x16_bf16 v[2:17], v[78:81], v[94:97], v[2:17]
	ds_read_b64_tr_b16 v[94:95], v169 offset:0x3200
	ds_read_b64_tr_b16 v[96:97], v169 offset:0x3a00
	s_waitcnt lgkmcnt(0)
	v_mfma_f32_32x32x16_bf16 v[50:65], v[74:77], v[82:85], v[50:65]
	ds_read_b64_tr_b16 v[82:83], v169 offset:0x400
	ds_read_b64_tr_b16 v[84:85], v169 offset:0xc00
	v_mfma_f32_32x32x16_bf16 v[50:65], v[66:69], v[86:89], v[50:65]
	ds_read_b64_tr_b16 v[86:87], v169 offset:0x1400
	ds_read_b64_tr_b16 v[88:89], v169 offset:0x1c00
	v_mfma_f32_32x32x16_bf16 v[50:65], v[70:73], v[90:93], v[50:65]
	ds_read_b64_tr_b16 v[90:91], v169 offset:0x2400
	ds_read_b64_tr_b16 v[92:93], v169 offset:0x2c00
	v_mfma_f32_32x32x16_bf16 v[50:65], v[78:81], v[94:97], v[50:65]
	ds_read_b64_tr_b16 v[94:95], v169 offset:0x3400
	ds_read_b64_tr_b16 v[96:97], v169 offset:0x3c00
	s_waitcnt lgkmcnt(0)
	v_mfma_f32_32x32x16_bf16 v[34:49], v[74:77], v[82:85], v[34:49]
	ds_read_b64_tr_b16 v[82:83], v169 offset:0x600
	ds_read_b64_tr_b16 v[84:85], v169 offset:0xe00
	v_mfma_f32_32x32x16_bf16 v[34:49], v[66:69], v[86:89], v[34:49]
	ds_read_b64_tr_b16 v[86:87], v169 offset:0x1600
	ds_read_b64_tr_b16 v[88:89], v169 offset:0x1e00
	v_mfma_f32_32x32x16_bf16 v[34:49], v[70:73], v[90:93], v[34:49]
	ds_read_b64_tr_b16 v[90:91], v169 offset:0x2600
	ds_read_b64_tr_b16 v[92:93], v169 offset:0x2e00
	v_mfma_f32_32x32x16_bf16 v[34:49], v[78:81], v[94:97], v[34:49]
	ds_read_b64_tr_b16 v[94:95], v169 offset:0x3600
	ds_read_b64_tr_b16 v[96:97], v169 offset:0x3e00
	s_waitcnt lgkmcnt(0)
	v_mfma_f32_32x32x16_bf16 v[18:33], v[74:77], v[82:85], v[18:33]
	v_mfma_f32_32x32x16_bf16 v[18:33], v[66:69], v[86:89], v[18:33]
	v_mfma_f32_32x32x16_bf16 v[18:33], v[70:73], v[90:93], v[18:33]
	v_mfma_f32_32x32x16_bf16 v[18:33], v[78:81], v[94:97], v[18:33]
	s_and_saveexec_b64 s[2:3], s[0:1]
	ds_write_b32 v168, v99 offset:49152
	s_or_b64 exec, exec, s[2:3]
	s_waitcnt lgkmcnt(0)
	s_cmp_lg_u64 s[38:39], 0
	s_cselect_b64 s[2:3], -1, 0
	s_and_b64 s[2:3], s[0:1], s[2:3]
	s_and_saveexec_b64 s[0:1], s[2:3]
	s_cbranch_execz .LBB0_764
	v_lshl_add_u64 v[66:67], v[154:155], 3, s[38:39]
	global_store_dwordx2 v[66:67], v[98:99], off
	s_branch .LBB0_764

; DI float grp16_sum(float v) { v += swz_xor<1>(v); v += swz_xor<2>(v); v += swz_xor<4>(v); v += swz_xor<8>(v); return v; }
; DI float silu_f(float x) { return x * __builtin_amdgcn_rcpf(1.f + __expf(-x)); }
; DI void mixer_post(const Frame& F, int l) {
;     ...
;     for (int r = F.gw; r < MT; r += F.ngw) {
;         {
;             const _Float16* a = og + (size_t)r * 512 + c0; const _Float16* bq = og + ((size_t)MT + r) * 512 + c0; float o[8], z[8]; float ss = 0.f;
;             const h16x8 ah = *(const h16x8*)a, bh8 = *(const h16x8*)bq;
;             const f32x4 a0 = __builtin_convertvector(__builtin_shufflevector(ah, ah, 0, 1, 2, 3), f32x4), a1 = __builtin_convertvector(__builtin_shufflevector(ah, ah, 4, 5, 6, 7), f32x4), b0 = __builtin_convertvector(__builtin_shufflevector(bh8, bh8, 0, 1, 2, 3), f32x4), b1 = __builtin_convertvector(__builtin_shufflevector(bh8, bh8, 4, 5, 6, 7), f32x4);
; #pragma unroll
;             for (int j = 0; j < 4; ++j) { o[j] = a0[j] + b0[j]; o[4 + j] = a1[j] + b1[j]; }
; #pragma unroll
;             for (int j = 0; j < 8; ++j) ss += o[j] * o[j];
;             ss = grp16_sum(ss); const float rs = rsqrtf(ss * (1.f / 128.f) + RMS_EPS);
;             unpack8(*(const u32x4*)(p + (size_t)r * NP + PC_GZ + c0), z);
; #pragma unroll
;             for (int j = 0; j < 8; ++j) o[j] = o[j] * rs * gn[j] * silu_f(z[j]);
;             *(u32x4*)(mix + (size_t)r * DM + c0) = pack8(o);
;         }
;         {
;             const _Float16* a = Od + (size_t)r * 512 + c0; const _Float16* bq = Od + ((size_t)MT + r) * 512 + c0; float o[8]; float ss = 0.f;
;             const h16x8 ah = *(const h16x8*)a, bh8 = *(const h16x8*)bq;
;             f32x4 a0 = __builtin_convertvector(__builtin_shufflevector(ah, ah, 0, 1, 2, 3), f32x4), a1 = __builtin_convertvector(__builtin_shufflevector(ah, ah, 4, 5, 6, 7), f32x4), b0 = __builtin_convertvector(__builtin_shufflevector(bh8, bh8, 0, 1, 2, 3), f32x4), b1 = __builtin_convertvector(__builtin_shufflevector(bh8, bh8, 4, 5, 6, 7), f32x4);
;             if (r < MLAT && ((r & (SEQ - 1)) >> 8) >= DIFF_QB_WHOLE) {
;                 const _Float16* a2 = (const _Float16*)(F.ws + WS_OD2) + (size_t)r * 512 + c0; const _Float16* b2 = (const _Float16*)(F.ws + WS_OD2) + ((size_t)MT + r) * 512 + c0;
;                 const h16x8 ch = *(const h16x8*)a2, eh = *(const h16x8*)b2;
.LBB0_1144:
	v_lshl_add_u64 v[22:23], s[0:1], 0, v[18:19]
	v_add_co_u32_e32 v2, vcc, 0x459fc000, v22
	s_mov_b32 s3, 0x19dc4000
	s_nop 0
	v_addc_co_u32_e32 v3, vcc, 0, v23, vcc
	v_add_co_u32_e32 v20, vcc, 0x46a7c000, v22
	global_load_dwordx4 v[2:5], v[2:3], off
	s_nop 0
	v_addc_co_u32_e32 v21, vcc, 0, v23, vcc
	global_load_dwordx4 v[24:27], v[20:21], off
	v_lshl_add_u64 v[20:21], s[0:1], 0, v[16:17]
	global_load_dwordx4 v[28:31], v[20:21], off
	s_cmpk_lt_i32 s2, 0x4000
	s_waitcnt vmcnt(2)
	v_cvt_f32_f16_e32 v20, v5
	v_cvt_f32_f16_sdwa v21, v5 dst_sel:DWORD dst_unused:UNUSED_PAD src0_sel:WORD_1
	s_waitcnt vmcnt(1)
	v_cvt_f32_f16_e32 v32, v27
	v_cvt_f32_f16_sdwa v33, v27 dst_sel:DWORD dst_unused:UNUSED_PAD src0_sel:WORD_1
	s_waitcnt vmcnt(0)
	v_lshlrev_b32_e32 v42, 16, v30
	v_mul_f32_e32 v0, 0xbfb8aa3b, v42
	v_exp_f32_e32 v0, v0
	v_and_b32_e32 v43, 0xffff0000, v30
	v_lshlrev_b32_e32 v50, 16, v29
	v_pk_add_f32 v[20:21], v[20:21], v[32:33]
	v_add_f32_e32 v0, 1.0, v0
	v_rcp_f32_e32 v44, v0
	v_mul_f32_e32 v0, 0xbfb8aa3b, v43
	v_exp_f32_e32 v0, v0
	v_cvt_f32_f16_e32 v32, v4
	v_cvt_f32_f16_sdwa v33, v4 dst_sel:DWORD dst_unused:UNUSED_PAD src0_sel:WORD_1
	v_cvt_f32_f16_e32 v4, v26
	v_add_f32_e32 v0, 1.0, v0
	v_cvt_f32_f16_sdwa v5, v26 dst_sel:DWORD dst_unused:UNUSED_PAD src0_sel:WORD_1
	v_rcp_f32_e32 v45, v0
	v_mul_f32_e32 v0, 0xbfb8aa3b, v50
	v_exp_f32_e32 v0, v0
	v_lshlrev_b32_e32 v40, 16, v31
	v_and_b32_e32 v41, 0xffff0000, v31
	v_pk_add_f32 v[4:5], v[32:33], v[4:5]
	global_load_dwordx4 v[30:33], v[6:7], off offset:16
	global_load_dwordx4 v[34:37], v[6:7], off
	v_and_b32_e32 v51, 0xffff0000, v29
	v_add_f32_e32 v0, 1.0, v0
	v_rcp_f32_e32 v52, v0
	v_mul_f32_e32 v0, 0xbfb8aa3b, v51
	v_exp_f32_e32 v0, v0
	v_pk_mul_f32 v[42:43], v[44:45], v[42:43]
	v_cvt_f32_f16_e32 v44, v3
	v_cvt_f32_f16_sdwa v45, v3 dst_sel:DWORD dst_unused:UNUSED_PAD src0_sel:WORD_1
	v_add_f32_e32 v0, 1.0, v0
	v_rcp_f32_e32 v53, v0
	v_cvt_f32_f16_sdwa v3, v24 dst_sel:DWORD dst_unused:UNUSED_PAD src0_sel:WORD_1
	v_cvt_f32_f16_e32 v48, v25
	v_cvt_f32_f16_sdwa v49, v25 dst_sel:DWORD dst_unused:UNUSED_PAD src0_sel:WORD_1
	v_pk_mul_f32 v[50:51], v[52:53], v[50:51]
	v_cvt_f32_f16_e32 v52, v2
	v_cvt_f32_f16_sdwa v53, v2 dst_sel:DWORD dst_unused:UNUSED_PAD src0_sel:WORD_1
	v_cvt_f32_f16_e32 v2, v24
	v_pk_add_f32 v[44:45], v[44:45], v[48:49]
	v_pk_mul_f32 v[26:27], v[4:5], v[4:5]
	v_pk_mul_f32 v[48:49], v[44:45], v[44:45]
	v_pk_add_f32 v[2:3], v[52:53], v[2:3]
	v_lshlrev_b32_e32 v52, 16, v28
	v_mul_f32_e32 v0, 0xbfb8aa3b, v52
	v_exp_f32_e32 v0, v0
	v_and_b32_e32 v53, 0xffff0000, v28
	v_pk_mul_f32 v[24:25], v[2:3], v[2:3]
	v_pk_mul_f32 v[38:39], v[20:21], v[20:21]
	v_add_f32_e32 v0, 1.0, v0
	v_rcp_f32_e32 v28, v0
	v_mul_f32_e32 v0, 0xbfb8aa3b, v53
	v_exp_f32_e32 v0, v0
	s_nop 0
	v_add_f32_e32 v0, 1.0, v0
	v_rcp_f32_e32 v29, v0
	v_add_f32_e32 v0, v24, v25
	v_add_f32_e32 v0, v48, v0
	v_add_f32_e32 v0, v49, v0
	v_add_f32_e32 v0, v26, v0
	v_add_f32_e32 v0, v27, v0
	v_add_f32_e32 v0, v38, v0
	v_add_f32_e32 v0, v39, v0
	ds_swizzle_b32 v24, v0 offset:swizzle(SWAP,1)
	v_mul_f32_e32 v26, 0xbfb8aa3b, v40
	v_exp_f32_e32 v26, v26
	v_pk_mul_f32 v[28:29], v[28:29], v[52:53]
	s_waitcnt lgkmcnt(0)
	v_add_f32_e32 v0, v0, v24
	ds_swizzle_b32 v24, v0 offset:swizzle(SWAP,2)
	v_add_f32_e32 v26, 1.0, v26
	v_rcp_f32_e32 v26, v26
	s_waitcnt lgkmcnt(0)
	v_add_f32_e32 v0, v0, v24
	ds_swizzle_b32 v24, v0 offset:swizzle(SWAP,4)
	s_waitcnt lgkmcnt(0)
	v_add_f32_e32 v0, v0, v24
	ds_swizzle_b32 v24, v0 offset:swizzle(SWAP,8)
	s_waitcnt lgkmcnt(0)
	v_add_f32_e32 v0, v0, v24
	v_fmamk_f32 v0, v0, 0x3c000000, v233
	v_cmp_gt_f32_e32 vcc, s16, v0
	v_mul_f32_e32 v24, 0x4b800000, v0
	s_cselect_b64 s[16:17], -1, 0
	v_cndmask_b32_e32 v0, v0, v24, vcc
	v_rsq_f32_e32 v0, v0
	s_nop 0
	v_mul_f32_e32 v24, 0x45800000, v0
	v_cndmask_b32_e32 v0, v0, v24, vcc
	v_pk_mul_f32 v[2:3], v[2:3], v[0:1] op_sel_hi:[1,0]
	v_pk_mul_f32 v[24:25], v[44:45], v[0:1] op_sel_hi:[1,0]
	v_pk_mul_f32 v[4:5], v[4:5], v[0:1] op_sel_hi:[1,0]
	v_pk_mul_f32 v[20:21], v[20:21], v[0:1] op_sel_hi:[1,0]
	v_mul_f32_e32 v0, 0xbfb8aa3b, v41
	v_exp_f32_e32 v0, v0
	s_waitcnt vmcnt(1)
	v_pk_mul_f32 v[4:5], v[30:31], v[4:5]
	v_pk_mul_f32 v[20:21], v[32:33], v[20:21]
	s_waitcnt vmcnt(0)
	v_pk_mul_f32 v[2:3], v[34:35], v[2:3]
	v_add_f32_e32 v0, 1.0, v0
	v_rcp_f32_e32 v27, v0
	v_pk_mul_f32 v[24:25], v[36:37], v[24:25]
	v_pk_mul_f32 v[4:5], v[42:43], v[4:5]
	v_pk_mul_f32 v[2:3], v[28:29], v[2:3]
	v_pk_mul_f32 v[26:27], v[26:27], v[40:41]
	v_pk_mul_f32 v[24:25], v[50:51], v[24:25]
	v_pk_mul_f32 v[20:21], v[26:27], v[20:21]
	v_cvt_pk_bf16_f32 v4, v4, v5
	v_cvt_pk_bf16_f32 v5, v20, v21
	v_lshl_add_u64 v[20:21], s[0:1], 0, v[14:15]
	v_cvt_pk_bf16_f32 v2, v2, v3
	v_cvt_pk_bf16_f32 v3, v24, v25
	v_add_co_u32_e32 v24, vcc, s3, v20
	s_mov_b32 s3, 0x38484000
	s_nop 0
	v_addc_co_u32_e32 v25, vcc, 0, v21, vcc
	global_store_dwordx4 v[24:25], v[2:5], off
	s_nop 1
	v_add_co_u32_e32 v2, vcc, s3, v22
	s_mov_b32 s3, 0x39504000
	s_nop 0
	v_addc_co_u32_e32 v3, vcc, 0, v23, vcc
	global_load_dwordx4 v[24:27], v[2:3], off
	v_add_co_u32_e32 v2, vcc, s3, v22
	s_and_b32 s3, s2, 0x1f00
	s_nop 0
	v_addc_co_u32_e32 v3, vcc, 0, v23, vcc
	global_load_dwordx4 v[34:37], v[2:3], off
	s_cmpk_gt_u32 s3, 0x1a00
	s_cselect_b64 s[18:19], -1, 0
	s_and_b64 s[16:17], s[16:17], s[18:19]
	s_andn2_b64 vcc, exec, s[16:17]
	s_waitcnt vmcnt(1)
	v_cvt_f32_f16_e32 v4, v25
	v_cvt_f32_f16_e32 v2, v24
	v_cvt_f32_f16_sdwa v5, v25 dst_sel:DWORD dst_unused:UNUSED_PAD src0_sel:WORD_1
	v_cvt_f32_f16_sdwa v3, v24 dst_sel:DWORD dst_unused:UNUSED_PAD src0_sel:WORD_1
	v_cvt_f32_f16_e32 v28, v27
	v_cvt_f32_f16_e32 v30, v26
	v_cvt_f32_f16_sdwa v29, v27 dst_sel:DWORD dst_unused:UNUSED_PAD src0_sel:WORD_1
	v_cvt_f32_f16_sdwa v31, v26 dst_sel:DWORD dst_unused:UNUSED_PAD src0_sel:WORD_1
	s_waitcnt vmcnt(0)
	v_cvt_f32_f16_e32 v26, v35
	v_cvt_f32_f16_e32 v24, v34
	v_cvt_f32_f16_sdwa v27, v35 dst_sel:DWORD dst_unused:UNUSED_PAD src0_sel:WORD_1
	v_cvt_f32_f16_sdwa v25, v34 dst_sel:DWORD dst_unused:UNUSED_PAD src0_sel:WORD_1
	v_cvt_f32_f16_e32 v32, v37
	v_cvt_f32_f16_e32 v34, v36
	v_cvt_f32_f16_sdwa v33, v37 dst_sel:DWORD dst_unused:UNUSED_PAD src0_sel:WORD_1
	v_cvt_f32_f16_sdwa v35, v36 dst_sel:DWORD dst_unused:UNUSED_PAD src0_sel:WORD_1
	s_cbranch_vccnz .LBB0_1143
; DI void mixer_post(const Frame& F, int l) {
;     ...
;             if (r < MLAT && ((r & (SEQ - 1)) >> 8) >= DIFF_QB_WHOLE) {
;                 const _Float16* a2 = (const _Float16*)(F.ws + WS_OD2) + (size_t)r * 512 + c0; const _Float16* b2 = (const _Float16*)(F.ws + WS_OD2) + ((size_t)MT + r) * 512 + c0;
;                 const h16x8 ch = *(const h16x8*)a2, eh = *(const h16x8*)b2;
;                 const f32x4 c0v = __builtin_convertvector(__builtin_shufflevector(ch, ch, 0, 1, 2, 3), f32x4), c1v = __builtin_convertvector(__builtin_shufflevector(ch, ch, 4, 5, 6, 7), f32x4), e0v = __builtin_convertvector(__builtin_shufflevector(eh, eh, 0, 1, 2, 3), f32x4), e1v = __builtin_convertvector(__builtin_shufflevector(eh, eh, 4, 5, 6, 7), f32x4);
;                 const f32x2* st = (const f32x2*)(F.big + WB_DST) + (size_t)(lane >> 4) * MT + r;
;                 const f32x2 s00 = st[0], s01 = st[(size_t)4 * MT], s10 = st[(size_t)8 * MT], s11 = st[(size_t)12 * MT];
;                 const float CC = 0.125f * 1.4426950408889634f;
;                 { const float M = fmaxf(s00.x, s10.x); const float w0 = s00.y * __builtin_amdgcn_exp2f((s00.x - M) * CC), w1 = s10.y * __builtin_amdgcn_exp2f((s10.x - M) * CC); const float inv = __builtin_amdgcn_rcpf(w0 + w1);
;                   a0 = (a0 * w0 + c0v * w1) * inv; a1 = (a1 * w0 + c1v * w1) * inv; }
;                 { const float M = fmaxf(s01.x, s11.x); const float w0 = s01.y * __builtin_amdgcn_exp2f((s01.x - M) * CC), w1 = s11.y * __builtin_amdgcn_exp2f((s11.x - M) * CC); const float inv = __builtin_amdgcn_rcpf(w0 + w1);
;                   b0 = (b0 * w0 + e0v * w1) * inv; b1 = (b1 * w0 + e1v * w1) * inv; }
	v_add_co_u32_e32 v36, vcc, 0x119c4000, v22
	v_lshl_add_u64 v[44:45], s[0:1], 0, v[12:13]
	s_nop 0
	v_addc_co_u32_e32 v37, vcc, 0, v23, vcc
	v_add_co_u32_e32 v22, vcc, 0x12a44000, v22
	global_load_dwordx4 v[36:39], v[36:37], off
	s_nop 0
	v_addc_co_u32_e32 v23, vcc, 0, v23, vcc
	global_load_dwordx4 v[40:43], v[22:23], off
	s_mov_b32 s3, 0x3dd34000
	s_waitcnt vmcnt(1)
	v_cvt_f32_f16_e32 v48, v36
	v_cvt_f32_f16_sdwa v49, v36 dst_sel:DWORD dst_unused:UNUSED_PAD src0_sel:WORD_1
	v_cvt_f32_f16_e32 v50, v37
	s_waitcnt vmcnt(0)
	v_cvt_f32_f16_e32 v22, v42
	v_cvt_f32_f16_sdwa v23, v42 dst_sel:DWORD dst_unused:UNUSED_PAD src0_sel:WORD_1
	v_add_co_u32_e32 v42, vcc, s3, v44
	v_cvt_f32_f16_sdwa v51, v37 dst_sel:DWORD dst_unused:UNUSED_PAD src0_sel:WORD_1
	v_cvt_f32_f16_e32 v36, v43
	v_cvt_f32_f16_sdwa v37, v43 dst_sel:DWORD dst_unused:UNUSED_PAD src0_sel:WORD_1
	v_addc_co_u32_e32 v43, vcc, 0, v45, vcc
	s_mov_b32 s3, 0x3ddb8000
	global_load_dwordx2 v[56:57], v[42:43], off
	v_add_co_u32_e32 v42, vcc, s3, v44
	s_mov_b32 s3, 0x3de3c000
	s_nop 0
	v_addc_co_u32_e32 v43, vcc, 0, v45, vcc
	v_add_co_u32_e32 v58, vcc, s3, v44
	s_mov_b32 s3, 0x3dec0000
	s_nop 0
	v_addc_co_u32_e32 v59, vcc, 0, v45, vcc
	global_load_dwordx2 v[58:59], v[58:59], off
	v_add_co_u32_e32 v44, vcc, s3, v44
	global_load_dwordx2 v[42:43], v[42:43], off
	s_nop 0
	v_addc_co_u32_e32 v45, vcc, 0, v45, vcc
	global_load_dwordx2 v[44:45], v[44:45], off
	v_cvt_f32_f16_e32 v52, v38
	v_cvt_f32_f16_sdwa v53, v38 dst_sel:DWORD dst_unused:UNUSED_PAD src0_sel:WORD_1
	v_cvt_f32_f16_e32 v54, v39
	v_cvt_f32_f16_sdwa v55, v39 dst_sel:DWORD dst_unused:UNUSED_PAD src0_sel:WORD_1
	v_cvt_f32_f16_e32 v38, v40
	v_cvt_f32_f16_sdwa v39, v40 dst_sel:DWORD dst_unused:UNUSED_PAD src0_sel:WORD_1
	v_cvt_f32_f16_e32 v40, v41
	v_cvt_f32_f16_sdwa v41, v41 dst_sel:DWORD dst_unused:UNUSED_PAD src0_sel:WORD_1
	s_waitcnt vmcnt(3)
	v_max_f32_e32 v47, v56, v56
	s_waitcnt vmcnt(2)
	v_max_f32_e32 v0, v58, v58
	v_max_f32_e32 v0, v47, v0
	v_sub_f32_e32 v47, v56, v0
	v_sub_f32_e32 v0, v58, v0
	v_mul_f32_e32 v47, 0x3f800000, v47
	v_mul_f32_e32 v0, 0x3f800000, v0
	v_exp_f32_e32 v60, v47
	v_exp_f32_e32 v61, v0
	v_mov_b32_e32 v58, v57
	s_waitcnt vmcnt(1)
	v_max_f32_e32 v47, v42, v42
	v_pk_mul_f32 v[56:57], v[58:59], v[60:61]
	s_nop 0
	v_add_f32_e32 v0, v56, v57
	v_rcp_f32_e32 v0, v0
	v_pk_mul_f32 v[50:51], v[56:57], v[50:51] op_sel:[1,0]
	v_pk_mul_f32 v[48:49], v[56:57], v[48:49] op_sel:[1,0]
	v_pk_fma_f32 v[4:5], v[56:57], v[4:5], v[50:51] op_sel_hi:[0,1,1]
	v_pk_fma_f32 v[2:3], v[56:57], v[2:3], v[48:49] op_sel_hi:[0,1,1]
	v_pk_mul_f32 v[48:49], v[56:57], v[54:55] op_sel:[1,0]
	v_pk_mul_f32 v[50:51], v[56:57], v[52:53] op_sel:[1,0]
	v_pk_fma_f32 v[28:29], v[56:57], v[28:29], v[48:49] op_sel_hi:[0,1,1]
	v_pk_fma_f32 v[30:31], v[56:57], v[30:31], v[50:51] op_sel_hi:[0,1,1]
	v_pk_mul_f32 v[4:5], v[4:5], v[0:1] op_sel_hi:[1,0]
	v_pk_mul_f32 v[2:3], v[2:3], v[0:1] op_sel_hi:[1,0]
	v_pk_mul_f32 v[28:29], v[28:29], v[0:1] op_sel_hi:[1,0]
	v_pk_mul_f32 v[30:31], v[30:31], v[0:1] op_sel_hi:[1,0]
	s_waitcnt vmcnt(0)
	v_max_f32_e32 v0, v44, v44
	v_max_f32_e32 v0, v47, v0
	v_sub_f32_e32 v42, v42, v0
	v_sub_f32_e32 v0, v44, v0
	v_mul_f32_e32 v42, 0x3f800000, v42
	v_mul_f32_e32 v0, 0x3f800000, v0
	v_exp_f32_e32 v48, v42
	v_exp_f32_e32 v49, v0
	v_mov_b32_e32 v44, v43
	v_pk_mul_f32 v[42:43], v[44:45], v[48:49]
	s_nop 0
	v_add_f32_e32 v0, v42, v43
	v_rcp_f32_e32 v0, v0
	v_pk_mul_f32 v[40:41], v[42:43], v[40:41] op_sel:[1,0]
	v_pk_mul_f32 v[38:39], v[42:43], v[38:39] op_sel:[1,0]
	v_pk_mul_f32 v[36:37], v[42:43], v[36:37] op_sel:[1,0]
	v_pk_mul_f32 v[22:23], v[42:43], v[22:23] op_sel:[1,0]
	v_pk_fma_f32 v[24:25], v[42:43], v[24:25], v[38:39] op_sel_hi:[0,1,1]
	v_pk_fma_f32 v[26:27], v[42:43], v[26:27], v[40:41] op_sel_hi:[0,1,1]
	v_pk_fma_f32 v[22:23], v[42:43], v[34:35], v[22:23] op_sel_hi:[0,1,1]
	v_pk_fma_f32 v[32:33], v[42:43], v[32:33], v[36:37] op_sel_hi:[0,1,1]
	v_pk_mul_f32 v[26:27], v[26:27], v[0:1] op_sel_hi:[1,0]
	v_pk_mul_f32 v[24:25], v[24:25], v[0:1] op_sel_hi:[1,0]
	v_pk_mul_f32 v[32:33], v[32:33], v[0:1] op_sel_hi:[1,0]
	v_pk_mul_f32 v[34:35], v[22:23], v[0:1] op_sel_hi:[1,0]
	s_branch .LBB0_1143
